# every unit of the QKV, q_b/kv_b, gate/up, O-proj and down GEMM K-loops starts with one cloned first K iteration (original waits) whose first MFMA per accumulator takes C=0; all v_mov accumulator zeroi
# speedup vs baseline: 1.0069x; 1.0069x over previous
.LBB0_429:
	s_ashr_i32 s27, s26, 31
	s_lshl_b64 s[28:29], s[26:27], 18
	s_cmp_eq_u32 s44, 0
	s_cselect_b32 s9, s79, s83
	s_cselect_b32 s7, s80, s84
	s_cselect_b32 s21, s81, s77
	s_cselect_b32 s27, s82, s85
	s_add_u32 s28, s9, s28
	s_addc_u32 s29, s7, s29
	s_and_b64 s[30:31], s[22:23], exec
	s_cselect_b32 s7, s29, s37
	s_cselect_b32 s9, s28, s36
	s_ashr_i32 s25, s24, 31
	s_lshl_b64 s[30:31], s[24:25], 18
	s_add_u32 s30, s21, s30
	s_addc_u32 s31, s27, s31
	s_and_b64 s[38:39], s[22:23], exec
	s_cselect_b32 s21, s31, s35
	s_cselect_b32 s25, s30, s34
	s_add_u32 s27, s34, 0x100
	s_addc_u32 s45, s35, 0
	s_add_u32 s34, s36, 0x20080
	s_addc_u32 s35, s37, 0
	s_mov_b32 s48, -2
.Lpeel_G67:
	s_add_u32 s36, s34, 0xfffe0080
	s_addc_u32 s37, s35, -1
	s_add_i32 s49, 0, 0x10000
	s_cmp_eq_u32 s48, 4
	s_cselect_b32 s39, s7, s37
	s_cselect_b32 s38, s9, s36
	s_cselect_b32 s37, s21, s45
	s_cselect_b32 s36, s25, s27
	s_add_i32 s61, 0, 0x14000
	v_add_u32_e32 v142, s49, v216
	v_add_u32_e32 v158, s61, v216
	ds_read_b128 v[130:133], v142
	ds_read_b128 v[134:137], v142 offset:1024
	ds_read_b128 v[138:141], v142 offset:2048
	ds_read_b128 v[142:145], v142 offset:3072
	ds_read_b128 v[146:149], v158
	ds_read_b128 v[150:153], v158 offset:1024
	ds_read_b128 v[154:157], v158 offset:2048
	ds_read_b128 v[158:161], v158 offset:3072
	v_lshl_add_u64 v[202:203], s[34:35], 0, v[210:211]
	s_add_i32 m0, s87, 0xc000
	ds_read_b128 v[162:165], v221
	ds_read_b128 v[166:169], v221 offset:1024
	ds_read_b128 v[170:173], v221 offset:2048
	ds_read_b128 v[174:177], v221 offset:3072
	ds_read_b128 v[178:181], v221 offset:4096
	ds_read_b128 v[182:185], v221 offset:5120
	ds_read_b128 v[186:189], v221 offset:6144
	ds_read_b128 v[190:193], v221 offset:7168
	global_load_lds_dwordx4 v[202:203], off
	v_lshl_add_u64 v[202:203], s[34:35], 0, v[208:209]
	s_add_i32 m0, s87, 0xe000
	s_nop 0
	global_load_lds_dwordx4 v[202:203], off
	s_waitcnt vmcnt(8)
	s_waitcnt lgkmcnt(0)
	s_barrier
	s_setprio 1
	s_waitcnt lgkmcnt(0)
	v_mfma_f32_16x16x32_bf16 v[126:129], v[130:133], v[162:165], 0
	v_mfma_f32_16x16x32_bf16 v[122:125], v[138:141], v[162:165], 0
	v_mfma_f32_16x16x32_bf16 v[110:113], v[130:133], v[170:173], 0
	v_mfma_f32_16x16x32_bf16 v[106:109], v[138:141], v[170:173], 0
	v_mfma_f32_16x16x32_bf16 v[94:97], v[130:133], v[178:181], 0
	v_mfma_f32_16x16x32_bf16 v[90:93], v[138:141], v[178:181], 0
	v_mfma_f32_16x16x32_bf16 v[78:81], v[130:133], v[186:189], 0
	v_mfma_f32_16x16x32_bf16 v[74:77], v[138:141], v[186:189], 0
	v_mfma_f32_16x16x32_bf16 v[126:129], v[134:137], v[166:169], v[126:129]
	v_mfma_f32_16x16x32_bf16 v[122:125], v[142:145], v[166:169], v[122:125]
	v_mfma_f32_16x16x32_bf16 v[110:113], v[134:137], v[174:177], v[110:113]
	v_mfma_f32_16x16x32_bf16 v[106:109], v[142:145], v[174:177], v[106:109]
	v_mfma_f32_16x16x32_bf16 v[94:97], v[134:137], v[182:185], v[94:97]
	v_mfma_f32_16x16x32_bf16 v[90:93], v[142:145], v[182:185], v[90:93]
	v_mfma_f32_16x16x32_bf16 v[78:81], v[134:137], v[190:193], v[78:81]
	v_mfma_f32_16x16x32_bf16 v[74:77], v[142:145], v[190:193], v[74:77]
	s_setprio 0
	s_setprio 1
	v_mfma_f32_16x16x32_bf16 v[118:121], v[146:149], v[162:165], 0
	v_mfma_f32_16x16x32_bf16 v[114:117], v[154:157], v[162:165], 0
	v_mfma_f32_16x16x32_bf16 v[102:105], v[146:149], v[170:173], 0
	v_mfma_f32_16x16x32_bf16 v[98:101], v[154:157], v[170:173], 0
	v_mfma_f32_16x16x32_bf16 v[86:89], v[146:149], v[178:181], 0
	v_mfma_f32_16x16x32_bf16 v[82:85], v[154:157], v[178:181], 0
	v_mfma_f32_16x16x32_bf16 v[70:73], v[146:149], v[186:189], 0
	v_mfma_f32_16x16x32_bf16 v[66:69], v[154:157], v[186:189], 0
	v_mfma_f32_16x16x32_bf16 v[118:121], v[150:153], v[166:169], v[118:121]
	v_mfma_f32_16x16x32_bf16 v[114:117], v[158:161], v[166:169], v[114:117]
	v_mfma_f32_16x16x32_bf16 v[102:105], v[150:153], v[174:177], v[102:105]
	v_mfma_f32_16x16x32_bf16 v[98:101], v[158:161], v[174:177], v[98:101]
	v_mfma_f32_16x16x32_bf16 v[86:89], v[150:153], v[182:185], v[86:89]
	v_mfma_f32_16x16x32_bf16 v[82:85], v[158:161], v[182:185], v[82:85]
	v_mfma_f32_16x16x32_bf16 v[70:73], v[150:153], v[190:193], v[70:73]
	v_mfma_f32_16x16x32_bf16 v[66:69], v[158:161], v[190:193], v[66:69]
	s_setprio 0
	s_barrier
	s_add_i32 s49, s49, s86
	v_lshl_add_u64 v[202:203], s[36:37], 0, v[194:195]
	s_mov_b32 m0, s49
	ds_read_b128 v[162:165], v221 offset:16384
	ds_read_b128 v[166:169], v221 offset:17408
	ds_read_b128 v[170:173], v221 offset:18432
	ds_read_b128 v[174:177], v221 offset:19456
	ds_read_b128 v[178:181], v221 offset:20480
	ds_read_b128 v[182:185], v221 offset:21504
	ds_read_b128 v[186:189], v221 offset:22528
	ds_read_b128 v[190:193], v221 offset:23552
	global_load_lds_dwordx4 v[202:203], off
	s_add_i32 m0, s49, 0x2000
	s_add_u32 s94, s36, 0x20000
	v_lshl_add_u64 v[204:205], s[36:37], 0, v[196:197]
	s_addc_u32 s95, s37, 0
	s_add_i32 s49, s61, s86
	global_load_lds_dwordx4 v[204:205], off
	v_lshl_add_u64 v[206:207], s[94:95], 0, v[194:195]
	s_mov_b32 m0, s49
	v_lshl_add_u64 v[222:223], s[38:39], 0, v[196:197]
	global_load_lds_dwordx4 v[206:207], off
	v_lshl_add_u64 v[206:207], s[94:95], 0, v[196:197]
	s_add_i32 m0, s49, 0x2000
	s_nop 0
	global_load_lds_dwordx4 v[206:207], off
	v_lshl_add_u64 v[206:207], s[38:39], 0, v[194:195]
	s_mov_b32 m0, s87
	s_nop 0
	global_load_lds_dwordx4 v[206:207], off
	s_mov_b32 m0, s68
	s_nop 0
	global_load_lds_dwordx4 v[222:223], off
	s_waitcnt vmcnt(8)
	s_waitcnt lgkmcnt(0)
	s_barrier
	s_setprio 1
	s_waitcnt lgkmcnt(0)
	v_mfma_f32_16x16x32_bf16 v[62:65], v[130:133], v[162:165], 0
	v_mfma_f32_16x16x32_bf16 v[58:61], v[138:141], v[162:165], 0
	v_mfma_f32_16x16x32_bf16 v[46:49], v[130:133], v[170:173], 0
	v_mfma_f32_16x16x32_bf16 v[42:45], v[138:141], v[170:173], 0
	v_mfma_f32_16x16x32_bf16 v[30:33], v[130:133], v[178:181], 0
	v_mfma_f32_16x16x32_bf16 v[26:29], v[138:141], v[178:181], 0
	v_mfma_f32_16x16x32_bf16 v[14:17], v[130:133], v[186:189], 0
	v_mfma_f32_16x16x32_bf16 v[10:13], v[138:141], v[186:189], 0
	v_mfma_f32_16x16x32_bf16 v[62:65], v[134:137], v[166:169], v[62:65]
	v_mfma_f32_16x16x32_bf16 v[58:61], v[142:145], v[166:169], v[58:61]
	v_mfma_f32_16x16x32_bf16 v[46:49], v[134:137], v[174:177], v[46:49]
	v_mfma_f32_16x16x32_bf16 v[42:45], v[142:145], v[174:177], v[42:45]
	v_mfma_f32_16x16x32_bf16 v[30:33], v[134:137], v[182:185], v[30:33]
	v_mfma_f32_16x16x32_bf16 v[26:29], v[142:145], v[182:185], v[26:29]
	v_mfma_f32_16x16x32_bf16 v[14:17], v[134:137], v[190:193], v[14:17]
	v_mfma_f32_16x16x32_bf16 v[10:13], v[142:145], v[190:193], v[10:13]
	s_setprio 0
	s_setprio 1
	v_mfma_f32_16x16x32_bf16 v[54:57], v[146:149], v[162:165], 0
	v_mfma_f32_16x16x32_bf16 v[50:53], v[154:157], v[162:165], 0
	v_mfma_f32_16x16x32_bf16 v[38:41], v[146:149], v[170:173], 0
	v_mfma_f32_16x16x32_bf16 v[34:37], v[154:157], v[170:173], 0
	v_mfma_f32_16x16x32_bf16 v[22:25], v[146:149], v[178:181], 0
	v_mfma_f32_16x16x32_bf16 v[18:21], v[154:157], v[178:181], 0
	v_mfma_f32_16x16x32_bf16 v[6:9], v[146:149], v[186:189], 0
	v_mfma_f32_16x16x32_bf16 v[2:5], v[154:157], v[186:189], 0
	v_mfma_f32_16x16x32_bf16 v[54:57], v[150:153], v[166:169], v[54:57]
	v_mfma_f32_16x16x32_bf16 v[50:53], v[158:161], v[166:169], v[50:53]
	v_mfma_f32_16x16x32_bf16 v[38:41], v[150:153], v[174:177], v[38:41]
	v_mfma_f32_16x16x32_bf16 v[34:37], v[158:161], v[174:177], v[34:37]
	v_mfma_f32_16x16x32_bf16 v[22:25], v[150:153], v[182:185], v[22:25]
	v_mfma_f32_16x16x32_bf16 v[18:21], v[158:161], v[182:185], v[18:21]
	v_mfma_f32_16x16x32_bf16 v[6:9], v[150:153], v[190:193], v[6:9]
	v_mfma_f32_16x16x32_bf16 v[2:5], v[158:161], v[190:193], v[2:5]
	s_setprio 0
	s_barrier
	s_add_i32 s49, 0, 0x18000
	s_add_i32 s61, 0, 0x1c000
	v_add_u32_e32 v142, s49, v216
	v_add_u32_e32 v158, s61, v216
	ds_read_b128 v[130:133], v142
	ds_read_b128 v[134:137], v142 offset:1024
	ds_read_b128 v[138:141], v142 offset:2048
	ds_read_b128 v[142:145], v142 offset:3072
	ds_read_b128 v[146:149], v158
	ds_read_b128 v[150:153], v158 offset:1024
	ds_read_b128 v[154:157], v158 offset:2048
	ds_read_b128 v[158:161], v158 offset:3072
	s_add_u32 s38, s38, 0x20000
	s_addc_u32 s39, s39, 0
	s_mov_b32 m0, s69
	v_lshl_add_u64 v[226:227], s[38:39], 0, v[194:195]
	ds_read_b128 v[162:165], v221 offset:32768
	ds_read_b128 v[166:169], v221 offset:33792
	ds_read_b128 v[170:173], v221 offset:34816
	ds_read_b128 v[174:177], v221 offset:35840
	ds_read_b128 v[178:181], v221 offset:36864
	ds_read_b128 v[182:185], v221 offset:37888
	ds_read_b128 v[186:189], v221 offset:38912
	ds_read_b128 v[190:193], v221 offset:39936
	global_load_lds_dwordx4 v[226:227], off
	v_lshl_add_u64 v[226:227], s[38:39], 0, v[196:197]
	s_mov_b32 m0, s70
	s_nop 0
	global_load_lds_dwordx4 v[226:227], off
	s_waitcnt vmcnt(8)
	s_waitcnt lgkmcnt(0)
	s_barrier
	s_setprio 1
	s_waitcnt lgkmcnt(0)
	v_mfma_f32_16x16x32_bf16 v[126:129], v[130:133], v[162:165], v[126:129]
	v_mfma_f32_16x16x32_bf16 v[122:125], v[138:141], v[162:165], v[122:125]
	v_mfma_f32_16x16x32_bf16 v[110:113], v[130:133], v[170:173], v[110:113]
	v_mfma_f32_16x16x32_bf16 v[106:109], v[138:141], v[170:173], v[106:109]
	v_mfma_f32_16x16x32_bf16 v[94:97], v[130:133], v[178:181], v[94:97]
	v_mfma_f32_16x16x32_bf16 v[90:93], v[138:141], v[178:181], v[90:93]
	v_mfma_f32_16x16x32_bf16 v[78:81], v[130:133], v[186:189], v[78:81]
	v_mfma_f32_16x16x32_bf16 v[74:77], v[138:141], v[186:189], v[74:77]
	v_mfma_f32_16x16x32_bf16 v[126:129], v[134:137], v[166:169], v[126:129]
	v_mfma_f32_16x16x32_bf16 v[122:125], v[142:145], v[166:169], v[122:125]
	v_mfma_f32_16x16x32_bf16 v[110:113], v[134:137], v[174:177], v[110:113]
	v_mfma_f32_16x16x32_bf16 v[106:109], v[142:145], v[174:177], v[106:109]
	v_mfma_f32_16x16x32_bf16 v[94:97], v[134:137], v[182:185], v[94:97]
	v_mfma_f32_16x16x32_bf16 v[90:93], v[142:145], v[182:185], v[90:93]
	v_mfma_f32_16x16x32_bf16 v[78:81], v[134:137], v[190:193], v[78:81]
	v_mfma_f32_16x16x32_bf16 v[74:77], v[142:145], v[190:193], v[74:77]
	s_setprio 0
	s_setprio 1
	v_mfma_f32_16x16x32_bf16 v[118:121], v[146:149], v[162:165], v[118:121]
	v_mfma_f32_16x16x32_bf16 v[114:117], v[154:157], v[162:165], v[114:117]
	v_mfma_f32_16x16x32_bf16 v[102:105], v[146:149], v[170:173], v[102:105]
	v_mfma_f32_16x16x32_bf16 v[98:101], v[154:157], v[170:173], v[98:101]
	v_mfma_f32_16x16x32_bf16 v[86:89], v[146:149], v[178:181], v[86:89]
	v_mfma_f32_16x16x32_bf16 v[82:85], v[154:157], v[178:181], v[82:85]
	v_mfma_f32_16x16x32_bf16 v[70:73], v[146:149], v[186:189], v[70:73]
	v_mfma_f32_16x16x32_bf16 v[66:69], v[154:157], v[186:189], v[66:69]
	v_mfma_f32_16x16x32_bf16 v[118:121], v[150:153], v[166:169], v[118:121]
	v_mfma_f32_16x16x32_bf16 v[114:117], v[158:161], v[166:169], v[114:117]
	v_mfma_f32_16x16x32_bf16 v[102:105], v[150:153], v[174:177], v[102:105]
	v_mfma_f32_16x16x32_bf16 v[98:101], v[158:161], v[174:177], v[98:101]
	v_mfma_f32_16x16x32_bf16 v[86:89], v[150:153], v[182:185], v[86:89]
	v_mfma_f32_16x16x32_bf16 v[82:85], v[158:161], v[182:185], v[82:85]
	v_mfma_f32_16x16x32_bf16 v[70:73], v[150:153], v[190:193], v[70:73]
	v_mfma_f32_16x16x32_bf16 v[66:69], v[158:161], v[190:193], v[66:69]
	s_setprio 0
	s_barrier
	s_add_i32 s38, s49, s86
	v_lshl_add_u64 v[202:203], v[202:203], 0, s[54:55]
	s_mov_b32 m0, s38
	ds_read_b128 v[162:165], v221 offset:49152
	ds_read_b128 v[166:169], v221 offset:50176
	ds_read_b128 v[170:173], v221 offset:51200
	ds_read_b128 v[174:177], v221 offset:52224
	ds_read_b128 v[178:181], v221 offset:53248
	ds_read_b128 v[182:185], v221 offset:54272
	ds_read_b128 v[186:189], v221 offset:55296
	ds_read_b128 v[190:193], v221 offset:56320
	global_load_lds_dwordx4 v[202:203], off
	s_add_i32 m0, s38, 0x2000
	s_add_u32 s36, s36, 0x20080
	v_lshl_add_u64 v[202:203], v[204:205], 0, s[54:55]
	s_addc_u32 s37, s37, 0
	s_add_i32 s38, s61, s86
	global_load_lds_dwordx4 v[202:203], off
	v_lshl_add_u64 v[202:203], s[36:37], 0, v[194:195]
	s_mov_b32 m0, s38
	s_nop 0
	global_load_lds_dwordx4 v[202:203], off
	v_lshl_add_u64 v[202:203], s[36:37], 0, v[196:197]
	s_add_i32 m0, s38, 0x2000
	s_nop 0
	global_load_lds_dwordx4 v[202:203], off
	v_lshl_add_u64 v[202:203], v[206:207], 0, s[54:55]
	s_mov_b32 m0, s73
	s_nop 0
	global_load_lds_dwordx4 v[202:203], off
	v_lshl_add_u64 v[202:203], v[222:223], 0, s[54:55]
	s_mov_b32 m0, s89
	s_nop 0
	global_load_lds_dwordx4 v[202:203], off
	s_waitcnt vmcnt(8)
	s_waitcnt lgkmcnt(0)
	s_barrier
	s_setprio 1
	s_waitcnt lgkmcnt(0)
	v_mfma_f32_16x16x32_bf16 v[62:65], v[130:133], v[162:165], v[62:65]
	v_mfma_f32_16x16x32_bf16 v[58:61], v[138:141], v[162:165], v[58:61]
	v_mfma_f32_16x16x32_bf16 v[46:49], v[130:133], v[170:173], v[46:49]
	v_mfma_f32_16x16x32_bf16 v[42:45], v[138:141], v[170:173], v[42:45]
	v_mfma_f32_16x16x32_bf16 v[30:33], v[130:133], v[178:181], v[30:33]
	v_mfma_f32_16x16x32_bf16 v[26:29], v[138:141], v[178:181], v[26:29]
	v_mfma_f32_16x16x32_bf16 v[14:17], v[130:133], v[186:189], v[14:17]
	v_mfma_f32_16x16x32_bf16 v[10:13], v[138:141], v[186:189], v[10:13]
	v_mfma_f32_16x16x32_bf16 v[62:65], v[134:137], v[166:169], v[62:65]
	v_mfma_f32_16x16x32_bf16 v[58:61], v[142:145], v[166:169], v[58:61]
	v_mfma_f32_16x16x32_bf16 v[46:49], v[134:137], v[174:177], v[46:49]
	v_mfma_f32_16x16x32_bf16 v[42:45], v[142:145], v[174:177], v[42:45]
	v_mfma_f32_16x16x32_bf16 v[30:33], v[134:137], v[182:185], v[30:33]
	v_mfma_f32_16x16x32_bf16 v[26:29], v[142:145], v[182:185], v[26:29]
	v_mfma_f32_16x16x32_bf16 v[14:17], v[134:137], v[190:193], v[14:17]
	v_mfma_f32_16x16x32_bf16 v[10:13], v[142:145], v[190:193], v[10:13]
	s_setprio 0
	s_setprio 1
	v_mfma_f32_16x16x32_bf16 v[54:57], v[146:149], v[162:165], v[54:57]
	v_mfma_f32_16x16x32_bf16 v[50:53], v[154:157], v[162:165], v[50:53]
	v_mfma_f32_16x16x32_bf16 v[38:41], v[146:149], v[170:173], v[38:41]
	v_mfma_f32_16x16x32_bf16 v[34:37], v[154:157], v[170:173], v[34:37]
	v_mfma_f32_16x16x32_bf16 v[22:25], v[146:149], v[178:181], v[22:25]
	v_mfma_f32_16x16x32_bf16 v[18:21], v[154:157], v[178:181], v[18:21]
	v_mfma_f32_16x16x32_bf16 v[6:9], v[146:149], v[186:189], v[6:9]
	v_mfma_f32_16x16x32_bf16 v[2:5], v[154:157], v[186:189], v[2:5]
	v_mfma_f32_16x16x32_bf16 v[54:57], v[150:153], v[166:169], v[54:57]
	v_mfma_f32_16x16x32_bf16 v[50:53], v[158:161], v[166:169], v[50:53]
	v_mfma_f32_16x16x32_bf16 v[38:41], v[150:153], v[174:177], v[38:41]
	v_mfma_f32_16x16x32_bf16 v[34:37], v[158:161], v[174:177], v[34:37]
	v_mfma_f32_16x16x32_bf16 v[22:25], v[150:153], v[182:185], v[22:25]
	v_mfma_f32_16x16x32_bf16 v[18:21], v[158:161], v[182:185], v[18:21]
	v_mfma_f32_16x16x32_bf16 v[6:9], v[150:153], v[190:193], v[6:9]
	v_mfma_f32_16x16x32_bf16 v[2:5], v[158:161], v[190:193], v[2:5]
	s_setprio 0
	s_barrier
	s_add_i32 s48, s48, 2
	s_add_u32 s27, s27, 0x100
	s_addc_u32 s45, s45, 0
	s_add_u32 s34, s34, 0x100
	s_addc_u32 s35, s35, 0
	s_cmp_gt_u32 s48, 5
	s_cbranch_scc1 .Lpeel_exit_G67
.LBB0_430:
	s_add_u32 s36, s34, 0xfffe0080
	s_addc_u32 s37, s35, -1
	s_add_i32 s49, 0, 0x10000
	s_cmp_eq_u32 s48, 4
	s_cselect_b32 s39, s7, s37
	s_cselect_b32 s38, s9, s36
	s_cselect_b32 s37, s21, s45
	s_cselect_b32 s36, s25, s27
	s_add_i32 s61, 0, 0x14000
	v_add_u32_e32 v142, s49, v216
	v_add_u32_e32 v158, s61, v216
	ds_read_b128 v[130:133], v142
	ds_read_b128 v[134:137], v142 offset:1024
	ds_read_b128 v[138:141], v142 offset:2048
	ds_read_b128 v[142:145], v142 offset:3072
	ds_read_b128 v[146:149], v158
	ds_read_b128 v[150:153], v158 offset:1024
	ds_read_b128 v[154:157], v158 offset:2048
	ds_read_b128 v[158:161], v158 offset:3072
	v_lshl_add_u64 v[202:203], s[34:35], 0, v[210:211]
	s_add_i32 m0, s87, 0xc000
	ds_read_b128 v[162:165], v221
	ds_read_b128 v[166:169], v221 offset:1024
	ds_read_b128 v[170:173], v221 offset:2048
	ds_read_b128 v[174:177], v221 offset:3072
	ds_read_b128 v[178:181], v221 offset:4096
	ds_read_b128 v[182:185], v221 offset:5120
	ds_read_b128 v[186:189], v221 offset:6144
	ds_read_b128 v[190:193], v221 offset:7168
	global_load_lds_dwordx4 v[202:203], off
	v_lshl_add_u64 v[202:203], s[34:35], 0, v[208:209]
	s_add_i32 m0, s87, 0xe000
	s_nop 0
	global_load_lds_dwordx4 v[202:203], off
	s_waitcnt vmcnt(8)
	s_waitcnt lgkmcnt(0)
	s_barrier
	s_setprio 1
	s_waitcnt lgkmcnt(0)
	v_mfma_f32_16x16x32_bf16 v[126:129], v[130:133], v[162:165], v[126:129]
	v_mfma_f32_16x16x32_bf16 v[122:125], v[138:141], v[162:165], v[122:125]
	v_mfma_f32_16x16x32_bf16 v[110:113], v[130:133], v[170:173], v[110:113]
	v_mfma_f32_16x16x32_bf16 v[106:109], v[138:141], v[170:173], v[106:109]
	v_mfma_f32_16x16x32_bf16 v[94:97], v[130:133], v[178:181], v[94:97]
	v_mfma_f32_16x16x32_bf16 v[90:93], v[138:141], v[178:181], v[90:93]
	v_mfma_f32_16x16x32_bf16 v[78:81], v[130:133], v[186:189], v[78:81]
	v_mfma_f32_16x16x32_bf16 v[74:77], v[138:141], v[186:189], v[74:77]
	v_mfma_f32_16x16x32_bf16 v[126:129], v[134:137], v[166:169], v[126:129]
	v_mfma_f32_16x16x32_bf16 v[122:125], v[142:145], v[166:169], v[122:125]
	v_mfma_f32_16x16x32_bf16 v[110:113], v[134:137], v[174:177], v[110:113]
	v_mfma_f32_16x16x32_bf16 v[106:109], v[142:145], v[174:177], v[106:109]
	v_mfma_f32_16x16x32_bf16 v[94:97], v[134:137], v[182:185], v[94:97]
	v_mfma_f32_16x16x32_bf16 v[90:93], v[142:145], v[182:185], v[90:93]
	v_mfma_f32_16x16x32_bf16 v[78:81], v[134:137], v[190:193], v[78:81]
	v_mfma_f32_16x16x32_bf16 v[74:77], v[142:145], v[190:193], v[74:77]
	s_setprio 0
	s_setprio 1
	v_mfma_f32_16x16x32_bf16 v[118:121], v[146:149], v[162:165], v[118:121]
	v_mfma_f32_16x16x32_bf16 v[114:117], v[154:157], v[162:165], v[114:117]
	v_mfma_f32_16x16x32_bf16 v[102:105], v[146:149], v[170:173], v[102:105]
	v_mfma_f32_16x16x32_bf16 v[98:101], v[154:157], v[170:173], v[98:101]
	v_mfma_f32_16x16x32_bf16 v[86:89], v[146:149], v[178:181], v[86:89]
	v_mfma_f32_16x16x32_bf16 v[82:85], v[154:157], v[178:181], v[82:85]
	v_mfma_f32_16x16x32_bf16 v[70:73], v[146:149], v[186:189], v[70:73]
	v_mfma_f32_16x16x32_bf16 v[66:69], v[154:157], v[186:189], v[66:69]
	v_mfma_f32_16x16x32_bf16 v[118:121], v[150:153], v[166:169], v[118:121]
	v_mfma_f32_16x16x32_bf16 v[114:117], v[158:161], v[166:169], v[114:117]
	v_mfma_f32_16x16x32_bf16 v[102:105], v[150:153], v[174:177], v[102:105]
	v_mfma_f32_16x16x32_bf16 v[98:101], v[158:161], v[174:177], v[98:101]
	v_mfma_f32_16x16x32_bf16 v[86:89], v[150:153], v[182:185], v[86:89]
	v_mfma_f32_16x16x32_bf16 v[82:85], v[158:161], v[182:185], v[82:85]
	v_mfma_f32_16x16x32_bf16 v[70:73], v[150:153], v[190:193], v[70:73]
	v_mfma_f32_16x16x32_bf16 v[66:69], v[158:161], v[190:193], v[66:69]
	s_setprio 0
	s_barrier
	s_add_i32 s49, s49, s86
	v_lshl_add_u64 v[202:203], s[36:37], 0, v[194:195]
	s_mov_b32 m0, s49
	ds_read_b128 v[162:165], v221 offset:16384
	ds_read_b128 v[166:169], v221 offset:17408
	ds_read_b128 v[170:173], v221 offset:18432
	ds_read_b128 v[174:177], v221 offset:19456
	ds_read_b128 v[178:181], v221 offset:20480
	ds_read_b128 v[182:185], v221 offset:21504
	ds_read_b128 v[186:189], v221 offset:22528
	ds_read_b128 v[190:193], v221 offset:23552
	global_load_lds_dwordx4 v[202:203], off
	s_add_i32 m0, s49, 0x2000
	s_add_u32 s94, s36, 0x20000
	v_lshl_add_u64 v[204:205], s[36:37], 0, v[196:197]
	s_addc_u32 s95, s37, 0
	s_add_i32 s49, s61, s86
	global_load_lds_dwordx4 v[204:205], off
	v_lshl_add_u64 v[206:207], s[94:95], 0, v[194:195]
	s_mov_b32 m0, s49
	v_lshl_add_u64 v[222:223], s[38:39], 0, v[196:197]
	global_load_lds_dwordx4 v[206:207], off
	v_lshl_add_u64 v[206:207], s[94:95], 0, v[196:197]
	s_add_i32 m0, s49, 0x2000
	s_nop 0
	global_load_lds_dwordx4 v[206:207], off
	v_lshl_add_u64 v[206:207], s[38:39], 0, v[194:195]
	s_mov_b32 m0, s87
	s_nop 0
	global_load_lds_dwordx4 v[206:207], off
	s_mov_b32 m0, s68
	s_nop 0
	global_load_lds_dwordx4 v[222:223], off
	s_waitcnt vmcnt(8)
	s_waitcnt lgkmcnt(0)
	s_barrier
	s_setprio 1
	s_waitcnt lgkmcnt(0)
	v_mfma_f32_16x16x32_bf16 v[62:65], v[130:133], v[162:165], v[62:65]
	v_mfma_f32_16x16x32_bf16 v[58:61], v[138:141], v[162:165], v[58:61]
	v_mfma_f32_16x16x32_bf16 v[46:49], v[130:133], v[170:173], v[46:49]
	v_mfma_f32_16x16x32_bf16 v[42:45], v[138:141], v[170:173], v[42:45]
	v_mfma_f32_16x16x32_bf16 v[30:33], v[130:133], v[178:181], v[30:33]
	v_mfma_f32_16x16x32_bf16 v[26:29], v[138:141], v[178:181], v[26:29]
	v_mfma_f32_16x16x32_bf16 v[14:17], v[130:133], v[186:189], v[14:17]
	v_mfma_f32_16x16x32_bf16 v[10:13], v[138:141], v[186:189], v[10:13]
	v_mfma_f32_16x16x32_bf16 v[62:65], v[134:137], v[166:169], v[62:65]
	v_mfma_f32_16x16x32_bf16 v[58:61], v[142:145], v[166:169], v[58:61]
	v_mfma_f32_16x16x32_bf16 v[46:49], v[134:137], v[174:177], v[46:49]
	v_mfma_f32_16x16x32_bf16 v[42:45], v[142:145], v[174:177], v[42:45]
	v_mfma_f32_16x16x32_bf16 v[30:33], v[134:137], v[182:185], v[30:33]
	v_mfma_f32_16x16x32_bf16 v[26:29], v[142:145], v[182:185], v[26:29]
	v_mfma_f32_16x16x32_bf16 v[14:17], v[134:137], v[190:193], v[14:17]
	v_mfma_f32_16x16x32_bf16 v[10:13], v[142:145], v[190:193], v[10:13]
	s_setprio 0
	s_setprio 1
	v_mfma_f32_16x16x32_bf16 v[54:57], v[146:149], v[162:165], v[54:57]
	v_mfma_f32_16x16x32_bf16 v[50:53], v[154:157], v[162:165], v[50:53]
	v_mfma_f32_16x16x32_bf16 v[38:41], v[146:149], v[170:173], v[38:41]
	v_mfma_f32_16x16x32_bf16 v[34:37], v[154:157], v[170:173], v[34:37]
	v_mfma_f32_16x16x32_bf16 v[22:25], v[146:149], v[178:181], v[22:25]
	v_mfma_f32_16x16x32_bf16 v[18:21], v[154:157], v[178:181], v[18:21]
	v_mfma_f32_16x16x32_bf16 v[6:9], v[146:149], v[186:189], v[6:9]
	v_mfma_f32_16x16x32_bf16 v[2:5], v[154:157], v[186:189], v[2:5]
	v_mfma_f32_16x16x32_bf16 v[54:57], v[150:153], v[166:169], v[54:57]
	v_mfma_f32_16x16x32_bf16 v[50:53], v[158:161], v[166:169], v[50:53]
	v_mfma_f32_16x16x32_bf16 v[38:41], v[150:153], v[174:177], v[38:41]
	v_mfma_f32_16x16x32_bf16 v[34:37], v[158:161], v[174:177], v[34:37]
	v_mfma_f32_16x16x32_bf16 v[22:25], v[150:153], v[182:185], v[22:25]
	v_mfma_f32_16x16x32_bf16 v[18:21], v[158:161], v[182:185], v[18:21]
	v_mfma_f32_16x16x32_bf16 v[6:9], v[150:153], v[190:193], v[6:9]
	v_mfma_f32_16x16x32_bf16 v[2:5], v[158:161], v[190:193], v[2:5]
	s_setprio 0
	s_barrier
	s_add_i32 s49, 0, 0x18000
	s_add_i32 s61, 0, 0x1c000
	v_add_u32_e32 v142, s49, v216
	v_add_u32_e32 v158, s61, v216
	ds_read_b128 v[130:133], v142
	ds_read_b128 v[134:137], v142 offset:1024
	ds_read_b128 v[138:141], v142 offset:2048
	ds_read_b128 v[142:145], v142 offset:3072
	ds_read_b128 v[146:149], v158
	ds_read_b128 v[150:153], v158 offset:1024
	ds_read_b128 v[154:157], v158 offset:2048
	ds_read_b128 v[158:161], v158 offset:3072
	s_add_u32 s38, s38, 0x20000
	s_addc_u32 s39, s39, 0
	s_mov_b32 m0, s69
	v_lshl_add_u64 v[226:227], s[38:39], 0, v[194:195]
	ds_read_b128 v[162:165], v221 offset:32768
	ds_read_b128 v[166:169], v221 offset:33792
	ds_read_b128 v[170:173], v221 offset:34816
	ds_read_b128 v[174:177], v221 offset:35840
	ds_read_b128 v[178:181], v221 offset:36864
	ds_read_b128 v[182:185], v221 offset:37888
	ds_read_b128 v[186:189], v221 offset:38912
	ds_read_b128 v[190:193], v221 offset:39936
	global_load_lds_dwordx4 v[226:227], off
	v_lshl_add_u64 v[226:227], s[38:39], 0, v[196:197]
	s_mov_b32 m0, s70
	s_nop 0
	global_load_lds_dwordx4 v[226:227], off
	s_waitcnt vmcnt(8)
	s_waitcnt lgkmcnt(0)
	s_barrier
	s_setprio 1
	s_waitcnt lgkmcnt(0)
	v_mfma_f32_16x16x32_bf16 v[126:129], v[130:133], v[162:165], v[126:129]
	v_mfma_f32_16x16x32_bf16 v[122:125], v[138:141], v[162:165], v[122:125]
	v_mfma_f32_16x16x32_bf16 v[110:113], v[130:133], v[170:173], v[110:113]
	v_mfma_f32_16x16x32_bf16 v[106:109], v[138:141], v[170:173], v[106:109]
	v_mfma_f32_16x16x32_bf16 v[94:97], v[130:133], v[178:181], v[94:97]
	v_mfma_f32_16x16x32_bf16 v[90:93], v[138:141], v[178:181], v[90:93]
	v_mfma_f32_16x16x32_bf16 v[78:81], v[130:133], v[186:189], v[78:81]
	v_mfma_f32_16x16x32_bf16 v[74:77], v[138:141], v[186:189], v[74:77]
	v_mfma_f32_16x16x32_bf16 v[126:129], v[134:137], v[166:169], v[126:129]
	v_mfma_f32_16x16x32_bf16 v[122:125], v[142:145], v[166:169], v[122:125]
	v_mfma_f32_16x16x32_bf16 v[110:113], v[134:137], v[174:177], v[110:113]
	v_mfma_f32_16x16x32_bf16 v[106:109], v[142:145], v[174:177], v[106:109]
	v_mfma_f32_16x16x32_bf16 v[94:97], v[134:137], v[182:185], v[94:97]
	v_mfma_f32_16x16x32_bf16 v[90:93], v[142:145], v[182:185], v[90:93]
	v_mfma_f32_16x16x32_bf16 v[78:81], v[134:137], v[190:193], v[78:81]
	v_mfma_f32_16x16x32_bf16 v[74:77], v[142:145], v[190:193], v[74:77]
	s_setprio 0
	s_setprio 1
	v_mfma_f32_16x16x32_bf16 v[118:121], v[146:149], v[162:165], v[118:121]
	v_mfma_f32_16x16x32_bf16 v[114:117], v[154:157], v[162:165], v[114:117]
	v_mfma_f32_16x16x32_bf16 v[102:105], v[146:149], v[170:173], v[102:105]
	v_mfma_f32_16x16x32_bf16 v[98:101], v[154:157], v[170:173], v[98:101]
	v_mfma_f32_16x16x32_bf16 v[86:89], v[146:149], v[178:181], v[86:89]
	v_mfma_f32_16x16x32_bf16 v[82:85], v[154:157], v[178:181], v[82:85]
	v_mfma_f32_16x16x32_bf16 v[70:73], v[146:149], v[186:189], v[70:73]
	v_mfma_f32_16x16x32_bf16 v[66:69], v[154:157], v[186:189], v[66:69]
	v_mfma_f32_16x16x32_bf16 v[118:121], v[150:153], v[166:169], v[118:121]
	v_mfma_f32_16x16x32_bf16 v[114:117], v[158:161], v[166:169], v[114:117]
	v_mfma_f32_16x16x32_bf16 v[102:105], v[150:153], v[174:177], v[102:105]
	v_mfma_f32_16x16x32_bf16 v[98:101], v[158:161], v[174:177], v[98:101]
	v_mfma_f32_16x16x32_bf16 v[86:89], v[150:153], v[182:185], v[86:89]
	v_mfma_f32_16x16x32_bf16 v[82:85], v[158:161], v[182:185], v[82:85]
	v_mfma_f32_16x16x32_bf16 v[70:73], v[150:153], v[190:193], v[70:73]
	v_mfma_f32_16x16x32_bf16 v[66:69], v[158:161], v[190:193], v[66:69]
	s_setprio 0
	s_barrier
	s_add_i32 s38, s49, s86
	v_lshl_add_u64 v[202:203], v[202:203], 0, s[54:55]
	s_mov_b32 m0, s38
	ds_read_b128 v[162:165], v221 offset:49152
	ds_read_b128 v[166:169], v221 offset:50176
	ds_read_b128 v[170:173], v221 offset:51200
	ds_read_b128 v[174:177], v221 offset:52224
	ds_read_b128 v[178:181], v221 offset:53248
	ds_read_b128 v[182:185], v221 offset:54272
	ds_read_b128 v[186:189], v221 offset:55296
	ds_read_b128 v[190:193], v221 offset:56320
	global_load_lds_dwordx4 v[202:203], off
	s_add_i32 m0, s38, 0x2000
	s_add_u32 s36, s36, 0x20080
	v_lshl_add_u64 v[202:203], v[204:205], 0, s[54:55]
	s_addc_u32 s37, s37, 0
	s_add_i32 s38, s61, s86
	global_load_lds_dwordx4 v[202:203], off
	v_lshl_add_u64 v[202:203], s[36:37], 0, v[194:195]
	s_mov_b32 m0, s38
	s_nop 0
	global_load_lds_dwordx4 v[202:203], off
	v_lshl_add_u64 v[202:203], s[36:37], 0, v[196:197]
	s_add_i32 m0, s38, 0x2000
	s_nop 0
	global_load_lds_dwordx4 v[202:203], off
	v_lshl_add_u64 v[202:203], v[206:207], 0, s[54:55]
	s_mov_b32 m0, s73
	s_nop 0
	global_load_lds_dwordx4 v[202:203], off
	v_lshl_add_u64 v[202:203], v[222:223], 0, s[54:55]
	s_mov_b32 m0, s89
	s_nop 0
	global_load_lds_dwordx4 v[202:203], off
	s_waitcnt vmcnt(8)
	s_waitcnt lgkmcnt(0)
	s_barrier
	s_setprio 1
	s_waitcnt lgkmcnt(0)
	v_mfma_f32_16x16x32_bf16 v[62:65], v[130:133], v[162:165], v[62:65]
	v_mfma_f32_16x16x32_bf16 v[58:61], v[138:141], v[162:165], v[58:61]
	v_mfma_f32_16x16x32_bf16 v[46:49], v[130:133], v[170:173], v[46:49]
	v_mfma_f32_16x16x32_bf16 v[42:45], v[138:141], v[170:173], v[42:45]
	v_mfma_f32_16x16x32_bf16 v[30:33], v[130:133], v[178:181], v[30:33]
	v_mfma_f32_16x16x32_bf16 v[26:29], v[138:141], v[178:181], v[26:29]
	v_mfma_f32_16x16x32_bf16 v[14:17], v[130:133], v[186:189], v[14:17]
	v_mfma_f32_16x16x32_bf16 v[10:13], v[138:141], v[186:189], v[10:13]
	v_mfma_f32_16x16x32_bf16 v[62:65], v[134:137], v[166:169], v[62:65]
	v_mfma_f32_16x16x32_bf16 v[58:61], v[142:145], v[166:169], v[58:61]
	v_mfma_f32_16x16x32_bf16 v[46:49], v[134:137], v[174:177], v[46:49]
	v_mfma_f32_16x16x32_bf16 v[42:45], v[142:145], v[174:177], v[42:45]
	v_mfma_f32_16x16x32_bf16 v[30:33], v[134:137], v[182:185], v[30:33]
	v_mfma_f32_16x16x32_bf16 v[26:29], v[142:145], v[182:185], v[26:29]
	v_mfma_f32_16x16x32_bf16 v[14:17], v[134:137], v[190:193], v[14:17]
	v_mfma_f32_16x16x32_bf16 v[10:13], v[142:145], v[190:193], v[10:13]
	s_setprio 0
	s_setprio 1
	v_mfma_f32_16x16x32_bf16 v[54:57], v[146:149], v[162:165], v[54:57]
	v_mfma_f32_16x16x32_bf16 v[50:53], v[154:157], v[162:165], v[50:53]
	v_mfma_f32_16x16x32_bf16 v[38:41], v[146:149], v[170:173], v[38:41]
	v_mfma_f32_16x16x32_bf16 v[34:37], v[154:157], v[170:173], v[34:37]
	v_mfma_f32_16x16x32_bf16 v[22:25], v[146:149], v[178:181], v[22:25]
	v_mfma_f32_16x16x32_bf16 v[18:21], v[154:157], v[178:181], v[18:21]
	v_mfma_f32_16x16x32_bf16 v[6:9], v[146:149], v[186:189], v[6:9]
	v_mfma_f32_16x16x32_bf16 v[2:5], v[154:157], v[186:189], v[2:5]
	v_mfma_f32_16x16x32_bf16 v[54:57], v[150:153], v[166:169], v[54:57]
	v_mfma_f32_16x16x32_bf16 v[50:53], v[158:161], v[166:169], v[50:53]
	v_mfma_f32_16x16x32_bf16 v[38:41], v[150:153], v[174:177], v[38:41]
	v_mfma_f32_16x16x32_bf16 v[34:37], v[158:161], v[174:177], v[34:37]
	v_mfma_f32_16x16x32_bf16 v[22:25], v[150:153], v[182:185], v[22:25]
	v_mfma_f32_16x16x32_bf16 v[18:21], v[158:161], v[182:185], v[18:21]
	v_mfma_f32_16x16x32_bf16 v[6:9], v[150:153], v[190:193], v[6:9]
	v_mfma_f32_16x16x32_bf16 v[2:5], v[158:161], v[190:193], v[2:5]
	s_setprio 0
	s_barrier
	s_add_i32 s48, s48, 2
	s_add_u32 s27, s27, 0x100
	s_addc_u32 s45, s45, 0
	s_add_u32 s34, s34, 0x100
	s_addc_u32 s35, s35, 0
	s_cmp_gt_u32 s48, 5
	s_cbranch_scc0 .LBB0_430

.LBB0_604:
	s_ashr_i32 s35, s34, 31
	s_lshl_b64 s[36:37], s[34:35], 20
	s_add_u32 s36, s73, s36
	s_addc_u32 s37, s89, s37
	s_and_b64 s[38:39], s[6:7], exec
	s_cselect_b32 s11, s37, s81
	s_cselect_b32 s35, s36, s80
	s_ashr_i32 s31, s30, 31
	s_lshl_b64 s[38:39], s[30:31], 20
	s_add_u32 s38, s97, s38
	s_addc_u32 s39, s65, s39
	s_and_b64 s[82:83], s[6:7], exec
	s_cselect_b32 s31, s39, s9
	s_cselect_b32 s79, s38, s8
	s_add_u32 s84, s8, 0x100
	s_addc_u32 s85, s9, 0
	s_add_u32 s8, s80, 0x80080
	s_addc_u32 s9, s81, 0
	s_mov_b32 s86, -2
.Lpeel_G1:
	s_add_u32 s80, s8, 0xfff80080
	s_addc_u32 s81, s9, -1
	s_add_i32 s87, 0, 0x10000
	s_cmp_eq_u32 s86, 28
	s_cselect_b32 s83, s11, s81
	s_cselect_b32 s82, s35, s80
	s_cselect_b32 s81, s31, s85
	s_cselect_b32 s80, s79, s84
	s_add_i32 s92, 0, 0x14000
	v_add_u32_e32 v142, s87, v228
	v_add_u32_e32 v158, s92, v228
	ds_read_b128 v[126:129], v142
	ds_read_b128 v[134:137], v142 offset:1024
	ds_read_b128 v[138:141], v142 offset:2048
	ds_read_b128 v[142:145], v142 offset:3072
	ds_read_b128 v[146:149], v158
	ds_read_b128 v[150:153], v158 offset:1024
	ds_read_b128 v[154:157], v158 offset:2048
	ds_read_b128 v[158:161], v158 offset:3072
	v_lshl_add_u64 v[202:203], s[8:9], 0, v[210:211]
	s_add_i32 m0, s61, 0xc000
	ds_read_b128 v[162:165], v233
	ds_read_b128 v[166:169], v233 offset:1024
	ds_read_b128 v[170:173], v233 offset:2048
	ds_read_b128 v[174:177], v233 offset:3072
	ds_read_b128 v[178:181], v233 offset:4096
	ds_read_b128 v[182:185], v233 offset:5120
	ds_read_b128 v[186:189], v233 offset:6144
	ds_read_b128 v[190:193], v233 offset:7168
	global_load_lds_dwordx4 v[202:203], off
	v_lshl_add_u64 v[202:203], s[8:9], 0, v[208:209]
	s_add_i32 m0, s61, 0xe000
	s_nop 0
	global_load_lds_dwordx4 v[202:203], off
	s_waitcnt vmcnt(8)
	s_waitcnt lgkmcnt(0)
	s_barrier
	s_setprio 1
	s_waitcnt lgkmcnt(0)
	v_mfma_f32_16x16x32_bf16 v[130:133], v[126:129], v[162:165], 0
	v_mfma_f32_16x16x32_bf16 v[122:125], v[138:141], v[162:165], 0
	v_mfma_f32_16x16x32_bf16 v[110:113], v[126:129], v[170:173], 0
	v_mfma_f32_16x16x32_bf16 v[106:109], v[138:141], v[170:173], 0
	v_mfma_f32_16x16x32_bf16 v[94:97], v[126:129], v[178:181], 0
	v_mfma_f32_16x16x32_bf16 v[90:93], v[138:141], v[178:181], 0
	v_mfma_f32_16x16x32_bf16 v[78:81], v[126:129], v[186:189], 0
	v_mfma_f32_16x16x32_bf16 v[74:77], v[138:141], v[186:189], 0
	v_mfma_f32_16x16x32_bf16 v[130:133], v[134:137], v[166:169], v[130:133]
	v_mfma_f32_16x16x32_bf16 v[122:125], v[142:145], v[166:169], v[122:125]
	v_mfma_f32_16x16x32_bf16 v[110:113], v[134:137], v[174:177], v[110:113]
	v_mfma_f32_16x16x32_bf16 v[106:109], v[142:145], v[174:177], v[106:109]
	v_mfma_f32_16x16x32_bf16 v[94:97], v[134:137], v[182:185], v[94:97]
	v_mfma_f32_16x16x32_bf16 v[90:93], v[142:145], v[182:185], v[90:93]
	v_mfma_f32_16x16x32_bf16 v[78:81], v[134:137], v[190:193], v[78:81]
	v_mfma_f32_16x16x32_bf16 v[74:77], v[142:145], v[190:193], v[74:77]
	s_setprio 0
	s_setprio 1
	v_mfma_f32_16x16x32_bf16 v[118:121], v[146:149], v[162:165], 0
	v_mfma_f32_16x16x32_bf16 v[114:117], v[154:157], v[162:165], 0
	v_mfma_f32_16x16x32_bf16 v[102:105], v[146:149], v[170:173], 0
	v_mfma_f32_16x16x32_bf16 v[98:101], v[154:157], v[170:173], 0
	v_mfma_f32_16x16x32_bf16 v[86:89], v[146:149], v[178:181], 0
	v_mfma_f32_16x16x32_bf16 v[82:85], v[154:157], v[178:181], 0
	v_mfma_f32_16x16x32_bf16 v[70:73], v[146:149], v[186:189], 0
	v_mfma_f32_16x16x32_bf16 v[66:69], v[154:157], v[186:189], 0
	v_mfma_f32_16x16x32_bf16 v[118:121], v[150:153], v[166:169], v[118:121]
	v_mfma_f32_16x16x32_bf16 v[114:117], v[158:161], v[166:169], v[114:117]
	v_mfma_f32_16x16x32_bf16 v[102:105], v[150:153], v[174:177], v[102:105]
	v_mfma_f32_16x16x32_bf16 v[98:101], v[158:161], v[174:177], v[98:101]
	v_mfma_f32_16x16x32_bf16 v[86:89], v[150:153], v[182:185], v[86:89]
	v_mfma_f32_16x16x32_bf16 v[82:85], v[158:161], v[182:185], v[82:85]
	v_mfma_f32_16x16x32_bf16 v[70:73], v[150:153], v[190:193], v[70:73]
	v_mfma_f32_16x16x32_bf16 v[66:69], v[158:161], v[190:193], v[66:69]
	s_setprio 0
	s_barrier
	s_add_i32 s87, s87, s95
	v_lshl_add_u64 v[202:203], s[80:81], 0, v[194:195]
	s_mov_b32 m0, s87
	ds_read_b128 v[162:165], v233 offset:16384
	ds_read_b128 v[166:169], v233 offset:17408
	ds_read_b128 v[170:173], v233 offset:18432
	ds_read_b128 v[174:177], v233 offset:19456
	ds_read_b128 v[178:181], v233 offset:20480
	ds_read_b128 v[182:185], v233 offset:21504
	ds_read_b128 v[186:189], v233 offset:22528
	ds_read_b128 v[190:193], v233 offset:23552
	global_load_lds_dwordx4 v[202:203], off
	s_add_i32 m0, s87, 0x2000
	s_add_u32 vcc_lo, s80, 0x80000
	v_lshl_add_u64 v[204:205], s[80:81], 0, v[196:197]
	s_addc_u32 vcc_hi, s81, 0
	s_add_i32 s87, s92, s95
	global_load_lds_dwordx4 v[204:205], off
	v_lshl_add_u64 v[206:207], vcc, 0, v[194:195]
	s_mov_b32 m0, s87
	v_lshl_add_u64 v[214:215], s[82:83], 0, v[196:197]
	global_load_lds_dwordx4 v[206:207], off
	v_lshl_add_u64 v[206:207], vcc, 0, v[196:197]
	s_add_i32 m0, s87, 0x2000
	s_nop 0
	global_load_lds_dwordx4 v[206:207], off
	v_lshl_add_u64 v[206:207], s[82:83], 0, v[194:195]
	s_mov_b32 m0, s61
	s_nop 0
	global_load_lds_dwordx4 v[206:207], off
	s_mov_b32 m0, s44
	s_nop 0
	global_load_lds_dwordx4 v[214:215], off
	s_waitcnt vmcnt(8)
	s_waitcnt lgkmcnt(0)
	s_barrier
	s_setprio 1
	s_waitcnt lgkmcnt(0)
	v_mfma_f32_16x16x32_bf16 v[62:65], v[126:129], v[162:165], 0
	v_mfma_f32_16x16x32_bf16 v[58:61], v[138:141], v[162:165], 0
	v_mfma_f32_16x16x32_bf16 v[46:49], v[126:129], v[170:173], 0
	v_mfma_f32_16x16x32_bf16 v[42:45], v[138:141], v[170:173], 0
	v_mfma_f32_16x16x32_bf16 v[30:33], v[126:129], v[178:181], 0
	v_mfma_f32_16x16x32_bf16 v[26:29], v[138:141], v[178:181], 0
	v_mfma_f32_16x16x32_bf16 v[14:17], v[126:129], v[186:189], 0
	v_mfma_f32_16x16x32_bf16 v[10:13], v[138:141], v[186:189], 0
	v_mfma_f32_16x16x32_bf16 v[62:65], v[134:137], v[166:169], v[62:65]
	v_mfma_f32_16x16x32_bf16 v[58:61], v[142:145], v[166:169], v[58:61]
	v_mfma_f32_16x16x32_bf16 v[46:49], v[134:137], v[174:177], v[46:49]
	v_mfma_f32_16x16x32_bf16 v[42:45], v[142:145], v[174:177], v[42:45]
	v_mfma_f32_16x16x32_bf16 v[30:33], v[134:137], v[182:185], v[30:33]
	v_mfma_f32_16x16x32_bf16 v[26:29], v[142:145], v[182:185], v[26:29]
	v_mfma_f32_16x16x32_bf16 v[14:17], v[134:137], v[190:193], v[14:17]
	v_mfma_f32_16x16x32_bf16 v[10:13], v[142:145], v[190:193], v[10:13]
	s_setprio 0
	s_setprio 1
	v_mfma_f32_16x16x32_bf16 v[54:57], v[146:149], v[162:165], 0
	v_mfma_f32_16x16x32_bf16 v[50:53], v[154:157], v[162:165], 0
	v_mfma_f32_16x16x32_bf16 v[38:41], v[146:149], v[170:173], 0
	v_mfma_f32_16x16x32_bf16 v[34:37], v[154:157], v[170:173], 0
	v_mfma_f32_16x16x32_bf16 v[22:25], v[146:149], v[178:181], 0
	v_mfma_f32_16x16x32_bf16 v[18:21], v[154:157], v[178:181], 0
	v_mfma_f32_16x16x32_bf16 v[6:9], v[146:149], v[186:189], 0
	v_mfma_f32_16x16x32_bf16 v[2:5], v[154:157], v[186:189], 0
	v_mfma_f32_16x16x32_bf16 v[54:57], v[150:153], v[166:169], v[54:57]
	v_mfma_f32_16x16x32_bf16 v[50:53], v[158:161], v[166:169], v[50:53]
	v_mfma_f32_16x16x32_bf16 v[38:41], v[150:153], v[174:177], v[38:41]
	v_mfma_f32_16x16x32_bf16 v[34:37], v[158:161], v[174:177], v[34:37]
	v_mfma_f32_16x16x32_bf16 v[22:25], v[150:153], v[182:185], v[22:25]
	v_mfma_f32_16x16x32_bf16 v[18:21], v[158:161], v[182:185], v[18:21]
	v_mfma_f32_16x16x32_bf16 v[6:9], v[150:153], v[190:193], v[6:9]
	v_mfma_f32_16x16x32_bf16 v[2:5], v[158:161], v[190:193], v[2:5]
	s_setprio 0
	s_barrier
	s_add_i32 s87, 0, 0x18000
	s_add_i32 s92, 0, 0x1c000
	v_add_u32_e32 v142, s87, v228
	v_add_u32_e32 v158, s92, v228
	ds_read_b128 v[126:129], v142
	ds_read_b128 v[134:137], v142 offset:1024
	ds_read_b128 v[138:141], v142 offset:2048
	ds_read_b128 v[142:145], v142 offset:3072
	ds_read_b128 v[146:149], v158
	ds_read_b128 v[150:153], v158 offset:1024
	ds_read_b128 v[154:157], v158 offset:2048
	ds_read_b128 v[158:161], v158 offset:3072
	s_add_u32 s82, s82, 0x80000
	s_addc_u32 s83, s83, 0
	s_mov_b32 m0, s45
	v_lshl_add_u64 v[216:217], s[82:83], 0, v[194:195]
	ds_read_b128 v[162:165], v233 offset:32768
	ds_read_b128 v[166:169], v233 offset:33792
	ds_read_b128 v[170:173], v233 offset:34816
	ds_read_b128 v[174:177], v233 offset:35840
	ds_read_b128 v[178:181], v233 offset:36864
	ds_read_b128 v[182:185], v233 offset:37888
	ds_read_b128 v[186:189], v233 offset:38912
	ds_read_b128 v[190:193], v233 offset:39936
	global_load_lds_dwordx4 v[216:217], off
	v_lshl_add_u64 v[216:217], s[82:83], 0, v[196:197]
	s_mov_b32 m0, s88
	s_nop 0
	global_load_lds_dwordx4 v[216:217], off
	s_waitcnt vmcnt(8)
	s_waitcnt lgkmcnt(0)
	s_barrier
	s_setprio 1
	s_waitcnt lgkmcnt(0)
	v_mfma_f32_16x16x32_bf16 v[130:133], v[126:129], v[162:165], v[130:133]
	v_mfma_f32_16x16x32_bf16 v[122:125], v[138:141], v[162:165], v[122:125]
	v_mfma_f32_16x16x32_bf16 v[110:113], v[126:129], v[170:173], v[110:113]
	v_mfma_f32_16x16x32_bf16 v[106:109], v[138:141], v[170:173], v[106:109]
	v_mfma_f32_16x16x32_bf16 v[94:97], v[126:129], v[178:181], v[94:97]
	v_mfma_f32_16x16x32_bf16 v[90:93], v[138:141], v[178:181], v[90:93]
	v_mfma_f32_16x16x32_bf16 v[78:81], v[126:129], v[186:189], v[78:81]
	v_mfma_f32_16x16x32_bf16 v[74:77], v[138:141], v[186:189], v[74:77]
	v_mfma_f32_16x16x32_bf16 v[130:133], v[134:137], v[166:169], v[130:133]
	v_mfma_f32_16x16x32_bf16 v[122:125], v[142:145], v[166:169], v[122:125]
	v_mfma_f32_16x16x32_bf16 v[110:113], v[134:137], v[174:177], v[110:113]
	v_mfma_f32_16x16x32_bf16 v[106:109], v[142:145], v[174:177], v[106:109]
	v_mfma_f32_16x16x32_bf16 v[94:97], v[134:137], v[182:185], v[94:97]
	v_mfma_f32_16x16x32_bf16 v[90:93], v[142:145], v[182:185], v[90:93]
	v_mfma_f32_16x16x32_bf16 v[78:81], v[134:137], v[190:193], v[78:81]
	v_mfma_f32_16x16x32_bf16 v[74:77], v[142:145], v[190:193], v[74:77]
	s_setprio 0
	s_setprio 1
	v_mfma_f32_16x16x32_bf16 v[118:121], v[146:149], v[162:165], v[118:121]
	v_mfma_f32_16x16x32_bf16 v[114:117], v[154:157], v[162:165], v[114:117]
	v_mfma_f32_16x16x32_bf16 v[102:105], v[146:149], v[170:173], v[102:105]
	v_mfma_f32_16x16x32_bf16 v[98:101], v[154:157], v[170:173], v[98:101]
	v_mfma_f32_16x16x32_bf16 v[86:89], v[146:149], v[178:181], v[86:89]
	v_mfma_f32_16x16x32_bf16 v[82:85], v[154:157], v[178:181], v[82:85]
	v_mfma_f32_16x16x32_bf16 v[70:73], v[146:149], v[186:189], v[70:73]
	v_mfma_f32_16x16x32_bf16 v[66:69], v[154:157], v[186:189], v[66:69]
	v_mfma_f32_16x16x32_bf16 v[118:121], v[150:153], v[166:169], v[118:121]
	v_mfma_f32_16x16x32_bf16 v[114:117], v[158:161], v[166:169], v[114:117]
	v_mfma_f32_16x16x32_bf16 v[102:105], v[150:153], v[174:177], v[102:105]
	v_mfma_f32_16x16x32_bf16 v[98:101], v[158:161], v[174:177], v[98:101]
	v_mfma_f32_16x16x32_bf16 v[86:89], v[150:153], v[182:185], v[86:89]
	v_mfma_f32_16x16x32_bf16 v[82:85], v[158:161], v[182:185], v[82:85]
	v_mfma_f32_16x16x32_bf16 v[70:73], v[150:153], v[190:193], v[70:73]
	v_mfma_f32_16x16x32_bf16 v[66:69], v[158:161], v[190:193], v[66:69]
	s_setprio 0
	s_barrier
	s_add_i32 s82, s87, s95
	v_lshl_add_u64 v[202:203], v[202:203], 0, s[54:55]
	s_mov_b32 m0, s82
	ds_read_b128 v[162:165], v233 offset:49152
	ds_read_b128 v[166:169], v233 offset:50176
	ds_read_b128 v[170:173], v233 offset:51200
	ds_read_b128 v[174:177], v233 offset:52224
	ds_read_b128 v[178:181], v233 offset:53248
	ds_read_b128 v[182:185], v233 offset:54272
	ds_read_b128 v[186:189], v233 offset:55296
	ds_read_b128 v[190:193], v233 offset:56320
	global_load_lds_dwordx4 v[202:203], off
	s_add_i32 m0, s82, 0x2000
	s_add_u32 s80, s80, 0x80080
	v_lshl_add_u64 v[202:203], v[204:205], 0, s[54:55]
	s_addc_u32 s81, s81, 0
	s_add_i32 s82, s92, s95
	global_load_lds_dwordx4 v[202:203], off
	v_lshl_add_u64 v[202:203], s[80:81], 0, v[194:195]
	s_mov_b32 m0, s82
	s_nop 0
	global_load_lds_dwordx4 v[202:203], off
	v_lshl_add_u64 v[202:203], s[80:81], 0, v[196:197]
	s_add_i32 m0, s82, 0x2000
	s_nop 0
	global_load_lds_dwordx4 v[202:203], off
	v_lshl_add_u64 v[202:203], v[206:207], 0, s[54:55]
	s_mov_b32 m0, s48
	s_nop 0
	global_load_lds_dwordx4 v[202:203], off
	v_lshl_add_u64 v[202:203], v[214:215], 0, s[54:55]
	s_mov_b32 m0, s49
	s_nop 0
	global_load_lds_dwordx4 v[202:203], off
	s_waitcnt vmcnt(8)
	s_waitcnt lgkmcnt(0)
	s_barrier
	s_setprio 1
	s_waitcnt lgkmcnt(0)
	v_mfma_f32_16x16x32_bf16 v[62:65], v[126:129], v[162:165], v[62:65]
	v_mfma_f32_16x16x32_bf16 v[58:61], v[138:141], v[162:165], v[58:61]
	v_mfma_f32_16x16x32_bf16 v[46:49], v[126:129], v[170:173], v[46:49]
	v_mfma_f32_16x16x32_bf16 v[42:45], v[138:141], v[170:173], v[42:45]
	v_mfma_f32_16x16x32_bf16 v[30:33], v[126:129], v[178:181], v[30:33]
	v_mfma_f32_16x16x32_bf16 v[26:29], v[138:141], v[178:181], v[26:29]
	v_mfma_f32_16x16x32_bf16 v[14:17], v[126:129], v[186:189], v[14:17]
	v_mfma_f32_16x16x32_bf16 v[10:13], v[138:141], v[186:189], v[10:13]
	v_mfma_f32_16x16x32_bf16 v[62:65], v[134:137], v[166:169], v[62:65]
	v_mfma_f32_16x16x32_bf16 v[58:61], v[142:145], v[166:169], v[58:61]
	v_mfma_f32_16x16x32_bf16 v[46:49], v[134:137], v[174:177], v[46:49]
	v_mfma_f32_16x16x32_bf16 v[42:45], v[142:145], v[174:177], v[42:45]
	v_mfma_f32_16x16x32_bf16 v[30:33], v[134:137], v[182:185], v[30:33]
	v_mfma_f32_16x16x32_bf16 v[26:29], v[142:145], v[182:185], v[26:29]
	v_mfma_f32_16x16x32_bf16 v[14:17], v[134:137], v[190:193], v[14:17]
	v_mfma_f32_16x16x32_bf16 v[10:13], v[142:145], v[190:193], v[10:13]
	s_setprio 0
	s_setprio 1
	v_mfma_f32_16x16x32_bf16 v[54:57], v[146:149], v[162:165], v[54:57]
	v_mfma_f32_16x16x32_bf16 v[50:53], v[154:157], v[162:165], v[50:53]
	v_mfma_f32_16x16x32_bf16 v[38:41], v[146:149], v[170:173], v[38:41]
	v_mfma_f32_16x16x32_bf16 v[34:37], v[154:157], v[170:173], v[34:37]
	v_mfma_f32_16x16x32_bf16 v[22:25], v[146:149], v[178:181], v[22:25]
	v_mfma_f32_16x16x32_bf16 v[18:21], v[154:157], v[178:181], v[18:21]
	v_mfma_f32_16x16x32_bf16 v[6:9], v[146:149], v[186:189], v[6:9]
	v_mfma_f32_16x16x32_bf16 v[2:5], v[154:157], v[186:189], v[2:5]
	v_mfma_f32_16x16x32_bf16 v[54:57], v[150:153], v[166:169], v[54:57]
	v_mfma_f32_16x16x32_bf16 v[50:53], v[158:161], v[166:169], v[50:53]
	v_mfma_f32_16x16x32_bf16 v[38:41], v[150:153], v[174:177], v[38:41]
	v_mfma_f32_16x16x32_bf16 v[34:37], v[158:161], v[174:177], v[34:37]
	v_mfma_f32_16x16x32_bf16 v[22:25], v[150:153], v[182:185], v[22:25]
	v_mfma_f32_16x16x32_bf16 v[18:21], v[158:161], v[182:185], v[18:21]
	v_mfma_f32_16x16x32_bf16 v[6:9], v[150:153], v[190:193], v[6:9]
	v_mfma_f32_16x16x32_bf16 v[2:5], v[158:161], v[190:193], v[2:5]
	s_setprio 0
	s_barrier
	s_add_i32 s86, s86, 2
	s_add_u32 s84, s84, 0x100
	s_addc_u32 s85, s85, 0
	s_add_u32 s8, s8, 0x100
	s_addc_u32 s9, s9, 0
	s_cmp_gt_u32 s86, 29
	s_cbranch_scc1 .Lpeel_exit_G1
.LBB0_605:
	s_add_u32 s80, s8, 0xfff80080
	s_addc_u32 s81, s9, -1
	s_add_i32 s87, 0, 0x10000
	s_cmp_eq_u32 s86, 28
	s_cselect_b32 s83, s11, s81
	s_cselect_b32 s82, s35, s80
	s_cselect_b32 s81, s31, s85
	s_cselect_b32 s80, s79, s84
	s_add_i32 s92, 0, 0x14000
	v_add_u32_e32 v142, s87, v228
	v_add_u32_e32 v158, s92, v228
	ds_read_b128 v[126:129], v142
	ds_read_b128 v[134:137], v142 offset:1024
	ds_read_b128 v[138:141], v142 offset:2048
	ds_read_b128 v[142:145], v142 offset:3072
	ds_read_b128 v[146:149], v158
	ds_read_b128 v[150:153], v158 offset:1024
	ds_read_b128 v[154:157], v158 offset:2048
	ds_read_b128 v[158:161], v158 offset:3072
	v_lshl_add_u64 v[202:203], s[8:9], 0, v[210:211]
	s_add_i32 m0, s61, 0xc000
	ds_read_b128 v[162:165], v233
	ds_read_b128 v[166:169], v233 offset:1024
	ds_read_b128 v[170:173], v233 offset:2048
	ds_read_b128 v[174:177], v233 offset:3072
	ds_read_b128 v[178:181], v233 offset:4096
	ds_read_b128 v[182:185], v233 offset:5120
	ds_read_b128 v[186:189], v233 offset:6144
	ds_read_b128 v[190:193], v233 offset:7168
	global_load_lds_dwordx4 v[202:203], off
	v_lshl_add_u64 v[202:203], s[8:9], 0, v[208:209]
	s_add_i32 m0, s61, 0xe000
	s_nop 0
	global_load_lds_dwordx4 v[202:203], off
	s_waitcnt vmcnt(8)
	s_waitcnt lgkmcnt(0)
	s_barrier
	s_setprio 1
	s_waitcnt lgkmcnt(0)
	v_mfma_f32_16x16x32_bf16 v[130:133], v[126:129], v[162:165], v[130:133]
	v_mfma_f32_16x16x32_bf16 v[122:125], v[138:141], v[162:165], v[122:125]
	v_mfma_f32_16x16x32_bf16 v[110:113], v[126:129], v[170:173], v[110:113]
	v_mfma_f32_16x16x32_bf16 v[106:109], v[138:141], v[170:173], v[106:109]
	v_mfma_f32_16x16x32_bf16 v[94:97], v[126:129], v[178:181], v[94:97]
	v_mfma_f32_16x16x32_bf16 v[90:93], v[138:141], v[178:181], v[90:93]
	v_mfma_f32_16x16x32_bf16 v[78:81], v[126:129], v[186:189], v[78:81]
	v_mfma_f32_16x16x32_bf16 v[74:77], v[138:141], v[186:189], v[74:77]
	v_mfma_f32_16x16x32_bf16 v[130:133], v[134:137], v[166:169], v[130:133]
	v_mfma_f32_16x16x32_bf16 v[122:125], v[142:145], v[166:169], v[122:125]
	v_mfma_f32_16x16x32_bf16 v[110:113], v[134:137], v[174:177], v[110:113]
	v_mfma_f32_16x16x32_bf16 v[106:109], v[142:145], v[174:177], v[106:109]
	v_mfma_f32_16x16x32_bf16 v[94:97], v[134:137], v[182:185], v[94:97]
	v_mfma_f32_16x16x32_bf16 v[90:93], v[142:145], v[182:185], v[90:93]
	v_mfma_f32_16x16x32_bf16 v[78:81], v[134:137], v[190:193], v[78:81]
	v_mfma_f32_16x16x32_bf16 v[74:77], v[142:145], v[190:193], v[74:77]
	s_setprio 0
	s_setprio 1
	v_mfma_f32_16x16x32_bf16 v[118:121], v[146:149], v[162:165], v[118:121]
	v_mfma_f32_16x16x32_bf16 v[114:117], v[154:157], v[162:165], v[114:117]
	v_mfma_f32_16x16x32_bf16 v[102:105], v[146:149], v[170:173], v[102:105]
	v_mfma_f32_16x16x32_bf16 v[98:101], v[154:157], v[170:173], v[98:101]
	v_mfma_f32_16x16x32_bf16 v[86:89], v[146:149], v[178:181], v[86:89]
	v_mfma_f32_16x16x32_bf16 v[82:85], v[154:157], v[178:181], v[82:85]
	v_mfma_f32_16x16x32_bf16 v[70:73], v[146:149], v[186:189], v[70:73]
	v_mfma_f32_16x16x32_bf16 v[66:69], v[154:157], v[186:189], v[66:69]
	v_mfma_f32_16x16x32_bf16 v[118:121], v[150:153], v[166:169], v[118:121]
	v_mfma_f32_16x16x32_bf16 v[114:117], v[158:161], v[166:169], v[114:117]
	v_mfma_f32_16x16x32_bf16 v[102:105], v[150:153], v[174:177], v[102:105]
	v_mfma_f32_16x16x32_bf16 v[98:101], v[158:161], v[174:177], v[98:101]
	v_mfma_f32_16x16x32_bf16 v[86:89], v[150:153], v[182:185], v[86:89]
	v_mfma_f32_16x16x32_bf16 v[82:85], v[158:161], v[182:185], v[82:85]
	v_mfma_f32_16x16x32_bf16 v[70:73], v[150:153], v[190:193], v[70:73]
	v_mfma_f32_16x16x32_bf16 v[66:69], v[158:161], v[190:193], v[66:69]
	s_setprio 0
	s_barrier
	s_add_i32 s87, s87, s95
	v_lshl_add_u64 v[202:203], s[80:81], 0, v[194:195]
	s_mov_b32 m0, s87
	ds_read_b128 v[162:165], v233 offset:16384
	ds_read_b128 v[166:169], v233 offset:17408
	ds_read_b128 v[170:173], v233 offset:18432
	ds_read_b128 v[174:177], v233 offset:19456
	ds_read_b128 v[178:181], v233 offset:20480
	ds_read_b128 v[182:185], v233 offset:21504
	ds_read_b128 v[186:189], v233 offset:22528
	ds_read_b128 v[190:193], v233 offset:23552
	global_load_lds_dwordx4 v[202:203], off
	s_add_i32 m0, s87, 0x2000
	s_add_u32 vcc_lo, s80, 0x80000
	v_lshl_add_u64 v[204:205], s[80:81], 0, v[196:197]
	s_addc_u32 vcc_hi, s81, 0
	s_add_i32 s87, s92, s95
	global_load_lds_dwordx4 v[204:205], off
	v_lshl_add_u64 v[206:207], vcc, 0, v[194:195]
	s_mov_b32 m0, s87
	v_lshl_add_u64 v[214:215], s[82:83], 0, v[196:197]
	global_load_lds_dwordx4 v[206:207], off
	v_lshl_add_u64 v[206:207], vcc, 0, v[196:197]
	s_add_i32 m0, s87, 0x2000
	s_nop 0
	global_load_lds_dwordx4 v[206:207], off
	v_lshl_add_u64 v[206:207], s[82:83], 0, v[194:195]
	s_mov_b32 m0, s61
	s_nop 0
	global_load_lds_dwordx4 v[206:207], off
	s_mov_b32 m0, s44
	s_nop 0
	global_load_lds_dwordx4 v[214:215], off
	s_waitcnt vmcnt(8)
	s_waitcnt lgkmcnt(0)
	s_barrier
	s_setprio 1
	s_waitcnt lgkmcnt(0)
	v_mfma_f32_16x16x32_bf16 v[62:65], v[126:129], v[162:165], v[62:65]
	v_mfma_f32_16x16x32_bf16 v[58:61], v[138:141], v[162:165], v[58:61]
	v_mfma_f32_16x16x32_bf16 v[46:49], v[126:129], v[170:173], v[46:49]
	v_mfma_f32_16x16x32_bf16 v[42:45], v[138:141], v[170:173], v[42:45]
	v_mfma_f32_16x16x32_bf16 v[30:33], v[126:129], v[178:181], v[30:33]
	v_mfma_f32_16x16x32_bf16 v[26:29], v[138:141], v[178:181], v[26:29]
	v_mfma_f32_16x16x32_bf16 v[14:17], v[126:129], v[186:189], v[14:17]
	v_mfma_f32_16x16x32_bf16 v[10:13], v[138:141], v[186:189], v[10:13]
	v_mfma_f32_16x16x32_bf16 v[62:65], v[134:137], v[166:169], v[62:65]
	v_mfma_f32_16x16x32_bf16 v[58:61], v[142:145], v[166:169], v[58:61]
	v_mfma_f32_16x16x32_bf16 v[46:49], v[134:137], v[174:177], v[46:49]
	v_mfma_f32_16x16x32_bf16 v[42:45], v[142:145], v[174:177], v[42:45]
	v_mfma_f32_16x16x32_bf16 v[30:33], v[134:137], v[182:185], v[30:33]
	v_mfma_f32_16x16x32_bf16 v[26:29], v[142:145], v[182:185], v[26:29]
	v_mfma_f32_16x16x32_bf16 v[14:17], v[134:137], v[190:193], v[14:17]
	v_mfma_f32_16x16x32_bf16 v[10:13], v[142:145], v[190:193], v[10:13]
	s_setprio 0
	s_setprio 1
	v_mfma_f32_16x16x32_bf16 v[54:57], v[146:149], v[162:165], v[54:57]
	v_mfma_f32_16x16x32_bf16 v[50:53], v[154:157], v[162:165], v[50:53]
	v_mfma_f32_16x16x32_bf16 v[38:41], v[146:149], v[170:173], v[38:41]
	v_mfma_f32_16x16x32_bf16 v[34:37], v[154:157], v[170:173], v[34:37]
	v_mfma_f32_16x16x32_bf16 v[22:25], v[146:149], v[178:181], v[22:25]
	v_mfma_f32_16x16x32_bf16 v[18:21], v[154:157], v[178:181], v[18:21]
	v_mfma_f32_16x16x32_bf16 v[6:9], v[146:149], v[186:189], v[6:9]
	v_mfma_f32_16x16x32_bf16 v[2:5], v[154:157], v[186:189], v[2:5]
	v_mfma_f32_16x16x32_bf16 v[54:57], v[150:153], v[166:169], v[54:57]
	v_mfma_f32_16x16x32_bf16 v[50:53], v[158:161], v[166:169], v[50:53]
	v_mfma_f32_16x16x32_bf16 v[38:41], v[150:153], v[174:177], v[38:41]
	v_mfma_f32_16x16x32_bf16 v[34:37], v[158:161], v[174:177], v[34:37]
	v_mfma_f32_16x16x32_bf16 v[22:25], v[150:153], v[182:185], v[22:25]
	v_mfma_f32_16x16x32_bf16 v[18:21], v[158:161], v[182:185], v[18:21]
	v_mfma_f32_16x16x32_bf16 v[6:9], v[150:153], v[190:193], v[6:9]
	v_mfma_f32_16x16x32_bf16 v[2:5], v[158:161], v[190:193], v[2:5]
	s_setprio 0
	s_barrier
	s_add_i32 s87, 0, 0x18000
	s_add_i32 s92, 0, 0x1c000
	v_add_u32_e32 v142, s87, v228
	v_add_u32_e32 v158, s92, v228
	ds_read_b128 v[126:129], v142
	ds_read_b128 v[134:137], v142 offset:1024
	ds_read_b128 v[138:141], v142 offset:2048
	ds_read_b128 v[142:145], v142 offset:3072
	ds_read_b128 v[146:149], v158
	ds_read_b128 v[150:153], v158 offset:1024
	ds_read_b128 v[154:157], v158 offset:2048
	ds_read_b128 v[158:161], v158 offset:3072
	s_add_u32 s82, s82, 0x80000
	s_addc_u32 s83, s83, 0
	s_mov_b32 m0, s45
	v_lshl_add_u64 v[216:217], s[82:83], 0, v[194:195]
	ds_read_b128 v[162:165], v233 offset:32768
	ds_read_b128 v[166:169], v233 offset:33792
	ds_read_b128 v[170:173], v233 offset:34816
	ds_read_b128 v[174:177], v233 offset:35840
	ds_read_b128 v[178:181], v233 offset:36864
	ds_read_b128 v[182:185], v233 offset:37888
	ds_read_b128 v[186:189], v233 offset:38912
	ds_read_b128 v[190:193], v233 offset:39936
	global_load_lds_dwordx4 v[216:217], off
	v_lshl_add_u64 v[216:217], s[82:83], 0, v[196:197]
	s_mov_b32 m0, s88
	s_nop 0
	global_load_lds_dwordx4 v[216:217], off
	s_waitcnt vmcnt(8)
	s_waitcnt lgkmcnt(0)
	s_barrier
	s_setprio 1
	s_waitcnt lgkmcnt(0)
	v_mfma_f32_16x16x32_bf16 v[130:133], v[126:129], v[162:165], v[130:133]
	v_mfma_f32_16x16x32_bf16 v[122:125], v[138:141], v[162:165], v[122:125]
	v_mfma_f32_16x16x32_bf16 v[110:113], v[126:129], v[170:173], v[110:113]
	v_mfma_f32_16x16x32_bf16 v[106:109], v[138:141], v[170:173], v[106:109]
	v_mfma_f32_16x16x32_bf16 v[94:97], v[126:129], v[178:181], v[94:97]
	v_mfma_f32_16x16x32_bf16 v[90:93], v[138:141], v[178:181], v[90:93]
	v_mfma_f32_16x16x32_bf16 v[78:81], v[126:129], v[186:189], v[78:81]
	v_mfma_f32_16x16x32_bf16 v[74:77], v[138:141], v[186:189], v[74:77]
	v_mfma_f32_16x16x32_bf16 v[130:133], v[134:137], v[166:169], v[130:133]
	v_mfma_f32_16x16x32_bf16 v[122:125], v[142:145], v[166:169], v[122:125]
	v_mfma_f32_16x16x32_bf16 v[110:113], v[134:137], v[174:177], v[110:113]
	v_mfma_f32_16x16x32_bf16 v[106:109], v[142:145], v[174:177], v[106:109]
	v_mfma_f32_16x16x32_bf16 v[94:97], v[134:137], v[182:185], v[94:97]
	v_mfma_f32_16x16x32_bf16 v[90:93], v[142:145], v[182:185], v[90:93]
	v_mfma_f32_16x16x32_bf16 v[78:81], v[134:137], v[190:193], v[78:81]
	v_mfma_f32_16x16x32_bf16 v[74:77], v[142:145], v[190:193], v[74:77]
	s_setprio 0
	s_setprio 1
	v_mfma_f32_16x16x32_bf16 v[118:121], v[146:149], v[162:165], v[118:121]
	v_mfma_f32_16x16x32_bf16 v[114:117], v[154:157], v[162:165], v[114:117]
	v_mfma_f32_16x16x32_bf16 v[102:105], v[146:149], v[170:173], v[102:105]
	v_mfma_f32_16x16x32_bf16 v[98:101], v[154:157], v[170:173], v[98:101]
	v_mfma_f32_16x16x32_bf16 v[86:89], v[146:149], v[178:181], v[86:89]
	v_mfma_f32_16x16x32_bf16 v[82:85], v[154:157], v[178:181], v[82:85]
	v_mfma_f32_16x16x32_bf16 v[70:73], v[146:149], v[186:189], v[70:73]
	v_mfma_f32_16x16x32_bf16 v[66:69], v[154:157], v[186:189], v[66:69]
	v_mfma_f32_16x16x32_bf16 v[118:121], v[150:153], v[166:169], v[118:121]
	v_mfma_f32_16x16x32_bf16 v[114:117], v[158:161], v[166:169], v[114:117]
	v_mfma_f32_16x16x32_bf16 v[102:105], v[150:153], v[174:177], v[102:105]
	v_mfma_f32_16x16x32_bf16 v[98:101], v[158:161], v[174:177], v[98:101]
	v_mfma_f32_16x16x32_bf16 v[86:89], v[150:153], v[182:185], v[86:89]
	v_mfma_f32_16x16x32_bf16 v[82:85], v[158:161], v[182:185], v[82:85]
	v_mfma_f32_16x16x32_bf16 v[70:73], v[150:153], v[190:193], v[70:73]
	v_mfma_f32_16x16x32_bf16 v[66:69], v[158:161], v[190:193], v[66:69]
	s_setprio 0
	s_barrier
	s_add_i32 s82, s87, s95
	v_lshl_add_u64 v[202:203], v[202:203], 0, s[54:55]
	s_mov_b32 m0, s82
	ds_read_b128 v[162:165], v233 offset:49152
	ds_read_b128 v[166:169], v233 offset:50176
	ds_read_b128 v[170:173], v233 offset:51200
	ds_read_b128 v[174:177], v233 offset:52224
	ds_read_b128 v[178:181], v233 offset:53248
	ds_read_b128 v[182:185], v233 offset:54272
	ds_read_b128 v[186:189], v233 offset:55296
	ds_read_b128 v[190:193], v233 offset:56320
	global_load_lds_dwordx4 v[202:203], off
	s_add_i32 m0, s82, 0x2000
	s_add_u32 s80, s80, 0x80080
	v_lshl_add_u64 v[202:203], v[204:205], 0, s[54:55]
	s_addc_u32 s81, s81, 0
	s_add_i32 s82, s92, s95
	global_load_lds_dwordx4 v[202:203], off
	v_lshl_add_u64 v[202:203], s[80:81], 0, v[194:195]
	s_mov_b32 m0, s82
	s_nop 0
	global_load_lds_dwordx4 v[202:203], off
	v_lshl_add_u64 v[202:203], s[80:81], 0, v[196:197]
	s_add_i32 m0, s82, 0x2000
	s_nop 0
	global_load_lds_dwordx4 v[202:203], off
	v_lshl_add_u64 v[202:203], v[206:207], 0, s[54:55]
	s_mov_b32 m0, s48
	s_nop 0
	global_load_lds_dwordx4 v[202:203], off
	v_lshl_add_u64 v[202:203], v[214:215], 0, s[54:55]
	s_mov_b32 m0, s49
	s_nop 0
	global_load_lds_dwordx4 v[202:203], off
	s_waitcnt vmcnt(8)
	s_waitcnt lgkmcnt(0)
	s_barrier
	s_setprio 1
	s_waitcnt lgkmcnt(0)
	v_mfma_f32_16x16x32_bf16 v[62:65], v[126:129], v[162:165], v[62:65]
	v_mfma_f32_16x16x32_bf16 v[58:61], v[138:141], v[162:165], v[58:61]
	v_mfma_f32_16x16x32_bf16 v[46:49], v[126:129], v[170:173], v[46:49]
	v_mfma_f32_16x16x32_bf16 v[42:45], v[138:141], v[170:173], v[42:45]
	v_mfma_f32_16x16x32_bf16 v[30:33], v[126:129], v[178:181], v[30:33]
	v_mfma_f32_16x16x32_bf16 v[26:29], v[138:141], v[178:181], v[26:29]
	v_mfma_f32_16x16x32_bf16 v[14:17], v[126:129], v[186:189], v[14:17]
	v_mfma_f32_16x16x32_bf16 v[10:13], v[138:141], v[186:189], v[10:13]
	v_mfma_f32_16x16x32_bf16 v[62:65], v[134:137], v[166:169], v[62:65]
	v_mfma_f32_16x16x32_bf16 v[58:61], v[142:145], v[166:169], v[58:61]
	v_mfma_f32_16x16x32_bf16 v[46:49], v[134:137], v[174:177], v[46:49]
	v_mfma_f32_16x16x32_bf16 v[42:45], v[142:145], v[174:177], v[42:45]
	v_mfma_f32_16x16x32_bf16 v[30:33], v[134:137], v[182:185], v[30:33]
	v_mfma_f32_16x16x32_bf16 v[26:29], v[142:145], v[182:185], v[26:29]
	v_mfma_f32_16x16x32_bf16 v[14:17], v[134:137], v[190:193], v[14:17]
	v_mfma_f32_16x16x32_bf16 v[10:13], v[142:145], v[190:193], v[10:13]
	s_setprio 0
	s_setprio 1
	v_mfma_f32_16x16x32_bf16 v[54:57], v[146:149], v[162:165], v[54:57]
	v_mfma_f32_16x16x32_bf16 v[50:53], v[154:157], v[162:165], v[50:53]
	v_mfma_f32_16x16x32_bf16 v[38:41], v[146:149], v[170:173], v[38:41]
	v_mfma_f32_16x16x32_bf16 v[34:37], v[154:157], v[170:173], v[34:37]
	v_mfma_f32_16x16x32_bf16 v[22:25], v[146:149], v[178:181], v[22:25]
	v_mfma_f32_16x16x32_bf16 v[18:21], v[154:157], v[178:181], v[18:21]
	v_mfma_f32_16x16x32_bf16 v[6:9], v[146:149], v[186:189], v[6:9]
	v_mfma_f32_16x16x32_bf16 v[2:5], v[154:157], v[186:189], v[2:5]
	v_mfma_f32_16x16x32_bf16 v[54:57], v[150:153], v[166:169], v[54:57]
	v_mfma_f32_16x16x32_bf16 v[50:53], v[158:161], v[166:169], v[50:53]
	v_mfma_f32_16x16x32_bf16 v[38:41], v[150:153], v[174:177], v[38:41]
	v_mfma_f32_16x16x32_bf16 v[34:37], v[158:161], v[174:177], v[34:37]
	v_mfma_f32_16x16x32_bf16 v[22:25], v[150:153], v[182:185], v[22:25]
	v_mfma_f32_16x16x32_bf16 v[18:21], v[158:161], v[182:185], v[18:21]
	v_mfma_f32_16x16x32_bf16 v[6:9], v[150:153], v[190:193], v[6:9]
	v_mfma_f32_16x16x32_bf16 v[2:5], v[158:161], v[190:193], v[2:5]
	s_setprio 0
	s_barrier
	s_add_i32 s86, s86, 2
	s_add_u32 s84, s84, 0x100
	s_addc_u32 s85, s85, 0
	s_add_u32 s8, s8, 0x100
	s_addc_u32 s9, s9, 0
	s_cmp_gt_u32 s86, 29
	s_cbranch_scc0 .LBB0_605

.LBB0_877:
	v_lshl_add_u64 v[10:11], s[36:37], 0, v[0:1]
	v_mov_b32_e32 v131, v1
	v_and_b32_e32 v221, 15, v212
	v_and_b32_e32 v18, 48, v212
	v_lshlrev_b32_e32 v19, 2, v212
	v_lshl_add_u64 v[12:13], s[36:37], 0, v[130:131]
	s_and_b32 s33, s19, 3
	s_lshl_b32 s4, s7, 13
	v_lshl_or_b32 v18, v221, 6, v18
	v_and_b32_e32 v19, 32, v19
	s_add_i32 m0, s21, 0x18000
	v_lshl_add_u64 v[10:11], v[10:11], 0, s[54:55]
	v_lshl_add_u64 v[14:15], s[24:25], 0, v[0:1]
	s_lshl_b32 s80, s7, 6
	v_bitop3_b32 v20, v18, s4, v19 bitop3:0xde
	s_lshl_b32 s4, s33, 12
	s_waitcnt vmcnt(2)
	s_barrier
	global_load_lds_dwordx4 v[10:11], off
	v_lshl_add_u64 v[10:11], v[12:13], 0, s[54:55]
	s_add_i32 m0, s21, 0x1a000
	s_add_i32 s68, s21, 0x8000
	s_add_i32 s69, s21, 0xa000
	v_lshl_add_u64 v[16:17], s[24:25], 0, v[130:131]
	v_bitop3_b32 v140, v18, s4, v19 bitop3:0xde
	global_load_lds_dwordx4 v[10:11], off
	v_lshl_add_u64 v[10:11], v[14:15], 0, s[54:55]
	s_mov_b32 m0, s68
	s_add_u32 s4, s36, 0x80080
	global_load_lds_dwordx4 v[10:11], off
	v_lshl_add_u64 v[10:11], v[16:17], 0, s[54:55]
	s_mov_b32 m0, s69
	s_addc_u32 s5, s37, 0
	global_load_lds_dwordx4 v[10:11], off
	s_add_i32 m0, s21, 0x1c000
	v_lshl_add_u64 v[10:11], s[4:5], 0, v[0:1]
	global_load_lds_dwordx4 v[10:11], off
	v_lshl_add_u64 v[10:11], s[4:5], 0, v[130:131]
	s_add_i32 m0, s21, 0x1e000
	v_lshlrev_b32_e32 v2, 14, v2
	global_load_lds_dwordx4 v[10:11], off
	v_lshlrev_b32_e32 v6, 14, v6
	v_and_b32_e32 v2, 0x7fff8000, v2
	v_and_b32_e32 v6, 0x7fff8000, v6
	v_lshl_add_u32 v2, v3, 11, v2
	s_waitcnt vmcnt(6)
	v_lshl_add_u32 v6, v7, 11, v6
	v_or_b32_e32 v2, v2, v4
	v_or_b32_e32 v6, v6, v8
	v_add_lshl_u32 v134, v2, v5, 1
	s_sext_i32_i8 s18, s6
	v_or_b32_e32 v211, s80, v221
	v_add_lshl_u32 v132, v6, v9, 1
	v_mov_b32_e32 v133, v1
	v_mov_b32_e32 v135, v1
	s_mov_b32 s70, 0
	v_add_u32_e32 v141, 0, v20
	s_barrier

.Lz0_G2a:
	s_add_u32 s38, s24, s36
	s_addc_u32 s39, s25, s37
	s_add_u32 s38, s38, 0x100
	s_addc_u32 s39, s39, 0
	s_add_u32 s88, s72, s36
	s_addc_u32 s89, s73, s37
	s_add_i32 s92, 0, 0x10000
	s_cmpk_eq_i32 s36, 0xf00
	s_cselect_b32 s79, s29, s39
	s_cselect_b32 s78, s81, s38
	s_cselect_b32 s39, s27, s89
	s_cselect_b32 s38, s86, s88
	s_add_i32 s93, 0, 0x14000
	v_add_u32_e32 v154, s92, v140
	v_add_u32_e32 v170, s93, v140
	ds_read_b128 v[142:145], v154
	ds_read_b128 v[146:149], v154 offset:1024
	ds_read_b128 v[150:153], v154 offset:2048
	ds_read_b128 v[154:157], v154 offset:3072
	ds_read_b128 v[158:161], v170
	ds_read_b128 v[162:165], v170 offset:1024
	ds_read_b128 v[166:169], v170 offset:2048
	ds_read_b128 v[170:173], v170 offset:3072
	v_lshl_add_u64 v[206:207], v[138:139], 0, s[36:37]
	s_add_i32 m0, s21, 0xc000
	ds_read_b128 v[174:177], v141
	ds_read_b128 v[178:181], v141 offset:1024
	ds_read_b128 v[182:185], v141 offset:2048
	ds_read_b128 v[186:189], v141 offset:3072
	ds_read_b128 v[190:193], v141 offset:4096
	ds_read_b128 v[194:197], v141 offset:5120
	ds_read_b128 v[198:201], v141 offset:6144
	ds_read_b128 v[202:205], v141 offset:7168
	global_load_lds_dwordx4 v[206:207], off
	v_lshl_add_u64 v[206:207], v[136:137], 0, s[36:37]
	s_add_i32 m0, s21, 0xe000
	s_nop 0
	global_load_lds_dwordx4 v[206:207], off
	s_waitcnt vmcnt(8)
	s_waitcnt lgkmcnt(0)
	s_barrier
	s_setprio 1
	s_waitcnt lgkmcnt(0)
	v_mfma_f32_16x16x32_bf16 v[126:129], v[142:145], v[174:177], 0
	v_mfma_f32_16x16x32_bf16 v[122:125], v[150:153], v[174:177], 0
	v_mfma_f32_16x16x32_bf16 v[110:113], v[142:145], v[182:185], 0
	v_mfma_f32_16x16x32_bf16 v[106:109], v[150:153], v[182:185], 0
	v_mfma_f32_16x16x32_bf16 v[98:101], v[142:145], v[190:193], 0
	v_mfma_f32_16x16x32_bf16 v[90:93], v[150:153], v[190:193], 0
	v_mfma_f32_16x16x32_bf16 v[82:85], v[142:145], v[198:201], 0
	v_mfma_f32_16x16x32_bf16 v[74:77], v[150:153], v[198:201], 0
	v_mfma_f32_16x16x32_bf16 v[126:129], v[146:149], v[178:181], v[126:129]
	v_mfma_f32_16x16x32_bf16 v[122:125], v[154:157], v[178:181], v[122:125]
	v_mfma_f32_16x16x32_bf16 v[110:113], v[146:149], v[186:189], v[110:113]
	v_mfma_f32_16x16x32_bf16 v[106:109], v[154:157], v[186:189], v[106:109]
	v_mfma_f32_16x16x32_bf16 v[98:101], v[146:149], v[194:197], v[98:101]
	v_mfma_f32_16x16x32_bf16 v[90:93], v[154:157], v[194:197], v[90:93]
	v_mfma_f32_16x16x32_bf16 v[82:85], v[146:149], v[202:205], v[82:85]
	v_mfma_f32_16x16x32_bf16 v[74:77], v[154:157], v[202:205], v[74:77]
	s_setprio 0
	s_setprio 1
	v_mfma_f32_16x16x32_bf16 v[118:121], v[158:161], v[174:177], 0
	v_mfma_f32_16x16x32_bf16 v[114:117], v[166:169], v[174:177], 0
	v_mfma_f32_16x16x32_bf16 v[102:105], v[158:161], v[182:185], 0
	v_mfma_f32_16x16x32_bf16 v[94:97], v[166:169], v[182:185], 0
	v_mfma_f32_16x16x32_bf16 v[86:89], v[158:161], v[190:193], 0
	v_mfma_f32_16x16x32_bf16 v[78:81], v[166:169], v[190:193], 0
	v_mfma_f32_16x16x32_bf16 v[70:73], v[158:161], v[198:201], 0
	v_mfma_f32_16x16x32_bf16 v[66:69], v[166:169], v[198:201], 0
	v_mfma_f32_16x16x32_bf16 v[118:121], v[162:165], v[178:181], v[118:121]
	v_mfma_f32_16x16x32_bf16 v[114:117], v[170:173], v[178:181], v[114:117]
	v_mfma_f32_16x16x32_bf16 v[102:105], v[162:165], v[186:189], v[102:105]
	v_mfma_f32_16x16x32_bf16 v[94:97], v[170:173], v[186:189], v[94:97]
	v_mfma_f32_16x16x32_bf16 v[86:89], v[162:165], v[194:197], v[86:89]
	v_mfma_f32_16x16x32_bf16 v[78:81], v[170:173], v[194:197], v[78:81]
	v_mfma_f32_16x16x32_bf16 v[70:73], v[162:165], v[202:205], v[70:73]
	v_mfma_f32_16x16x32_bf16 v[66:69], v[170:173], v[202:205], v[66:69]
	s_setprio 0
	s_barrier
	s_add_i32 s88, s92, s48
	v_lshl_add_u64 v[206:207], s[38:39], 0, v[0:1]
	s_mov_b32 m0, s88
	ds_read_b128 v[174:177], v141 offset:16384
	ds_read_b128 v[178:181], v141 offset:17408
	ds_read_b128 v[182:185], v141 offset:18432
	ds_read_b128 v[186:189], v141 offset:19456
	ds_read_b128 v[190:193], v141 offset:20480
	ds_read_b128 v[194:197], v141 offset:21504
	ds_read_b128 v[198:201], v141 offset:22528
	ds_read_b128 v[202:205], v141 offset:23552
	global_load_lds_dwordx4 v[206:207], off
	s_add_i32 m0, s88, 0x2000
	s_add_u32 s88, s38, 0x80000
	v_lshl_add_u64 v[208:209], s[38:39], 0, v[130:131]
	s_addc_u32 s89, s39, 0
	s_add_i32 s92, s93, s48
	global_load_lds_dwordx4 v[208:209], off
	v_lshl_add_u64 v[214:215], s[88:89], 0, v[0:1]
	s_mov_b32 m0, s92
	v_lshl_add_u64 v[216:217], s[78:79], 0, v[130:131]
	global_load_lds_dwordx4 v[214:215], off
	v_lshl_add_u64 v[214:215], s[88:89], 0, v[130:131]
	s_add_i32 m0, s92, 0x2000
	s_nop 0
	global_load_lds_dwordx4 v[214:215], off
	v_lshl_add_u64 v[214:215], s[78:79], 0, v[0:1]
	s_mov_b32 m0, s21
	s_nop 0
	global_load_lds_dwordx4 v[214:215], off
	s_mov_b32 m0, s49
	s_nop 0
	global_load_lds_dwordx4 v[216:217], off
	s_waitcnt vmcnt(8)
	s_waitcnt lgkmcnt(0)
	s_barrier
	s_setprio 1
	s_waitcnt lgkmcnt(0)
	v_mfma_f32_16x16x32_bf16 v[62:65], v[142:145], v[174:177], 0
	v_mfma_f32_16x16x32_bf16 v[58:61], v[150:153], v[174:177], 0
	v_mfma_f32_16x16x32_bf16 v[50:53], v[142:145], v[182:185], 0
	v_mfma_f32_16x16x32_bf16 v[42:45], v[150:153], v[182:185], 0
	v_mfma_f32_16x16x32_bf16 v[34:37], v[142:145], v[190:193], 0
	v_mfma_f32_16x16x32_bf16 v[26:29], v[150:153], v[190:193], 0
	v_mfma_f32_16x16x32_bf16 v[18:21], v[142:145], v[198:201], 0
	v_mfma_f32_16x16x32_bf16 v[10:13], v[150:153], v[198:201], 0
	v_mfma_f32_16x16x32_bf16 v[62:65], v[146:149], v[178:181], v[62:65]
	v_mfma_f32_16x16x32_bf16 v[58:61], v[154:157], v[178:181], v[58:61]
	v_mfma_f32_16x16x32_bf16 v[50:53], v[146:149], v[186:189], v[50:53]
	v_mfma_f32_16x16x32_bf16 v[42:45], v[154:157], v[186:189], v[42:45]
	v_mfma_f32_16x16x32_bf16 v[34:37], v[146:149], v[194:197], v[34:37]
	v_mfma_f32_16x16x32_bf16 v[26:29], v[154:157], v[194:197], v[26:29]
	v_mfma_f32_16x16x32_bf16 v[18:21], v[146:149], v[202:205], v[18:21]
	v_mfma_f32_16x16x32_bf16 v[10:13], v[154:157], v[202:205], v[10:13]
	s_setprio 0
	s_setprio 1
	v_mfma_f32_16x16x32_bf16 v[54:57], v[158:161], v[174:177], 0
	v_mfma_f32_16x16x32_bf16 v[46:49], v[166:169], v[174:177], 0
	v_mfma_f32_16x16x32_bf16 v[38:41], v[158:161], v[182:185], 0
	v_mfma_f32_16x16x32_bf16 v[30:33], v[166:169], v[182:185], 0
	v_mfma_f32_16x16x32_bf16 v[22:25], v[158:161], v[190:193], 0
	v_mfma_f32_16x16x32_bf16 v[14:17], v[166:169], v[190:193], 0
	v_mfma_f32_16x16x32_bf16 v[6:9], v[158:161], v[198:201], 0
	v_mfma_f32_16x16x32_bf16 v[2:5], v[166:169], v[198:201], 0
	v_mfma_f32_16x16x32_bf16 v[54:57], v[162:165], v[178:181], v[54:57]
	v_mfma_f32_16x16x32_bf16 v[46:49], v[170:173], v[178:181], v[46:49]
	v_mfma_f32_16x16x32_bf16 v[38:41], v[162:165], v[186:189], v[38:41]
	v_mfma_f32_16x16x32_bf16 v[30:33], v[170:173], v[186:189], v[30:33]
	v_mfma_f32_16x16x32_bf16 v[22:25], v[162:165], v[194:197], v[22:25]
	v_mfma_f32_16x16x32_bf16 v[14:17], v[170:173], v[194:197], v[14:17]
	v_mfma_f32_16x16x32_bf16 v[6:9], v[162:165], v[202:205], v[6:9]
	v_mfma_f32_16x16x32_bf16 v[2:5], v[170:173], v[202:205], v[2:5]
	s_setprio 0
	s_barrier
	s_add_i32 s88, 0, 0x18000
	s_add_i32 s89, 0, 0x1c000
	v_add_u32_e32 v154, s88, v140
	v_add_u32_e32 v170, s89, v140
	ds_read_b128 v[142:145], v154
	ds_read_b128 v[146:149], v154 offset:1024
	ds_read_b128 v[150:153], v154 offset:2048
	ds_read_b128 v[154:157], v154 offset:3072
	ds_read_b128 v[158:161], v170
	ds_read_b128 v[162:165], v170 offset:1024
	ds_read_b128 v[166:169], v170 offset:2048
	ds_read_b128 v[170:173], v170 offset:3072
	s_add_u32 s78, s78, 0x80000
	s_addc_u32 s79, s79, 0
	s_mov_b32 m0, s61
	v_lshl_add_u64 v[218:219], s[78:79], 0, v[0:1]
	ds_read_b128 v[174:177], v141 offset:32768
	ds_read_b128 v[178:181], v141 offset:33792
	ds_read_b128 v[182:185], v141 offset:34816
	ds_read_b128 v[186:189], v141 offset:35840
	ds_read_b128 v[190:193], v141 offset:36864
	ds_read_b128 v[194:197], v141 offset:37888
	ds_read_b128 v[198:201], v141 offset:38912
	ds_read_b128 v[202:205], v141 offset:39936
	global_load_lds_dwordx4 v[218:219], off
	v_lshl_add_u64 v[218:219], s[78:79], 0, v[130:131]
	s_mov_b32 m0, s65
	s_nop 0
	global_load_lds_dwordx4 v[218:219], off
	s_waitcnt vmcnt(8)
	s_waitcnt lgkmcnt(0)
	s_barrier
	s_setprio 1
	s_waitcnt lgkmcnt(0)
	v_mfma_f32_16x16x32_bf16 v[126:129], v[142:145], v[174:177], v[126:129]
	v_mfma_f32_16x16x32_bf16 v[122:125], v[150:153], v[174:177], v[122:125]
	v_mfma_f32_16x16x32_bf16 v[110:113], v[142:145], v[182:185], v[110:113]
	v_mfma_f32_16x16x32_bf16 v[106:109], v[150:153], v[182:185], v[106:109]
	v_mfma_f32_16x16x32_bf16 v[98:101], v[142:145], v[190:193], v[98:101]
	v_mfma_f32_16x16x32_bf16 v[90:93], v[150:153], v[190:193], v[90:93]
	v_mfma_f32_16x16x32_bf16 v[82:85], v[142:145], v[198:201], v[82:85]
	v_mfma_f32_16x16x32_bf16 v[74:77], v[150:153], v[198:201], v[74:77]
	v_mfma_f32_16x16x32_bf16 v[126:129], v[146:149], v[178:181], v[126:129]
	v_mfma_f32_16x16x32_bf16 v[122:125], v[154:157], v[178:181], v[122:125]
	v_mfma_f32_16x16x32_bf16 v[110:113], v[146:149], v[186:189], v[110:113]
	v_mfma_f32_16x16x32_bf16 v[106:109], v[154:157], v[186:189], v[106:109]
	v_mfma_f32_16x16x32_bf16 v[98:101], v[146:149], v[194:197], v[98:101]
	v_mfma_f32_16x16x32_bf16 v[90:93], v[154:157], v[194:197], v[90:93]
	v_mfma_f32_16x16x32_bf16 v[82:85], v[146:149], v[202:205], v[82:85]
	v_mfma_f32_16x16x32_bf16 v[74:77], v[154:157], v[202:205], v[74:77]
	s_setprio 0
	s_setprio 1
	v_mfma_f32_16x16x32_bf16 v[118:121], v[158:161], v[174:177], v[118:121]
	v_mfma_f32_16x16x32_bf16 v[114:117], v[166:169], v[174:177], v[114:117]
	v_mfma_f32_16x16x32_bf16 v[102:105], v[158:161], v[182:185], v[102:105]
	v_mfma_f32_16x16x32_bf16 v[94:97], v[166:169], v[182:185], v[94:97]
	v_mfma_f32_16x16x32_bf16 v[86:89], v[158:161], v[190:193], v[86:89]
	v_mfma_f32_16x16x32_bf16 v[78:81], v[166:169], v[190:193], v[78:81]
	v_mfma_f32_16x16x32_bf16 v[70:73], v[158:161], v[198:201], v[70:73]
	v_mfma_f32_16x16x32_bf16 v[66:69], v[166:169], v[198:201], v[66:69]
	v_mfma_f32_16x16x32_bf16 v[118:121], v[162:165], v[178:181], v[118:121]
	v_mfma_f32_16x16x32_bf16 v[114:117], v[170:173], v[178:181], v[114:117]
	v_mfma_f32_16x16x32_bf16 v[102:105], v[162:165], v[186:189], v[102:105]
	v_mfma_f32_16x16x32_bf16 v[94:97], v[170:173], v[186:189], v[94:97]
	v_mfma_f32_16x16x32_bf16 v[86:89], v[162:165], v[194:197], v[86:89]
	v_mfma_f32_16x16x32_bf16 v[78:81], v[170:173], v[194:197], v[78:81]
	v_mfma_f32_16x16x32_bf16 v[70:73], v[162:165], v[202:205], v[70:73]
	v_mfma_f32_16x16x32_bf16 v[66:69], v[170:173], v[202:205], v[66:69]
	s_setprio 0
	s_barrier
	s_add_i32 s78, s88, s48
	v_lshl_add_u64 v[206:207], v[206:207], 0, s[54:55]
	s_mov_b32 m0, s78
	ds_read_b128 v[174:177], v141 offset:49152
	ds_read_b128 v[178:181], v141 offset:50176
	ds_read_b128 v[182:185], v141 offset:51200
	ds_read_b128 v[186:189], v141 offset:52224
	ds_read_b128 v[190:193], v141 offset:53248
	ds_read_b128 v[194:197], v141 offset:54272
	ds_read_b128 v[198:201], v141 offset:55296
	ds_read_b128 v[202:205], v141 offset:56320
	global_load_lds_dwordx4 v[206:207], off
	s_add_i32 m0, s78, 0x2000
	s_add_u32 s38, s38, 0x80080
	v_lshl_add_u64 v[206:207], v[208:209], 0, s[54:55]
	s_addc_u32 s39, s39, 0
	s_add_i32 s78, s89, s48
	global_load_lds_dwordx4 v[206:207], off
	v_lshl_add_u64 v[206:207], s[38:39], 0, v[0:1]
	s_mov_b32 m0, s78
	s_nop 0
	global_load_lds_dwordx4 v[206:207], off
	v_lshl_add_u64 v[206:207], s[38:39], 0, v[130:131]
	s_add_i32 m0, s78, 0x2000
	s_nop 0
	global_load_lds_dwordx4 v[206:207], off
	v_lshl_add_u64 v[206:207], v[214:215], 0, s[54:55]
	s_mov_b32 m0, s68
	s_nop 0
	global_load_lds_dwordx4 v[206:207], off
	v_lshl_add_u64 v[206:207], v[216:217], 0, s[54:55]
	s_mov_b32 m0, s69
	s_nop 0
	global_load_lds_dwordx4 v[206:207], off
	s_waitcnt vmcnt(8)
	s_waitcnt lgkmcnt(0)
	s_barrier
	s_setprio 1
	s_waitcnt lgkmcnt(0)
	v_mfma_f32_16x16x32_bf16 v[62:65], v[142:145], v[174:177], v[62:65]
	v_mfma_f32_16x16x32_bf16 v[58:61], v[150:153], v[174:177], v[58:61]
	v_mfma_f32_16x16x32_bf16 v[50:53], v[142:145], v[182:185], v[50:53]
	v_mfma_f32_16x16x32_bf16 v[42:45], v[150:153], v[182:185], v[42:45]
	v_mfma_f32_16x16x32_bf16 v[34:37], v[142:145], v[190:193], v[34:37]
	v_mfma_f32_16x16x32_bf16 v[26:29], v[150:153], v[190:193], v[26:29]
	v_mfma_f32_16x16x32_bf16 v[18:21], v[142:145], v[198:201], v[18:21]
	v_mfma_f32_16x16x32_bf16 v[10:13], v[150:153], v[198:201], v[10:13]
	v_mfma_f32_16x16x32_bf16 v[62:65], v[146:149], v[178:181], v[62:65]
	v_mfma_f32_16x16x32_bf16 v[58:61], v[154:157], v[178:181], v[58:61]
	v_mfma_f32_16x16x32_bf16 v[50:53], v[146:149], v[186:189], v[50:53]
	v_mfma_f32_16x16x32_bf16 v[42:45], v[154:157], v[186:189], v[42:45]
	v_mfma_f32_16x16x32_bf16 v[34:37], v[146:149], v[194:197], v[34:37]
	v_mfma_f32_16x16x32_bf16 v[26:29], v[154:157], v[194:197], v[26:29]
	v_mfma_f32_16x16x32_bf16 v[18:21], v[146:149], v[202:205], v[18:21]
	v_mfma_f32_16x16x32_bf16 v[10:13], v[154:157], v[202:205], v[10:13]
	s_setprio 0
	s_setprio 1
	v_mfma_f32_16x16x32_bf16 v[54:57], v[158:161], v[174:177], v[54:57]
	v_mfma_f32_16x16x32_bf16 v[46:49], v[166:169], v[174:177], v[46:49]
	v_mfma_f32_16x16x32_bf16 v[38:41], v[158:161], v[182:185], v[38:41]
	v_mfma_f32_16x16x32_bf16 v[30:33], v[166:169], v[182:185], v[30:33]
	v_mfma_f32_16x16x32_bf16 v[22:25], v[158:161], v[190:193], v[22:25]
	v_mfma_f32_16x16x32_bf16 v[14:17], v[166:169], v[190:193], v[14:17]
	v_mfma_f32_16x16x32_bf16 v[6:9], v[158:161], v[198:201], v[6:9]
	v_mfma_f32_16x16x32_bf16 v[2:5], v[166:169], v[198:201], v[2:5]
	v_mfma_f32_16x16x32_bf16 v[54:57], v[162:165], v[178:181], v[54:57]
	v_mfma_f32_16x16x32_bf16 v[46:49], v[170:173], v[178:181], v[46:49]
	v_mfma_f32_16x16x32_bf16 v[38:41], v[162:165], v[186:189], v[38:41]
	v_mfma_f32_16x16x32_bf16 v[30:33], v[170:173], v[186:189], v[30:33]
	v_mfma_f32_16x16x32_bf16 v[22:25], v[162:165], v[194:197], v[22:25]
	v_mfma_f32_16x16x32_bf16 v[14:17], v[170:173], v[194:197], v[14:17]
	v_mfma_f32_16x16x32_bf16 v[6:9], v[162:165], v[202:205], v[6:9]
	v_mfma_f32_16x16x32_bf16 v[2:5], v[170:173], v[202:205], v[2:5]
	s_setprio 0
	s_barrier
	s_add_i32 s87, s87, 2
	s_add_u32 s36, s36, 0x100
	s_addc_u32 s37, s37, 0
	s_cmp_gt_u32 s87, 29
	s_cbranch_scc1 .Lz0_exit_G2a

.Lz0_exit_G2a:
	s_add_u32 s36, s72, 0xffffff00
	s_addc_u32 s37, s73, -1
	s_andn2_b64 vcc, exec, s[6:7]
	s_cbranch_vccnz .LBB0_888
	v_mov_b32_e32 v2, 0
	s_mov_b32 s18, s26
	s_mov_b32 s20, s28
	s_mov_b64 s[24:25], s[34:35]
	s_mov_b32 s70, s71
	v_mov_b32_e32 v3, v2
	v_mov_b32_e32 v4, v2
	v_mov_b32_e32 v5, v2
	v_mov_b32_e32 v6, v2
	v_mov_b32_e32 v7, v2
	v_mov_b32_e32 v8, v2
	v_mov_b32_e32 v9, v2
	v_mov_b32_e32 v14, v2
	v_mov_b32_e32 v15, v2
	v_mov_b32_e32 v16, v2
	v_mov_b32_e32 v17, v2
	v_mov_b32_e32 v22, v2
	v_mov_b32_e32 v23, v2
	v_mov_b32_e32 v24, v2
	v_mov_b32_e32 v25, v2
	v_mov_b32_e32 v30, v2
	v_mov_b32_e32 v31, v2
	v_mov_b32_e32 v32, v2
	v_mov_b32_e32 v33, v2
	v_mov_b32_e32 v38, v2
	v_mov_b32_e32 v39, v2
	v_mov_b32_e32 v40, v2
	v_mov_b32_e32 v41, v2
	v_mov_b32_e32 v46, v2
	v_mov_b32_e32 v47, v2
	v_mov_b32_e32 v48, v2
	v_mov_b32_e32 v49, v2
	v_mov_b32_e32 v54, v2
	v_mov_b32_e32 v55, v2
	v_mov_b32_e32 v56, v2
	v_mov_b32_e32 v57, v2
	v_mov_b32_e32 v10, v2
	v_mov_b32_e32 v11, v2
	v_mov_b32_e32 v12, v2
	v_mov_b32_e32 v13, v2
	v_mov_b32_e32 v18, v2
	v_mov_b32_e32 v19, v2
	v_mov_b32_e32 v20, v2
	v_mov_b32_e32 v21, v2
	v_mov_b32_e32 v26, v2
	v_mov_b32_e32 v27, v2
	v_mov_b32_e32 v28, v2
	v_mov_b32_e32 v29, v2
	v_mov_b32_e32 v34, v2
	v_mov_b32_e32 v35, v2
	v_mov_b32_e32 v36, v2
	v_mov_b32_e32 v37, v2
	v_mov_b32_e32 v42, v2
	v_mov_b32_e32 v43, v2
	v_mov_b32_e32 v44, v2
	v_mov_b32_e32 v45, v2
	v_mov_b32_e32 v50, v2
	v_mov_b32_e32 v51, v2
	v_mov_b32_e32 v52, v2
	v_mov_b32_e32 v53, v2
	v_mov_b32_e32 v58, v2
	v_mov_b32_e32 v59, v2
	v_mov_b32_e32 v60, v2
	v_mov_b32_e32 v61, v2
	v_mov_b32_e32 v62, v2
	v_mov_b32_e32 v63, v2
	v_mov_b32_e32 v64, v2
	v_mov_b32_e32 v65, v2
	v_mov_b32_e32 v66, v2
	v_mov_b32_e32 v67, v2
	v_mov_b32_e32 v68, v2
	v_mov_b32_e32 v69, v2
	v_mov_b32_e32 v70, v2
	v_mov_b32_e32 v71, v2
	v_mov_b32_e32 v72, v2
	v_mov_b32_e32 v73, v2
	v_mov_b32_e32 v78, v2
	v_mov_b32_e32 v79, v2
	v_mov_b32_e32 v80, v2
	v_mov_b32_e32 v81, v2
	v_mov_b32_e32 v86, v2
	v_mov_b32_e32 v87, v2
	v_mov_b32_e32 v88, v2
	v_mov_b32_e32 v89, v2
	v_mov_b32_e32 v94, v2
	v_mov_b32_e32 v95, v2
	v_mov_b32_e32 v96, v2
	v_mov_b32_e32 v97, v2
	v_mov_b32_e32 v102, v2
	v_mov_b32_e32 v103, v2
	v_mov_b32_e32 v104, v2
	v_mov_b32_e32 v105, v2
	v_mov_b32_e32 v114, v2
	v_mov_b32_e32 v115, v2
	v_mov_b32_e32 v116, v2
	v_mov_b32_e32 v117, v2
	v_mov_b32_e32 v118, v2
	v_mov_b32_e32 v119, v2
	v_mov_b32_e32 v120, v2
	v_mov_b32_e32 v121, v2
	v_mov_b32_e32 v74, v2
	v_mov_b32_e32 v75, v2
	v_mov_b32_e32 v76, v2
	v_mov_b32_e32 v77, v2
	v_mov_b32_e32 v82, v2
	v_mov_b32_e32 v83, v2
	v_mov_b32_e32 v84, v2
	v_mov_b32_e32 v85, v2
	v_mov_b32_e32 v90, v2
	v_mov_b32_e32 v91, v2
	v_mov_b32_e32 v92, v2
	v_mov_b32_e32 v93, v2
	v_mov_b32_e32 v98, v2
	v_mov_b32_e32 v99, v2
	v_mov_b32_e32 v100, v2
	v_mov_b32_e32 v101, v2
	v_mov_b32_e32 v106, v2
	v_mov_b32_e32 v107, v2
	v_mov_b32_e32 v108, v2
	v_mov_b32_e32 v109, v2
	v_mov_b32_e32 v110, v2
	v_mov_b32_e32 v111, v2
	v_mov_b32_e32 v112, v2
	v_mov_b32_e32 v113, v2
	v_mov_b32_e32 v122, v2
	v_mov_b32_e32 v123, v2
	v_mov_b32_e32 v124, v2
	v_mov_b32_e32 v125, v2
	v_mov_b32_e32 v126, v2
	v_mov_b32_e32 v127, v2
	v_mov_b32_e32 v128, v2
	v_mov_b32_e32 v129, v2
	s_andn2_b64 vcc, exec, s[4:5]
	s_cbranch_vccnz .LBB0_889
	s_branch .LBB0_892

.LBB0_939:
	v_lshl_add_u64 v[8:9], s[38:39], 0, v[0:1]
	v_mov_b32_e32 v115, v1
	v_and_b32_e32 v221, 15, v220
	v_and_b32_e32 v16, 48, v220
	v_lshlrev_b32_e32 v17, 2, v220
	v_lshl_add_u64 v[10:11], s[38:39], 0, v[114:115]
	s_and_b32 s33, s17, 3
	s_lshl_b32 s4, s28, 13
	v_lshl_or_b32 v16, v221, 6, v16
	v_and_b32_e32 v17, 32, v17
	s_add_i32 m0, s19, 0x18000
	v_lshl_add_u64 v[8:9], v[8:9], 0, s[54:55]
	v_lshl_add_u64 v[12:13], s[26:27], 0, v[0:1]
	s_lshl_b32 s86, s28, 6
	v_bitop3_b32 v18, v16, s4, v17 bitop3:0xde
	s_lshl_b32 s4, s33, 12
	s_waitcnt vmcnt(2)
	s_barrier
	global_load_lds_dwordx4 v[8:9], off
	v_lshl_add_u64 v[8:9], v[10:11], 0, s[54:55]
	s_add_i32 m0, s19, 0x1a000
	s_add_i32 s68, s19, 0x8000
	s_add_i32 s69, s19, 0xa000
	v_lshl_add_u64 v[14:15], s[26:27], 0, v[114:115]
	v_bitop3_b32 v124, v16, s4, v17 bitop3:0xde
	global_load_lds_dwordx4 v[8:9], off
	v_lshl_add_u64 v[8:9], v[12:13], 0, s[54:55]
	s_mov_b32 m0, s68
	s_add_u32 s4, s38, 0x80080
	global_load_lds_dwordx4 v[8:9], off
	v_lshl_add_u64 v[8:9], v[14:15], 0, s[54:55]
	s_mov_b32 m0, s69
	s_addc_u32 s5, s39, 0
	global_load_lds_dwordx4 v[8:9], off
	s_add_i32 m0, s19, 0x1c000
	v_lshl_add_u64 v[8:9], s[4:5], 0, v[0:1]
	global_load_lds_dwordx4 v[8:9], off
	v_lshl_add_u64 v[8:9], s[4:5], 0, v[114:115]
	s_add_i32 m0, s19, 0x1e000
	s_sext_i32_i8 s16, s16
	global_load_lds_dwordx4 v[8:9], off
	v_lshlrev_b32_e32 v8, 15, v5
	v_and_b32_e32 v8, 0xffff0000, v8
	v_lshl_add_u32 v6, v6, 12, v8
	v_and_b32_e32 v5, 1, v5
	v_lshl_or_b32 v5, v5, 6, v6
	v_lshl_add_u32 v116, v7, 1, v5
	v_lshlrev_b32_e32 v5, 15, v2
	v_and_b32_e32 v5, 0xffff0000, v5
	v_lshl_add_u32 v3, v3, 12, v5
	v_and_b32_e32 v2, 1, v2
	s_waitcnt vmcnt(6)
	v_lshl_or_b32 v2, v2, 6, v3
	v_lshl_add_u32 v118, v4, 1, v2
	v_or_b32_e32 v151, s86, v221
	v_mov_b32_e32 v117, v1
	v_mov_b32_e32 v119, v1
	s_mov_b32 s70, 0
	v_add_u32_e32 v125, 0, v18
	s_barrier

.Lz0_G2b:
	s_add_u32 s78, s26, s38
	s_addc_u32 s79, s27, s39
	s_add_u32 s78, s78, 0x100
	s_addc_u32 s79, s79, 0
	s_add_u32 s92, s72, s38
	s_addc_u32 s93, s73, s39
	s_add_i32 s94, 0, 0x10000
	s_cmpk_eq_i32 s38, 0xf00
	s_cselect_b32 s81, s31, s79
	s_cselect_b32 s80, s87, s78
	v_add_u32_e32 v150, s94, v124
	s_cselect_b32 s79, s29, s93
	s_cselect_b32 s78, s88, s92
	s_add_i32 s92, 0, 0x14000
	ds_read_b128 v[126:129], v150
	ds_read_b128 v[146:149], v150 offset:1024
	ds_read_b128 v[152:155], v150 offset:2048
	ds_read_b128 v[156:159], v150 offset:3072
	v_add_u32_e32 v150, s92, v124
	ds_read_b128 v[160:163], v150
	ds_read_b128 v[164:167], v150 offset:1024
	ds_read_b128 v[168:171], v150 offset:2048
	ds_read_b128 v[172:175], v150 offset:3072
	v_lshl_add_u64 v[208:209], v[122:123], 0, s[38:39]
	s_add_i32 m0, s19, 0xc000
	ds_read_b128 v[176:179], v125
	ds_read_b128 v[180:183], v125 offset:1024
	ds_read_b128 v[184:187], v125 offset:2048
	ds_read_b128 v[188:191], v125 offset:3072
	ds_read_b128 v[192:195], v125 offset:4096
	ds_read_b128 v[196:199], v125 offset:5120
	ds_read_b128 v[200:203], v125 offset:6144
	ds_read_b128 v[204:207], v125 offset:7168
	global_load_lds_dwordx4 v[208:209], off
	v_lshl_add_u64 v[208:209], v[120:121], 0, s[38:39]
	s_add_i32 m0, s19, 0xe000
	s_nop 0
	global_load_lds_dwordx4 v[208:209], off
	s_waitcnt vmcnt(8)
	s_waitcnt lgkmcnt(0)
	s_barrier
	s_setprio 1
	s_waitcnt lgkmcnt(0)
	v_mfma_f32_16x16x32_bf16 v[142:145], v[126:129], v[176:179], 0
	v_mfma_f32_16x16x32_bf16 v[138:141], v[152:155], v[176:179], 0
	v_mfma_f32_16x16x32_bf16 v[110:113], v[126:129], v[184:187], 0
	v_mfma_f32_16x16x32_bf16 v[106:109], v[152:155], v[184:187], 0
	v_mfma_f32_16x16x32_bf16 v[94:97], v[126:129], v[192:195], 0
	v_mfma_f32_16x16x32_bf16 v[90:93], v[152:155], v[192:195], 0
	v_mfma_f32_16x16x32_bf16 v[78:81], v[126:129], v[200:203], 0
	v_mfma_f32_16x16x32_bf16 v[74:77], v[152:155], v[200:203], 0
	v_mfma_f32_16x16x32_bf16 v[142:145], v[146:149], v[180:183], v[142:145]
	v_mfma_f32_16x16x32_bf16 v[138:141], v[156:159], v[180:183], v[138:141]
	v_mfma_f32_16x16x32_bf16 v[110:113], v[146:149], v[188:191], v[110:113]
	v_mfma_f32_16x16x32_bf16 v[106:109], v[156:159], v[188:191], v[106:109]
	v_mfma_f32_16x16x32_bf16 v[94:97], v[146:149], v[196:199], v[94:97]
	v_mfma_f32_16x16x32_bf16 v[90:93], v[156:159], v[196:199], v[90:93]
	v_mfma_f32_16x16x32_bf16 v[78:81], v[146:149], v[204:207], v[78:81]
	v_mfma_f32_16x16x32_bf16 v[74:77], v[156:159], v[204:207], v[74:77]
	s_setprio 0
	s_setprio 1
	v_mfma_f32_16x16x32_bf16 v[134:137], v[160:163], v[176:179], 0
	v_mfma_f32_16x16x32_bf16 v[130:133], v[168:171], v[176:179], 0
	v_mfma_f32_16x16x32_bf16 v[102:105], v[160:163], v[184:187], 0
	v_mfma_f32_16x16x32_bf16 v[98:101], v[168:171], v[184:187], 0
	v_mfma_f32_16x16x32_bf16 v[86:89], v[160:163], v[192:195], 0
	v_mfma_f32_16x16x32_bf16 v[82:85], v[168:171], v[192:195], 0
	v_mfma_f32_16x16x32_bf16 v[70:73], v[160:163], v[200:203], 0
	v_mfma_f32_16x16x32_bf16 v[66:69], v[168:171], v[200:203], 0
	v_mfma_f32_16x16x32_bf16 v[134:137], v[164:167], v[180:183], v[134:137]
	v_mfma_f32_16x16x32_bf16 v[130:133], v[172:175], v[180:183], v[130:133]
	v_mfma_f32_16x16x32_bf16 v[102:105], v[164:167], v[188:191], v[102:105]
	v_mfma_f32_16x16x32_bf16 v[98:101], v[172:175], v[188:191], v[98:101]
	v_mfma_f32_16x16x32_bf16 v[86:89], v[164:167], v[196:199], v[86:89]
	v_mfma_f32_16x16x32_bf16 v[82:85], v[172:175], v[196:199], v[82:85]
	v_mfma_f32_16x16x32_bf16 v[70:73], v[164:167], v[204:207], v[70:73]
	v_mfma_f32_16x16x32_bf16 v[66:69], v[172:175], v[204:207], v[66:69]
	s_setprio 0
	s_barrier
	s_add_i32 s93, s94, s48
	v_lshl_add_u64 v[208:209], s[78:79], 0, v[0:1]
	s_mov_b32 m0, s93
	ds_read_b128 v[176:179], v125 offset:16384
	ds_read_b128 v[180:183], v125 offset:17408
	ds_read_b128 v[184:187], v125 offset:18432
	ds_read_b128 v[188:191], v125 offset:19456
	ds_read_b128 v[192:195], v125 offset:20480
	ds_read_b128 v[196:199], v125 offset:21504
	ds_read_b128 v[200:203], v125 offset:22528
	ds_read_b128 v[204:207], v125 offset:23552
	global_load_lds_dwordx4 v[208:209], off
	s_add_i32 m0, s93, 0x2000
	s_add_u32 s94, s78, 0x80000
	v_lshl_add_u64 v[210:211], s[78:79], 0, v[114:115]
	s_addc_u32 s95, s79, 0
	s_add_i32 s92, s92, s48
	global_load_lds_dwordx4 v[210:211], off
	v_lshl_add_u64 v[212:213], s[94:95], 0, v[0:1]
	s_mov_b32 m0, s92
	v_lshl_add_u64 v[214:215], s[80:81], 0, v[114:115]
	global_load_lds_dwordx4 v[212:213], off
	v_lshl_add_u64 v[212:213], s[94:95], 0, v[114:115]
	s_add_i32 m0, s92, 0x2000
	s_nop 0
	global_load_lds_dwordx4 v[212:213], off
	v_lshl_add_u64 v[212:213], s[80:81], 0, v[0:1]
	s_mov_b32 m0, s19
	s_nop 0
	global_load_lds_dwordx4 v[212:213], off
	s_mov_b32 m0, s49
	s_nop 0
	global_load_lds_dwordx4 v[214:215], off
	s_waitcnt vmcnt(8)
	s_waitcnt lgkmcnt(0)
	s_barrier
	s_setprio 1
	s_waitcnt lgkmcnt(0)
	v_mfma_f32_16x16x32_bf16 v[62:65], v[126:129], v[176:179], 0
	v_mfma_f32_16x16x32_bf16 v[58:61], v[152:155], v[176:179], 0
	v_mfma_f32_16x16x32_bf16 v[46:49], v[126:129], v[184:187], 0
	v_mfma_f32_16x16x32_bf16 v[42:45], v[152:155], v[184:187], 0
	v_mfma_f32_16x16x32_bf16 v[30:33], v[126:129], v[192:195], 0
	v_mfma_f32_16x16x32_bf16 v[26:29], v[152:155], v[192:195], 0
	v_mfma_f32_16x16x32_bf16 v[14:17], v[126:129], v[200:203], 0
	v_mfma_f32_16x16x32_bf16 v[10:13], v[152:155], v[200:203], 0
	v_mfma_f32_16x16x32_bf16 v[62:65], v[146:149], v[180:183], v[62:65]
	v_mfma_f32_16x16x32_bf16 v[58:61], v[156:159], v[180:183], v[58:61]
	v_mfma_f32_16x16x32_bf16 v[46:49], v[146:149], v[188:191], v[46:49]
	v_mfma_f32_16x16x32_bf16 v[42:45], v[156:159], v[188:191], v[42:45]
	v_mfma_f32_16x16x32_bf16 v[30:33], v[146:149], v[196:199], v[30:33]
	v_mfma_f32_16x16x32_bf16 v[26:29], v[156:159], v[196:199], v[26:29]
	v_mfma_f32_16x16x32_bf16 v[14:17], v[146:149], v[204:207], v[14:17]
	v_mfma_f32_16x16x32_bf16 v[10:13], v[156:159], v[204:207], v[10:13]
	s_setprio 0
	s_setprio 1
	v_mfma_f32_16x16x32_bf16 v[54:57], v[160:163], v[176:179], 0
	v_mfma_f32_16x16x32_bf16 v[50:53], v[168:171], v[176:179], 0
	v_mfma_f32_16x16x32_bf16 v[38:41], v[160:163], v[184:187], 0
	v_mfma_f32_16x16x32_bf16 v[34:37], v[168:171], v[184:187], 0
	v_mfma_f32_16x16x32_bf16 v[22:25], v[160:163], v[192:195], 0
	v_mfma_f32_16x16x32_bf16 v[18:21], v[168:171], v[192:195], 0
	v_mfma_f32_16x16x32_bf16 v[6:9], v[160:163], v[200:203], 0
	v_mfma_f32_16x16x32_bf16 v[2:5], v[168:171], v[200:203], 0
	v_mfma_f32_16x16x32_bf16 v[54:57], v[164:167], v[180:183], v[54:57]
	v_mfma_f32_16x16x32_bf16 v[50:53], v[172:175], v[180:183], v[50:53]
	v_mfma_f32_16x16x32_bf16 v[38:41], v[164:167], v[188:191], v[38:41]
	v_mfma_f32_16x16x32_bf16 v[34:37], v[172:175], v[188:191], v[34:37]
	v_mfma_f32_16x16x32_bf16 v[22:25], v[164:167], v[196:199], v[22:25]
	v_mfma_f32_16x16x32_bf16 v[18:21], v[172:175], v[196:199], v[18:21]
	v_mfma_f32_16x16x32_bf16 v[6:9], v[164:167], v[204:207], v[6:9]
	v_mfma_f32_16x16x32_bf16 v[2:5], v[172:175], v[204:207], v[2:5]
	s_setprio 0
	s_barrier
	s_add_i32 s92, 0, 0x18000
	v_add_u32_e32 v150, s92, v124
	s_add_i32 s93, 0, 0x1c000
	ds_read_b128 v[126:129], v150
	ds_read_b128 v[146:149], v150 offset:1024
	ds_read_b128 v[152:155], v150 offset:2048
	ds_read_b128 v[156:159], v150 offset:3072
	v_add_u32_e32 v150, s93, v124
	ds_read_b128 v[160:163], v150
	ds_read_b128 v[164:167], v150 offset:1024
	ds_read_b128 v[168:171], v150 offset:2048
	ds_read_b128 v[172:175], v150 offset:3072
	s_add_u32 s80, s80, 0x80000
	s_addc_u32 s81, s81, 0
	s_mov_b32 m0, s61
	v_lshl_add_u64 v[216:217], s[80:81], 0, v[0:1]
	ds_read_b128 v[176:179], v125 offset:32768
	ds_read_b128 v[180:183], v125 offset:33792
	ds_read_b128 v[184:187], v125 offset:34816
	ds_read_b128 v[188:191], v125 offset:35840
	ds_read_b128 v[192:195], v125 offset:36864
	ds_read_b128 v[196:199], v125 offset:37888
	ds_read_b128 v[200:203], v125 offset:38912
	ds_read_b128 v[204:207], v125 offset:39936
	global_load_lds_dwordx4 v[216:217], off
	v_lshl_add_u64 v[216:217], s[80:81], 0, v[114:115]
	s_mov_b32 m0, s65
	s_nop 0
	global_load_lds_dwordx4 v[216:217], off
	s_waitcnt vmcnt(8)
	s_waitcnt lgkmcnt(0)
	s_barrier
	s_setprio 1
	s_waitcnt lgkmcnt(0)
	v_mfma_f32_16x16x32_bf16 v[142:145], v[126:129], v[176:179], v[142:145]
	v_mfma_f32_16x16x32_bf16 v[138:141], v[152:155], v[176:179], v[138:141]
	v_mfma_f32_16x16x32_bf16 v[110:113], v[126:129], v[184:187], v[110:113]
	v_mfma_f32_16x16x32_bf16 v[106:109], v[152:155], v[184:187], v[106:109]
	v_mfma_f32_16x16x32_bf16 v[94:97], v[126:129], v[192:195], v[94:97]
	v_mfma_f32_16x16x32_bf16 v[90:93], v[152:155], v[192:195], v[90:93]
	v_mfma_f32_16x16x32_bf16 v[78:81], v[126:129], v[200:203], v[78:81]
	v_mfma_f32_16x16x32_bf16 v[74:77], v[152:155], v[200:203], v[74:77]
	v_mfma_f32_16x16x32_bf16 v[142:145], v[146:149], v[180:183], v[142:145]
	v_mfma_f32_16x16x32_bf16 v[138:141], v[156:159], v[180:183], v[138:141]
	v_mfma_f32_16x16x32_bf16 v[110:113], v[146:149], v[188:191], v[110:113]
	v_mfma_f32_16x16x32_bf16 v[106:109], v[156:159], v[188:191], v[106:109]
	v_mfma_f32_16x16x32_bf16 v[94:97], v[146:149], v[196:199], v[94:97]
	v_mfma_f32_16x16x32_bf16 v[90:93], v[156:159], v[196:199], v[90:93]
	v_mfma_f32_16x16x32_bf16 v[78:81], v[146:149], v[204:207], v[78:81]
	v_mfma_f32_16x16x32_bf16 v[74:77], v[156:159], v[204:207], v[74:77]
	s_setprio 0
	s_setprio 1
	v_mfma_f32_16x16x32_bf16 v[134:137], v[160:163], v[176:179], v[134:137]
	v_mfma_f32_16x16x32_bf16 v[130:133], v[168:171], v[176:179], v[130:133]
	v_mfma_f32_16x16x32_bf16 v[102:105], v[160:163], v[184:187], v[102:105]
	v_mfma_f32_16x16x32_bf16 v[98:101], v[168:171], v[184:187], v[98:101]
	v_mfma_f32_16x16x32_bf16 v[86:89], v[160:163], v[192:195], v[86:89]
	v_mfma_f32_16x16x32_bf16 v[82:85], v[168:171], v[192:195], v[82:85]
	v_mfma_f32_16x16x32_bf16 v[70:73], v[160:163], v[200:203], v[70:73]
	v_mfma_f32_16x16x32_bf16 v[66:69], v[168:171], v[200:203], v[66:69]
	v_mfma_f32_16x16x32_bf16 v[134:137], v[164:167], v[180:183], v[134:137]
	v_mfma_f32_16x16x32_bf16 v[130:133], v[172:175], v[180:183], v[130:133]
	v_mfma_f32_16x16x32_bf16 v[102:105], v[164:167], v[188:191], v[102:105]
	v_mfma_f32_16x16x32_bf16 v[98:101], v[172:175], v[188:191], v[98:101]
	v_mfma_f32_16x16x32_bf16 v[86:89], v[164:167], v[196:199], v[86:89]
	v_mfma_f32_16x16x32_bf16 v[82:85], v[172:175], v[196:199], v[82:85]
	v_mfma_f32_16x16x32_bf16 v[70:73], v[164:167], v[204:207], v[70:73]
	v_mfma_f32_16x16x32_bf16 v[66:69], v[172:175], v[204:207], v[66:69]
	s_setprio 0
	s_barrier
	s_add_i32 s80, s92, s48
	v_lshl_add_u64 v[208:209], v[208:209], 0, s[54:55]
	s_mov_b32 m0, s80
	ds_read_b128 v[176:179], v125 offset:49152
	ds_read_b128 v[180:183], v125 offset:50176
	ds_read_b128 v[184:187], v125 offset:51200
	ds_read_b128 v[188:191], v125 offset:52224
	ds_read_b128 v[192:195], v125 offset:53248
	ds_read_b128 v[196:199], v125 offset:54272
	ds_read_b128 v[200:203], v125 offset:55296
	ds_read_b128 v[204:207], v125 offset:56320
	global_load_lds_dwordx4 v[208:209], off
	s_add_i32 m0, s80, 0x2000
	s_add_u32 s78, s78, 0x80080
	v_lshl_add_u64 v[208:209], v[210:211], 0, s[54:55]
	s_addc_u32 s79, s79, 0
	s_add_i32 s80, s93, s48
	global_load_lds_dwordx4 v[208:209], off
	v_lshl_add_u64 v[208:209], s[78:79], 0, v[0:1]
	s_mov_b32 m0, s80
	s_nop 0
	global_load_lds_dwordx4 v[208:209], off
	v_lshl_add_u64 v[208:209], s[78:79], 0, v[114:115]
	s_add_i32 m0, s80, 0x2000
	s_nop 0
	global_load_lds_dwordx4 v[208:209], off
	v_lshl_add_u64 v[208:209], v[212:213], 0, s[54:55]
	s_mov_b32 m0, s68
	s_nop 0
	global_load_lds_dwordx4 v[208:209], off
	v_lshl_add_u64 v[208:209], v[214:215], 0, s[54:55]
	s_mov_b32 m0, s69
	s_nop 0
	global_load_lds_dwordx4 v[208:209], off
	s_waitcnt vmcnt(8)
	s_waitcnt lgkmcnt(0)
	s_barrier
	s_setprio 1
	s_waitcnt lgkmcnt(0)
	v_mfma_f32_16x16x32_bf16 v[62:65], v[126:129], v[176:179], v[62:65]
	v_mfma_f32_16x16x32_bf16 v[58:61], v[152:155], v[176:179], v[58:61]
	v_mfma_f32_16x16x32_bf16 v[46:49], v[126:129], v[184:187], v[46:49]
	v_mfma_f32_16x16x32_bf16 v[42:45], v[152:155], v[184:187], v[42:45]
	v_mfma_f32_16x16x32_bf16 v[30:33], v[126:129], v[192:195], v[30:33]
	v_mfma_f32_16x16x32_bf16 v[26:29], v[152:155], v[192:195], v[26:29]
	v_mfma_f32_16x16x32_bf16 v[14:17], v[126:129], v[200:203], v[14:17]
	v_mfma_f32_16x16x32_bf16 v[10:13], v[152:155], v[200:203], v[10:13]
	v_mfma_f32_16x16x32_bf16 v[62:65], v[146:149], v[180:183], v[62:65]
	v_mfma_f32_16x16x32_bf16 v[58:61], v[156:159], v[180:183], v[58:61]
	v_mfma_f32_16x16x32_bf16 v[46:49], v[146:149], v[188:191], v[46:49]
	v_mfma_f32_16x16x32_bf16 v[42:45], v[156:159], v[188:191], v[42:45]
	v_mfma_f32_16x16x32_bf16 v[30:33], v[146:149], v[196:199], v[30:33]
	v_mfma_f32_16x16x32_bf16 v[26:29], v[156:159], v[196:199], v[26:29]
	v_mfma_f32_16x16x32_bf16 v[14:17], v[146:149], v[204:207], v[14:17]
	v_mfma_f32_16x16x32_bf16 v[10:13], v[156:159], v[204:207], v[10:13]
	s_setprio 0
	s_setprio 1
	v_mfma_f32_16x16x32_bf16 v[54:57], v[160:163], v[176:179], v[54:57]
	v_mfma_f32_16x16x32_bf16 v[50:53], v[168:171], v[176:179], v[50:53]
	v_mfma_f32_16x16x32_bf16 v[38:41], v[160:163], v[184:187], v[38:41]
	v_mfma_f32_16x16x32_bf16 v[34:37], v[168:171], v[184:187], v[34:37]
	v_mfma_f32_16x16x32_bf16 v[22:25], v[160:163], v[192:195], v[22:25]
	v_mfma_f32_16x16x32_bf16 v[18:21], v[168:171], v[192:195], v[18:21]
	v_mfma_f32_16x16x32_bf16 v[6:9], v[160:163], v[200:203], v[6:9]
	v_mfma_f32_16x16x32_bf16 v[2:5], v[168:171], v[200:203], v[2:5]
	v_mfma_f32_16x16x32_bf16 v[54:57], v[164:167], v[180:183], v[54:57]
	v_mfma_f32_16x16x32_bf16 v[50:53], v[172:175], v[180:183], v[50:53]
	v_mfma_f32_16x16x32_bf16 v[38:41], v[164:167], v[188:191], v[38:41]
	v_mfma_f32_16x16x32_bf16 v[34:37], v[172:175], v[188:191], v[34:37]
	v_mfma_f32_16x16x32_bf16 v[22:25], v[164:167], v[196:199], v[22:25]
	v_mfma_f32_16x16x32_bf16 v[18:21], v[172:175], v[196:199], v[18:21]
	v_mfma_f32_16x16x32_bf16 v[6:9], v[164:167], v[204:207], v[6:9]
	v_mfma_f32_16x16x32_bf16 v[2:5], v[172:175], v[204:207], v[2:5]
	s_setprio 0
	s_barrier
	s_add_i32 s89, s89, 2
	s_add_u32 s38, s38, 0x100
	s_addc_u32 s39, s39, 0
	s_cmp_gt_u32 s89, 29
	s_cbranch_scc1 .Lz0_exit_G2b

.Lz0_exit_G2b:
	s_add_u32 s38, s72, 0xffffff00
	s_addc_u32 s39, s73, -1
	s_andn2_b64 vcc, exec, s[6:7]
	s_cbranch_vccnz .LBB0_950
	v_mov_b32_e32 v2, 0
	s_mov_b32 s16, s28
	s_mov_b32 s18, s30
	s_mov_b64 s[26:27], s[36:37]
	s_mov_b32 s70, s71
	v_mov_b32_e32 v3, v2
	v_mov_b32_e32 v4, v2
	v_mov_b32_e32 v5, v2
	v_mov_b32_e32 v6, v2
	v_mov_b32_e32 v7, v2
	v_mov_b32_e32 v8, v2
	v_mov_b32_e32 v9, v2
	v_mov_b32_e32 v18, v2
	v_mov_b32_e32 v19, v2
	v_mov_b32_e32 v20, v2
	v_mov_b32_e32 v21, v2
	v_mov_b32_e32 v22, v2
	v_mov_b32_e32 v23, v2
	v_mov_b32_e32 v24, v2
	v_mov_b32_e32 v25, v2
	v_mov_b32_e32 v34, v2
	v_mov_b32_e32 v35, v2
	v_mov_b32_e32 v36, v2
	v_mov_b32_e32 v37, v2
	v_mov_b32_e32 v38, v2
	v_mov_b32_e32 v39, v2
	v_mov_b32_e32 v40, v2
	v_mov_b32_e32 v41, v2
	v_mov_b32_e32 v50, v2
	v_mov_b32_e32 v51, v2
	v_mov_b32_e32 v52, v2
	v_mov_b32_e32 v53, v2
	v_mov_b32_e32 v54, v2
	v_mov_b32_e32 v55, v2
	v_mov_b32_e32 v56, v2
	v_mov_b32_e32 v57, v2
	v_mov_b32_e32 v10, v2
	v_mov_b32_e32 v11, v2
	v_mov_b32_e32 v12, v2
	v_mov_b32_e32 v13, v2
	v_mov_b32_e32 v14, v2
	v_mov_b32_e32 v15, v2
	v_mov_b32_e32 v16, v2
	v_mov_b32_e32 v17, v2
	v_mov_b32_e32 v26, v2
	v_mov_b32_e32 v27, v2
	v_mov_b32_e32 v28, v2
	v_mov_b32_e32 v29, v2
	v_mov_b32_e32 v30, v2
	v_mov_b32_e32 v31, v2
	v_mov_b32_e32 v32, v2
	v_mov_b32_e32 v33, v2
	v_mov_b32_e32 v42, v2
	v_mov_b32_e32 v43, v2
	v_mov_b32_e32 v44, v2
	v_mov_b32_e32 v45, v2
	v_mov_b32_e32 v46, v2
	v_mov_b32_e32 v47, v2
	v_mov_b32_e32 v48, v2
	v_mov_b32_e32 v49, v2
	v_mov_b32_e32 v58, v2
	v_mov_b32_e32 v59, v2
	v_mov_b32_e32 v60, v2
	v_mov_b32_e32 v61, v2
	v_mov_b32_e32 v62, v2
	v_mov_b32_e32 v63, v2
	v_mov_b32_e32 v64, v2
	v_mov_b32_e32 v65, v2
	v_mov_b32_e32 v66, v2
	v_mov_b32_e32 v67, v2
	v_mov_b32_e32 v68, v2
	v_mov_b32_e32 v69, v2
	v_mov_b32_e32 v70, v2
	v_mov_b32_e32 v71, v2
	v_mov_b32_e32 v72, v2
	v_mov_b32_e32 v73, v2
	v_mov_b32_e32 v82, v2
	v_mov_b32_e32 v83, v2
	v_mov_b32_e32 v84, v2
	v_mov_b32_e32 v85, v2
	v_mov_b32_e32 v86, v2
	v_mov_b32_e32 v87, v2
	v_mov_b32_e32 v88, v2
	v_mov_b32_e32 v89, v2
	v_mov_b32_e32 v98, v2
	v_mov_b32_e32 v99, v2
	v_mov_b32_e32 v100, v2
	v_mov_b32_e32 v101, v2
	v_mov_b32_e32 v102, v2
	v_mov_b32_e32 v103, v2
	v_mov_b32_e32 v104, v2
	v_mov_b32_e32 v105, v2
	v_mov_b32_e32 v130, v2
	v_mov_b32_e32 v131, v2
	v_mov_b32_e32 v132, v2
	v_mov_b32_e32 v133, v2
	v_mov_b32_e32 v134, v2
	v_mov_b32_e32 v135, v2
	v_mov_b32_e32 v136, v2
	v_mov_b32_e32 v137, v2
	v_mov_b32_e32 v74, v2
	v_mov_b32_e32 v75, v2
	v_mov_b32_e32 v76, v2
	v_mov_b32_e32 v77, v2
	v_mov_b32_e32 v78, v2
	v_mov_b32_e32 v79, v2
	v_mov_b32_e32 v80, v2
	v_mov_b32_e32 v81, v2
	v_mov_b32_e32 v90, v2
	v_mov_b32_e32 v91, v2
	v_mov_b32_e32 v92, v2
	v_mov_b32_e32 v93, v2
	v_mov_b32_e32 v94, v2
	v_mov_b32_e32 v95, v2
	v_mov_b32_e32 v96, v2
	v_mov_b32_e32 v97, v2
	v_mov_b32_e32 v106, v2
	v_mov_b32_e32 v107, v2
	v_mov_b32_e32 v108, v2
	v_mov_b32_e32 v109, v2
	v_mov_b32_e32 v110, v2
	v_mov_b32_e32 v111, v2
	v_mov_b32_e32 v112, v2
	v_mov_b32_e32 v113, v2
	v_mov_b32_e32 v138, v2
	v_mov_b32_e32 v139, v2
	v_mov_b32_e32 v140, v2
	v_mov_b32_e32 v141, v2
	v_mov_b32_e32 v142, v2
	v_mov_b32_e32 v143, v2
	v_mov_b32_e32 v144, v2
	v_mov_b32_e32 v145, v2
	s_andn2_b64 vcc, exec, s[4:5]
	s_cbranch_vccnz .LBB0_951
	s_branch .LBB0_952

.LBB0_1059:
	s_ashr_i32 s19, s18, 31
	s_lshl_b64 s[20:21], s[18:19], 20
	s_add_u32 s20, s67, s20
	s_addc_u32 s21, s78, s21
	s_and_b64 s[22:23], s[4:5], exec
	s_cselect_b32 s19, s21, s29
	s_cselect_b32 s33, s20, s28
	s_ashr_i32 s17, s16, 31
	s_lshl_b64 s[22:23], s[16:17], 20
	s_add_u32 s22, s79, s22
	s_addc_u32 s23, s80, s23
	s_and_b64 s[30:31], s[4:5], exec
	s_cselect_b32 s17, s23, s27
	s_cselect_b32 s44, s22, s26
	s_add_u32 s45, s26, 0x100
	s_addc_u32 s48, s27, 0
	s_add_u32 s26, s28, 0x80080
	s_addc_u32 s27, s29, 0
	s_mov_b32 s49, -2
.Lpeel_G3:
	s_add_u32 s28, s26, 0xfff80080
	s_addc_u32 s29, s27, -1
	s_add_i32 s61, 0, 0x10000
	s_cmp_eq_u32 s49, 28
	s_cselect_b32 s31, s19, s29
	s_cselect_b32 s30, s33, s28
	v_add_u32_e32 v141, s61, v138
	s_cselect_b32 s29, s17, s48
	s_cselect_b32 s28, s44, s45
	s_add_i32 s73, 0, 0x14000
	ds_read_b128 v[142:145], v141
	ds_read_b128 v[146:149], v141 offset:1024
	ds_read_b128 v[150:153], v141 offset:2048
	ds_read_b128 v[154:157], v141 offset:3072
	v_add_u32_e32 v141, s73, v138
	ds_read_b128 v[158:161], v141
	ds_read_b128 v[162:165], v141 offset:1024
	ds_read_b128 v[166:169], v141 offset:2048
	ds_read_b128 v[170:173], v141 offset:3072
	v_lshl_add_u64 v[206:207], s[26:27], 0, v[134:135]
	s_add_i32 m0, s82, 0xc000
	ds_read_b128 v[174:177], v140
	ds_read_b128 v[178:181], v140 offset:1024
	ds_read_b128 v[182:185], v140 offset:2048
	ds_read_b128 v[186:189], v140 offset:3072
	ds_read_b128 v[190:193], v140 offset:4096
	ds_read_b128 v[194:197], v140 offset:5120
	ds_read_b128 v[198:201], v140 offset:6144
	ds_read_b128 v[202:205], v140 offset:7168
	global_load_lds_dwordx4 v[206:207], off
	v_lshl_add_u64 v[206:207], s[26:27], 0, v[132:133]
	s_add_i32 m0, s82, 0xe000
	s_nop 0
	global_load_lds_dwordx4 v[206:207], off
	s_waitcnt vmcnt(8)
	s_waitcnt lgkmcnt(0)
	s_barrier
	s_setprio 1
	s_waitcnt lgkmcnt(0)
	v_mfma_f32_16x16x32_bf16 v[126:129], v[142:145], v[174:177], 0
	v_mfma_f32_16x16x32_bf16 v[118:121], v[150:153], v[174:177], 0
	v_mfma_f32_16x16x32_bf16 v[110:113], v[142:145], v[182:185], 0
	v_mfma_f32_16x16x32_bf16 v[102:105], v[150:153], v[182:185], 0
	v_mfma_f32_16x16x32_bf16 v[94:97], v[142:145], v[190:193], 0
	v_mfma_f32_16x16x32_bf16 v[86:89], v[150:153], v[190:193], 0
	v_mfma_f32_16x16x32_bf16 v[78:81], v[142:145], v[198:201], 0
	v_mfma_f32_16x16x32_bf16 v[70:73], v[150:153], v[198:201], 0
	v_mfma_f32_16x16x32_bf16 v[126:129], v[146:149], v[178:181], v[126:129]
	v_mfma_f32_16x16x32_bf16 v[118:121], v[154:157], v[178:181], v[118:121]
	v_mfma_f32_16x16x32_bf16 v[110:113], v[146:149], v[186:189], v[110:113]
	v_mfma_f32_16x16x32_bf16 v[102:105], v[154:157], v[186:189], v[102:105]
	v_mfma_f32_16x16x32_bf16 v[94:97], v[146:149], v[194:197], v[94:97]
	v_mfma_f32_16x16x32_bf16 v[86:89], v[154:157], v[194:197], v[86:89]
	v_mfma_f32_16x16x32_bf16 v[78:81], v[146:149], v[202:205], v[78:81]
	v_mfma_f32_16x16x32_bf16 v[70:73], v[154:157], v[202:205], v[70:73]
	s_setprio 0
	s_setprio 1
	v_mfma_f32_16x16x32_bf16 v[122:125], v[158:161], v[174:177], 0
	v_mfma_f32_16x16x32_bf16 v[114:117], v[166:169], v[174:177], 0
	v_mfma_f32_16x16x32_bf16 v[106:109], v[158:161], v[182:185], 0
	v_mfma_f32_16x16x32_bf16 v[98:101], v[166:169], v[182:185], 0
	v_mfma_f32_16x16x32_bf16 v[90:93], v[158:161], v[190:193], 0
	v_mfma_f32_16x16x32_bf16 v[82:85], v[166:169], v[190:193], 0
	v_mfma_f32_16x16x32_bf16 v[74:77], v[158:161], v[198:201], 0
	v_mfma_f32_16x16x32_bf16 v[66:69], v[166:169], v[198:201], 0
	v_mfma_f32_16x16x32_bf16 v[122:125], v[162:165], v[178:181], v[122:125]
	v_mfma_f32_16x16x32_bf16 v[114:117], v[170:173], v[178:181], v[114:117]
	v_mfma_f32_16x16x32_bf16 v[106:109], v[162:165], v[186:189], v[106:109]
	v_mfma_f32_16x16x32_bf16 v[98:101], v[170:173], v[186:189], v[98:101]
	v_mfma_f32_16x16x32_bf16 v[90:93], v[162:165], v[194:197], v[90:93]
	v_mfma_f32_16x16x32_bf16 v[82:85], v[170:173], v[194:197], v[82:85]
	v_mfma_f32_16x16x32_bf16 v[74:77], v[162:165], v[202:205], v[74:77]
	v_mfma_f32_16x16x32_bf16 v[66:69], v[170:173], v[202:205], v[66:69]
	s_setprio 0
	s_barrier
	s_add_i32 s61, s61, s81
	v_lshl_add_u64 v[206:207], s[28:29], 0, v[0:1]
	s_mov_b32 m0, s61
	ds_read_b128 v[174:177], v140 offset:16384
	ds_read_b128 v[178:181], v140 offset:17408
	ds_read_b128 v[182:185], v140 offset:18432
	ds_read_b128 v[186:189], v140 offset:19456
	ds_read_b128 v[190:193], v140 offset:20480
	ds_read_b128 v[194:197], v140 offset:21504
	ds_read_b128 v[198:201], v140 offset:22528
	ds_read_b128 v[202:205], v140 offset:23552
	global_load_lds_dwordx4 v[206:207], off
	s_add_i32 m0, s61, 0x2000
	s_add_u32 s84, s28, 0x80000
	v_lshl_add_u64 v[208:209], s[28:29], 0, v[130:131]
	s_addc_u32 s85, s29, 0
	s_add_i32 s61, s73, s81
	global_load_lds_dwordx4 v[208:209], off
	v_lshl_add_u64 v[210:211], s[84:85], 0, v[0:1]
	s_mov_b32 m0, s61
	v_lshl_add_u64 v[212:213], s[30:31], 0, v[130:131]
	global_load_lds_dwordx4 v[210:211], off
	v_lshl_add_u64 v[210:211], s[84:85], 0, v[130:131]
	s_add_i32 m0, s61, 0x2000
	s_nop 0
	global_load_lds_dwordx4 v[210:211], off
	v_lshl_add_u64 v[210:211], s[30:31], 0, v[0:1]
	s_mov_b32 m0, s82
	s_nop 0
	global_load_lds_dwordx4 v[210:211], off
	s_mov_b32 m0, s68
	s_nop 0
	global_load_lds_dwordx4 v[212:213], off
	s_waitcnt vmcnt(8)
	s_waitcnt lgkmcnt(0)
	s_barrier
	s_setprio 1
	s_waitcnt lgkmcnt(0)
	v_mfma_f32_16x16x32_bf16 v[62:65], v[142:145], v[174:177], 0
	v_mfma_f32_16x16x32_bf16 v[54:57], v[150:153], v[174:177], 0
	v_mfma_f32_16x16x32_bf16 v[46:49], v[142:145], v[182:185], 0
	v_mfma_f32_16x16x32_bf16 v[38:41], v[150:153], v[182:185], 0
	v_mfma_f32_16x16x32_bf16 v[30:33], v[142:145], v[190:193], 0
	v_mfma_f32_16x16x32_bf16 v[22:25], v[150:153], v[190:193], 0
	v_mfma_f32_16x16x32_bf16 v[14:17], v[142:145], v[198:201], 0
	v_mfma_f32_16x16x32_bf16 v[6:9], v[150:153], v[198:201], 0
	v_mfma_f32_16x16x32_bf16 v[62:65], v[146:149], v[178:181], v[62:65]
	v_mfma_f32_16x16x32_bf16 v[54:57], v[154:157], v[178:181], v[54:57]
	v_mfma_f32_16x16x32_bf16 v[46:49], v[146:149], v[186:189], v[46:49]
	v_mfma_f32_16x16x32_bf16 v[38:41], v[154:157], v[186:189], v[38:41]
	v_mfma_f32_16x16x32_bf16 v[30:33], v[146:149], v[194:197], v[30:33]
	v_mfma_f32_16x16x32_bf16 v[22:25], v[154:157], v[194:197], v[22:25]
	v_mfma_f32_16x16x32_bf16 v[14:17], v[146:149], v[202:205], v[14:17]
	v_mfma_f32_16x16x32_bf16 v[6:9], v[154:157], v[202:205], v[6:9]
	s_setprio 0
	s_setprio 1
	v_mfma_f32_16x16x32_bf16 v[58:61], v[158:161], v[174:177], 0
	v_mfma_f32_16x16x32_bf16 v[50:53], v[166:169], v[174:177], 0
	v_mfma_f32_16x16x32_bf16 v[42:45], v[158:161], v[182:185], 0
	v_mfma_f32_16x16x32_bf16 v[34:37], v[166:169], v[182:185], 0
	v_mfma_f32_16x16x32_bf16 v[26:29], v[158:161], v[190:193], 0
	v_mfma_f32_16x16x32_bf16 v[18:21], v[166:169], v[190:193], 0
	v_mfma_f32_16x16x32_bf16 v[10:13], v[158:161], v[198:201], 0
	v_mfma_f32_16x16x32_bf16 v[2:5], v[166:169], v[198:201], 0
	v_mfma_f32_16x16x32_bf16 v[58:61], v[162:165], v[178:181], v[58:61]
	v_mfma_f32_16x16x32_bf16 v[50:53], v[170:173], v[178:181], v[50:53]
	v_mfma_f32_16x16x32_bf16 v[42:45], v[162:165], v[186:189], v[42:45]
	v_mfma_f32_16x16x32_bf16 v[34:37], v[170:173], v[186:189], v[34:37]
	v_mfma_f32_16x16x32_bf16 v[26:29], v[162:165], v[194:197], v[26:29]
	v_mfma_f32_16x16x32_bf16 v[18:21], v[170:173], v[194:197], v[18:21]
	v_mfma_f32_16x16x32_bf16 v[10:13], v[162:165], v[202:205], v[10:13]
	v_mfma_f32_16x16x32_bf16 v[2:5], v[170:173], v[202:205], v[2:5]
	s_setprio 0
	s_barrier
	s_add_i32 s61, 0, 0x18000
	v_add_u32_e32 v141, s61, v138
	s_add_i32 s73, 0, 0x1c000
	ds_read_b128 v[142:145], v141
	ds_read_b128 v[146:149], v141 offset:1024
	ds_read_b128 v[150:153], v141 offset:2048
	ds_read_b128 v[154:157], v141 offset:3072
	v_add_u32_e32 v141, s73, v138
	ds_read_b128 v[158:161], v141
	ds_read_b128 v[162:165], v141 offset:1024
	ds_read_b128 v[166:169], v141 offset:2048
	ds_read_b128 v[170:173], v141 offset:3072
	s_add_u32 s30, s30, 0x80000
	s_addc_u32 s31, s31, 0
	s_mov_b32 m0, s69
	v_lshl_add_u64 v[214:215], s[30:31], 0, v[0:1]
	ds_read_b128 v[174:177], v140 offset:32768
	ds_read_b128 v[178:181], v140 offset:33792
	ds_read_b128 v[182:185], v140 offset:34816
	ds_read_b128 v[186:189], v140 offset:35840
	ds_read_b128 v[190:193], v140 offset:36864
	ds_read_b128 v[194:197], v140 offset:37888
	ds_read_b128 v[198:201], v140 offset:38912
	ds_read_b128 v[202:205], v140 offset:39936
	global_load_lds_dwordx4 v[214:215], off
	v_lshl_add_u64 v[214:215], s[30:31], 0, v[130:131]
	s_mov_b32 m0, s70
	s_nop 0
	global_load_lds_dwordx4 v[214:215], off
	s_waitcnt vmcnt(8)
	s_waitcnt lgkmcnt(0)
	s_barrier
	s_setprio 1
	s_waitcnt lgkmcnt(0)
	v_mfma_f32_16x16x32_bf16 v[126:129], v[142:145], v[174:177], v[126:129]
	v_mfma_f32_16x16x32_bf16 v[118:121], v[150:153], v[174:177], v[118:121]
	v_mfma_f32_16x16x32_bf16 v[110:113], v[142:145], v[182:185], v[110:113]
	v_mfma_f32_16x16x32_bf16 v[102:105], v[150:153], v[182:185], v[102:105]
	v_mfma_f32_16x16x32_bf16 v[94:97], v[142:145], v[190:193], v[94:97]
	v_mfma_f32_16x16x32_bf16 v[86:89], v[150:153], v[190:193], v[86:89]
	v_mfma_f32_16x16x32_bf16 v[78:81], v[142:145], v[198:201], v[78:81]
	v_mfma_f32_16x16x32_bf16 v[70:73], v[150:153], v[198:201], v[70:73]
	v_mfma_f32_16x16x32_bf16 v[126:129], v[146:149], v[178:181], v[126:129]
	v_mfma_f32_16x16x32_bf16 v[118:121], v[154:157], v[178:181], v[118:121]
	v_mfma_f32_16x16x32_bf16 v[110:113], v[146:149], v[186:189], v[110:113]
	v_mfma_f32_16x16x32_bf16 v[102:105], v[154:157], v[186:189], v[102:105]
	v_mfma_f32_16x16x32_bf16 v[94:97], v[146:149], v[194:197], v[94:97]
	v_mfma_f32_16x16x32_bf16 v[86:89], v[154:157], v[194:197], v[86:89]
	v_mfma_f32_16x16x32_bf16 v[78:81], v[146:149], v[202:205], v[78:81]
	v_mfma_f32_16x16x32_bf16 v[70:73], v[154:157], v[202:205], v[70:73]
	s_setprio 0
	s_setprio 1
	v_mfma_f32_16x16x32_bf16 v[122:125], v[158:161], v[174:177], v[122:125]
	v_mfma_f32_16x16x32_bf16 v[114:117], v[166:169], v[174:177], v[114:117]
	v_mfma_f32_16x16x32_bf16 v[106:109], v[158:161], v[182:185], v[106:109]
	v_mfma_f32_16x16x32_bf16 v[98:101], v[166:169], v[182:185], v[98:101]
	v_mfma_f32_16x16x32_bf16 v[90:93], v[158:161], v[190:193], v[90:93]
	v_mfma_f32_16x16x32_bf16 v[82:85], v[166:169], v[190:193], v[82:85]
	v_mfma_f32_16x16x32_bf16 v[74:77], v[158:161], v[198:201], v[74:77]
	v_mfma_f32_16x16x32_bf16 v[66:69], v[166:169], v[198:201], v[66:69]
	v_mfma_f32_16x16x32_bf16 v[122:125], v[162:165], v[178:181], v[122:125]
	v_mfma_f32_16x16x32_bf16 v[114:117], v[170:173], v[178:181], v[114:117]
	v_mfma_f32_16x16x32_bf16 v[106:109], v[162:165], v[186:189], v[106:109]
	v_mfma_f32_16x16x32_bf16 v[98:101], v[170:173], v[186:189], v[98:101]
	v_mfma_f32_16x16x32_bf16 v[90:93], v[162:165], v[194:197], v[90:93]
	v_mfma_f32_16x16x32_bf16 v[82:85], v[170:173], v[194:197], v[82:85]
	v_mfma_f32_16x16x32_bf16 v[74:77], v[162:165], v[202:205], v[74:77]
	v_mfma_f32_16x16x32_bf16 v[66:69], v[170:173], v[202:205], v[66:69]
	s_setprio 0
	s_barrier
	s_add_i32 s30, s61, s81
	v_lshl_add_u64 v[206:207], v[206:207], 0, s[54:55]
	s_mov_b32 m0, s30
	ds_read_b128 v[174:177], v140 offset:49152
	ds_read_b128 v[178:181], v140 offset:50176
	ds_read_b128 v[182:185], v140 offset:51200
	ds_read_b128 v[186:189], v140 offset:52224
	ds_read_b128 v[190:193], v140 offset:53248
	ds_read_b128 v[194:197], v140 offset:54272
	ds_read_b128 v[198:201], v140 offset:55296
	ds_read_b128 v[202:205], v140 offset:56320
	global_load_lds_dwordx4 v[206:207], off
	s_add_i32 m0, s30, 0x2000
	s_add_u32 s28, s28, 0x80080
	v_lshl_add_u64 v[206:207], v[208:209], 0, s[54:55]
	s_addc_u32 s29, s29, 0
	s_add_i32 s30, s73, s81
	global_load_lds_dwordx4 v[206:207], off
	v_lshl_add_u64 v[206:207], s[28:29], 0, v[0:1]
	s_mov_b32 m0, s30
	s_nop 0
	global_load_lds_dwordx4 v[206:207], off
	v_lshl_add_u64 v[206:207], s[28:29], 0, v[130:131]
	s_add_i32 m0, s30, 0x2000
	s_nop 0
	global_load_lds_dwordx4 v[206:207], off
	v_lshl_add_u64 v[206:207], v[210:211], 0, s[54:55]
	s_mov_b32 m0, s71
	s_nop 0
	global_load_lds_dwordx4 v[206:207], off
	v_lshl_add_u64 v[206:207], v[212:213], 0, s[54:55]
	s_mov_b32 m0, s72
	s_nop 0
	global_load_lds_dwordx4 v[206:207], off
	s_waitcnt vmcnt(8)
	s_waitcnt lgkmcnt(0)
	s_barrier
	s_setprio 1
	s_waitcnt lgkmcnt(0)
	v_mfma_f32_16x16x32_bf16 v[62:65], v[142:145], v[174:177], v[62:65]
	v_mfma_f32_16x16x32_bf16 v[54:57], v[150:153], v[174:177], v[54:57]
	v_mfma_f32_16x16x32_bf16 v[46:49], v[142:145], v[182:185], v[46:49]
	v_mfma_f32_16x16x32_bf16 v[38:41], v[150:153], v[182:185], v[38:41]
	v_mfma_f32_16x16x32_bf16 v[30:33], v[142:145], v[190:193], v[30:33]
	v_mfma_f32_16x16x32_bf16 v[22:25], v[150:153], v[190:193], v[22:25]
	v_mfma_f32_16x16x32_bf16 v[14:17], v[142:145], v[198:201], v[14:17]
	v_mfma_f32_16x16x32_bf16 v[6:9], v[150:153], v[198:201], v[6:9]
	v_mfma_f32_16x16x32_bf16 v[62:65], v[146:149], v[178:181], v[62:65]
	v_mfma_f32_16x16x32_bf16 v[54:57], v[154:157], v[178:181], v[54:57]
	v_mfma_f32_16x16x32_bf16 v[46:49], v[146:149], v[186:189], v[46:49]
	v_mfma_f32_16x16x32_bf16 v[38:41], v[154:157], v[186:189], v[38:41]
	v_mfma_f32_16x16x32_bf16 v[30:33], v[146:149], v[194:197], v[30:33]
	v_mfma_f32_16x16x32_bf16 v[22:25], v[154:157], v[194:197], v[22:25]
	v_mfma_f32_16x16x32_bf16 v[14:17], v[146:149], v[202:205], v[14:17]
	v_mfma_f32_16x16x32_bf16 v[6:9], v[154:157], v[202:205], v[6:9]
	s_setprio 0
	s_setprio 1
	v_mfma_f32_16x16x32_bf16 v[58:61], v[158:161], v[174:177], v[58:61]
	v_mfma_f32_16x16x32_bf16 v[50:53], v[166:169], v[174:177], v[50:53]
	v_mfma_f32_16x16x32_bf16 v[42:45], v[158:161], v[182:185], v[42:45]
	v_mfma_f32_16x16x32_bf16 v[34:37], v[166:169], v[182:185], v[34:37]
	v_mfma_f32_16x16x32_bf16 v[26:29], v[158:161], v[190:193], v[26:29]
	v_mfma_f32_16x16x32_bf16 v[18:21], v[166:169], v[190:193], v[18:21]
	v_mfma_f32_16x16x32_bf16 v[10:13], v[158:161], v[198:201], v[10:13]
	v_mfma_f32_16x16x32_bf16 v[2:5], v[166:169], v[198:201], v[2:5]
	v_mfma_f32_16x16x32_bf16 v[58:61], v[162:165], v[178:181], v[58:61]
	v_mfma_f32_16x16x32_bf16 v[50:53], v[170:173], v[178:181], v[50:53]
	v_mfma_f32_16x16x32_bf16 v[42:45], v[162:165], v[186:189], v[42:45]
	v_mfma_f32_16x16x32_bf16 v[34:37], v[170:173], v[186:189], v[34:37]
	v_mfma_f32_16x16x32_bf16 v[26:29], v[162:165], v[194:197], v[26:29]
	v_mfma_f32_16x16x32_bf16 v[18:21], v[170:173], v[194:197], v[18:21]
	v_mfma_f32_16x16x32_bf16 v[10:13], v[162:165], v[202:205], v[10:13]
	v_mfma_f32_16x16x32_bf16 v[2:5], v[170:173], v[202:205], v[2:5]
	s_setprio 0
	s_barrier
	s_add_i32 s49, s49, 2
	s_add_u32 s45, s45, 0x100
	s_addc_u32 s48, s48, 0
	s_add_u32 s26, s26, 0x100
	s_addc_u32 s27, s27, 0
	s_cmp_gt_u32 s49, 29
	s_cbranch_scc1 .Lpeel_exit_G3
.LBB0_1060:
	s_add_u32 s28, s26, 0xfff80080
	s_addc_u32 s29, s27, -1
	s_add_i32 s61, 0, 0x10000
	s_cmp_eq_u32 s49, 28
	s_cselect_b32 s31, s19, s29
	s_cselect_b32 s30, s33, s28
	v_add_u32_e32 v141, s61, v138
	s_cselect_b32 s29, s17, s48
	s_cselect_b32 s28, s44, s45
	s_add_i32 s73, 0, 0x14000
	ds_read_b128 v[142:145], v141
	ds_read_b128 v[146:149], v141 offset:1024
	ds_read_b128 v[150:153], v141 offset:2048
	ds_read_b128 v[154:157], v141 offset:3072
	v_add_u32_e32 v141, s73, v138
	ds_read_b128 v[158:161], v141
	ds_read_b128 v[162:165], v141 offset:1024
	ds_read_b128 v[166:169], v141 offset:2048
	ds_read_b128 v[170:173], v141 offset:3072
	v_lshl_add_u64 v[206:207], s[26:27], 0, v[134:135]
	s_add_i32 m0, s82, 0xc000
	ds_read_b128 v[174:177], v140
	ds_read_b128 v[178:181], v140 offset:1024
	ds_read_b128 v[182:185], v140 offset:2048
	ds_read_b128 v[186:189], v140 offset:3072
	ds_read_b128 v[190:193], v140 offset:4096
	ds_read_b128 v[194:197], v140 offset:5120
	ds_read_b128 v[198:201], v140 offset:6144
	ds_read_b128 v[202:205], v140 offset:7168
	global_load_lds_dwordx4 v[206:207], off
	v_lshl_add_u64 v[206:207], s[26:27], 0, v[132:133]
	s_add_i32 m0, s82, 0xe000
	s_nop 0
	global_load_lds_dwordx4 v[206:207], off
	s_waitcnt vmcnt(8)
	s_waitcnt lgkmcnt(0)
	s_barrier
	s_setprio 1
	s_waitcnt lgkmcnt(0)
	v_mfma_f32_16x16x32_bf16 v[126:129], v[142:145], v[174:177], v[126:129]
	v_mfma_f32_16x16x32_bf16 v[118:121], v[150:153], v[174:177], v[118:121]
	v_mfma_f32_16x16x32_bf16 v[110:113], v[142:145], v[182:185], v[110:113]
	v_mfma_f32_16x16x32_bf16 v[102:105], v[150:153], v[182:185], v[102:105]
	v_mfma_f32_16x16x32_bf16 v[94:97], v[142:145], v[190:193], v[94:97]
	v_mfma_f32_16x16x32_bf16 v[86:89], v[150:153], v[190:193], v[86:89]
	v_mfma_f32_16x16x32_bf16 v[78:81], v[142:145], v[198:201], v[78:81]
	v_mfma_f32_16x16x32_bf16 v[70:73], v[150:153], v[198:201], v[70:73]
	v_mfma_f32_16x16x32_bf16 v[126:129], v[146:149], v[178:181], v[126:129]
	v_mfma_f32_16x16x32_bf16 v[118:121], v[154:157], v[178:181], v[118:121]
	v_mfma_f32_16x16x32_bf16 v[110:113], v[146:149], v[186:189], v[110:113]
	v_mfma_f32_16x16x32_bf16 v[102:105], v[154:157], v[186:189], v[102:105]
	v_mfma_f32_16x16x32_bf16 v[94:97], v[146:149], v[194:197], v[94:97]
	v_mfma_f32_16x16x32_bf16 v[86:89], v[154:157], v[194:197], v[86:89]
	v_mfma_f32_16x16x32_bf16 v[78:81], v[146:149], v[202:205], v[78:81]
	v_mfma_f32_16x16x32_bf16 v[70:73], v[154:157], v[202:205], v[70:73]
	s_setprio 0
	s_setprio 1
	v_mfma_f32_16x16x32_bf16 v[122:125], v[158:161], v[174:177], v[122:125]
	v_mfma_f32_16x16x32_bf16 v[114:117], v[166:169], v[174:177], v[114:117]
	v_mfma_f32_16x16x32_bf16 v[106:109], v[158:161], v[182:185], v[106:109]
	v_mfma_f32_16x16x32_bf16 v[98:101], v[166:169], v[182:185], v[98:101]
	v_mfma_f32_16x16x32_bf16 v[90:93], v[158:161], v[190:193], v[90:93]
	v_mfma_f32_16x16x32_bf16 v[82:85], v[166:169], v[190:193], v[82:85]
	v_mfma_f32_16x16x32_bf16 v[74:77], v[158:161], v[198:201], v[74:77]
	v_mfma_f32_16x16x32_bf16 v[66:69], v[166:169], v[198:201], v[66:69]
	v_mfma_f32_16x16x32_bf16 v[122:125], v[162:165], v[178:181], v[122:125]
	v_mfma_f32_16x16x32_bf16 v[114:117], v[170:173], v[178:181], v[114:117]
	v_mfma_f32_16x16x32_bf16 v[106:109], v[162:165], v[186:189], v[106:109]
	v_mfma_f32_16x16x32_bf16 v[98:101], v[170:173], v[186:189], v[98:101]
	v_mfma_f32_16x16x32_bf16 v[90:93], v[162:165], v[194:197], v[90:93]
	v_mfma_f32_16x16x32_bf16 v[82:85], v[170:173], v[194:197], v[82:85]
	v_mfma_f32_16x16x32_bf16 v[74:77], v[162:165], v[202:205], v[74:77]
	v_mfma_f32_16x16x32_bf16 v[66:69], v[170:173], v[202:205], v[66:69]
	s_setprio 0
	s_barrier
	s_add_i32 s61, s61, s81
	v_lshl_add_u64 v[206:207], s[28:29], 0, v[0:1]
	s_mov_b32 m0, s61
	ds_read_b128 v[174:177], v140 offset:16384
	ds_read_b128 v[178:181], v140 offset:17408
	ds_read_b128 v[182:185], v140 offset:18432
	ds_read_b128 v[186:189], v140 offset:19456
	ds_read_b128 v[190:193], v140 offset:20480
	ds_read_b128 v[194:197], v140 offset:21504
	ds_read_b128 v[198:201], v140 offset:22528
	ds_read_b128 v[202:205], v140 offset:23552
	global_load_lds_dwordx4 v[206:207], off
	s_add_i32 m0, s61, 0x2000
	s_add_u32 s84, s28, 0x80000
	v_lshl_add_u64 v[208:209], s[28:29], 0, v[130:131]
	s_addc_u32 s85, s29, 0
	s_add_i32 s61, s73, s81
	global_load_lds_dwordx4 v[208:209], off
	v_lshl_add_u64 v[210:211], s[84:85], 0, v[0:1]
	s_mov_b32 m0, s61
	v_lshl_add_u64 v[212:213], s[30:31], 0, v[130:131]
	global_load_lds_dwordx4 v[210:211], off
	v_lshl_add_u64 v[210:211], s[84:85], 0, v[130:131]
	s_add_i32 m0, s61, 0x2000
	s_nop 0
	global_load_lds_dwordx4 v[210:211], off
	v_lshl_add_u64 v[210:211], s[30:31], 0, v[0:1]
	s_mov_b32 m0, s82
	s_nop 0
	global_load_lds_dwordx4 v[210:211], off
	s_mov_b32 m0, s68
	s_nop 0
	global_load_lds_dwordx4 v[212:213], off
	s_waitcnt vmcnt(8)
	s_waitcnt lgkmcnt(0)
	s_barrier
	s_setprio 1
	s_waitcnt lgkmcnt(0)
	v_mfma_f32_16x16x32_bf16 v[62:65], v[142:145], v[174:177], v[62:65]
	v_mfma_f32_16x16x32_bf16 v[54:57], v[150:153], v[174:177], v[54:57]
	v_mfma_f32_16x16x32_bf16 v[46:49], v[142:145], v[182:185], v[46:49]
	v_mfma_f32_16x16x32_bf16 v[38:41], v[150:153], v[182:185], v[38:41]
	v_mfma_f32_16x16x32_bf16 v[30:33], v[142:145], v[190:193], v[30:33]
	v_mfma_f32_16x16x32_bf16 v[22:25], v[150:153], v[190:193], v[22:25]
	v_mfma_f32_16x16x32_bf16 v[14:17], v[142:145], v[198:201], v[14:17]
	v_mfma_f32_16x16x32_bf16 v[6:9], v[150:153], v[198:201], v[6:9]
	v_mfma_f32_16x16x32_bf16 v[62:65], v[146:149], v[178:181], v[62:65]
	v_mfma_f32_16x16x32_bf16 v[54:57], v[154:157], v[178:181], v[54:57]
	v_mfma_f32_16x16x32_bf16 v[46:49], v[146:149], v[186:189], v[46:49]
	v_mfma_f32_16x16x32_bf16 v[38:41], v[154:157], v[186:189], v[38:41]
	v_mfma_f32_16x16x32_bf16 v[30:33], v[146:149], v[194:197], v[30:33]
	v_mfma_f32_16x16x32_bf16 v[22:25], v[154:157], v[194:197], v[22:25]
	v_mfma_f32_16x16x32_bf16 v[14:17], v[146:149], v[202:205], v[14:17]
	v_mfma_f32_16x16x32_bf16 v[6:9], v[154:157], v[202:205], v[6:9]
	s_setprio 0
	s_setprio 1
	v_mfma_f32_16x16x32_bf16 v[58:61], v[158:161], v[174:177], v[58:61]
	v_mfma_f32_16x16x32_bf16 v[50:53], v[166:169], v[174:177], v[50:53]
	v_mfma_f32_16x16x32_bf16 v[42:45], v[158:161], v[182:185], v[42:45]
	v_mfma_f32_16x16x32_bf16 v[34:37], v[166:169], v[182:185], v[34:37]
	v_mfma_f32_16x16x32_bf16 v[26:29], v[158:161], v[190:193], v[26:29]
	v_mfma_f32_16x16x32_bf16 v[18:21], v[166:169], v[190:193], v[18:21]
	v_mfma_f32_16x16x32_bf16 v[10:13], v[158:161], v[198:201], v[10:13]
	v_mfma_f32_16x16x32_bf16 v[2:5], v[166:169], v[198:201], v[2:5]
	v_mfma_f32_16x16x32_bf16 v[58:61], v[162:165], v[178:181], v[58:61]
	v_mfma_f32_16x16x32_bf16 v[50:53], v[170:173], v[178:181], v[50:53]
	v_mfma_f32_16x16x32_bf16 v[42:45], v[162:165], v[186:189], v[42:45]
	v_mfma_f32_16x16x32_bf16 v[34:37], v[170:173], v[186:189], v[34:37]
	v_mfma_f32_16x16x32_bf16 v[26:29], v[162:165], v[194:197], v[26:29]
	v_mfma_f32_16x16x32_bf16 v[18:21], v[170:173], v[194:197], v[18:21]
	v_mfma_f32_16x16x32_bf16 v[10:13], v[162:165], v[202:205], v[10:13]
	v_mfma_f32_16x16x32_bf16 v[2:5], v[170:173], v[202:205], v[2:5]
	s_setprio 0
	s_barrier
	s_add_i32 s61, 0, 0x18000
	v_add_u32_e32 v141, s61, v138
	s_add_i32 s73, 0, 0x1c000
	ds_read_b128 v[142:145], v141
	ds_read_b128 v[146:149], v141 offset:1024
	ds_read_b128 v[150:153], v141 offset:2048
	ds_read_b128 v[154:157], v141 offset:3072
	v_add_u32_e32 v141, s73, v138
	ds_read_b128 v[158:161], v141
	ds_read_b128 v[162:165], v141 offset:1024
	ds_read_b128 v[166:169], v141 offset:2048
	ds_read_b128 v[170:173], v141 offset:3072
	s_add_u32 s30, s30, 0x80000
	s_addc_u32 s31, s31, 0
	s_mov_b32 m0, s69
	v_lshl_add_u64 v[214:215], s[30:31], 0, v[0:1]
	ds_read_b128 v[174:177], v140 offset:32768
	ds_read_b128 v[178:181], v140 offset:33792
	ds_read_b128 v[182:185], v140 offset:34816
	ds_read_b128 v[186:189], v140 offset:35840
	ds_read_b128 v[190:193], v140 offset:36864
	ds_read_b128 v[194:197], v140 offset:37888
	ds_read_b128 v[198:201], v140 offset:38912
	ds_read_b128 v[202:205], v140 offset:39936
	global_load_lds_dwordx4 v[214:215], off
	v_lshl_add_u64 v[214:215], s[30:31], 0, v[130:131]
	s_mov_b32 m0, s70
	s_nop 0
	global_load_lds_dwordx4 v[214:215], off
	s_waitcnt vmcnt(8)
	s_waitcnt lgkmcnt(0)
	s_barrier
	s_setprio 1
	s_waitcnt lgkmcnt(0)
	v_mfma_f32_16x16x32_bf16 v[126:129], v[142:145], v[174:177], v[126:129]
	v_mfma_f32_16x16x32_bf16 v[118:121], v[150:153], v[174:177], v[118:121]
	v_mfma_f32_16x16x32_bf16 v[110:113], v[142:145], v[182:185], v[110:113]
	v_mfma_f32_16x16x32_bf16 v[102:105], v[150:153], v[182:185], v[102:105]
	v_mfma_f32_16x16x32_bf16 v[94:97], v[142:145], v[190:193], v[94:97]
	v_mfma_f32_16x16x32_bf16 v[86:89], v[150:153], v[190:193], v[86:89]
	v_mfma_f32_16x16x32_bf16 v[78:81], v[142:145], v[198:201], v[78:81]
	v_mfma_f32_16x16x32_bf16 v[70:73], v[150:153], v[198:201], v[70:73]
	v_mfma_f32_16x16x32_bf16 v[126:129], v[146:149], v[178:181], v[126:129]
	v_mfma_f32_16x16x32_bf16 v[118:121], v[154:157], v[178:181], v[118:121]
	v_mfma_f32_16x16x32_bf16 v[110:113], v[146:149], v[186:189], v[110:113]
	v_mfma_f32_16x16x32_bf16 v[102:105], v[154:157], v[186:189], v[102:105]
	v_mfma_f32_16x16x32_bf16 v[94:97], v[146:149], v[194:197], v[94:97]
	v_mfma_f32_16x16x32_bf16 v[86:89], v[154:157], v[194:197], v[86:89]
	v_mfma_f32_16x16x32_bf16 v[78:81], v[146:149], v[202:205], v[78:81]
	v_mfma_f32_16x16x32_bf16 v[70:73], v[154:157], v[202:205], v[70:73]
	s_setprio 0
	s_setprio 1
	v_mfma_f32_16x16x32_bf16 v[122:125], v[158:161], v[174:177], v[122:125]
	v_mfma_f32_16x16x32_bf16 v[114:117], v[166:169], v[174:177], v[114:117]
	v_mfma_f32_16x16x32_bf16 v[106:109], v[158:161], v[182:185], v[106:109]
	v_mfma_f32_16x16x32_bf16 v[98:101], v[166:169], v[182:185], v[98:101]
	v_mfma_f32_16x16x32_bf16 v[90:93], v[158:161], v[190:193], v[90:93]
	v_mfma_f32_16x16x32_bf16 v[82:85], v[166:169], v[190:193], v[82:85]
	v_mfma_f32_16x16x32_bf16 v[74:77], v[158:161], v[198:201], v[74:77]
	v_mfma_f32_16x16x32_bf16 v[66:69], v[166:169], v[198:201], v[66:69]
	v_mfma_f32_16x16x32_bf16 v[122:125], v[162:165], v[178:181], v[122:125]
	v_mfma_f32_16x16x32_bf16 v[114:117], v[170:173], v[178:181], v[114:117]
	v_mfma_f32_16x16x32_bf16 v[106:109], v[162:165], v[186:189], v[106:109]
	v_mfma_f32_16x16x32_bf16 v[98:101], v[170:173], v[186:189], v[98:101]
	v_mfma_f32_16x16x32_bf16 v[90:93], v[162:165], v[194:197], v[90:93]
	v_mfma_f32_16x16x32_bf16 v[82:85], v[170:173], v[194:197], v[82:85]
	v_mfma_f32_16x16x32_bf16 v[74:77], v[162:165], v[202:205], v[74:77]
	v_mfma_f32_16x16x32_bf16 v[66:69], v[170:173], v[202:205], v[66:69]
	s_setprio 0
	s_barrier
	s_add_i32 s30, s61, s81
	v_lshl_add_u64 v[206:207], v[206:207], 0, s[54:55]
	s_mov_b32 m0, s30
	ds_read_b128 v[174:177], v140 offset:49152
	ds_read_b128 v[178:181], v140 offset:50176
	ds_read_b128 v[182:185], v140 offset:51200
	ds_read_b128 v[186:189], v140 offset:52224
	ds_read_b128 v[190:193], v140 offset:53248
	ds_read_b128 v[194:197], v140 offset:54272
	ds_read_b128 v[198:201], v140 offset:55296
	ds_read_b128 v[202:205], v140 offset:56320
	global_load_lds_dwordx4 v[206:207], off
	s_add_i32 m0, s30, 0x2000
	s_add_u32 s28, s28, 0x80080
	v_lshl_add_u64 v[206:207], v[208:209], 0, s[54:55]
	s_addc_u32 s29, s29, 0
	s_add_i32 s30, s73, s81
	global_load_lds_dwordx4 v[206:207], off
	v_lshl_add_u64 v[206:207], s[28:29], 0, v[0:1]
	s_mov_b32 m0, s30
	s_nop 0
	global_load_lds_dwordx4 v[206:207], off
	v_lshl_add_u64 v[206:207], s[28:29], 0, v[130:131]
	s_add_i32 m0, s30, 0x2000
	s_nop 0
	global_load_lds_dwordx4 v[206:207], off
	v_lshl_add_u64 v[206:207], v[210:211], 0, s[54:55]
	s_mov_b32 m0, s71
	s_nop 0
	global_load_lds_dwordx4 v[206:207], off
	v_lshl_add_u64 v[206:207], v[212:213], 0, s[54:55]
	s_mov_b32 m0, s72
	s_nop 0
	global_load_lds_dwordx4 v[206:207], off
	s_waitcnt vmcnt(8)
	s_waitcnt lgkmcnt(0)
	s_barrier
	s_setprio 1
	s_waitcnt lgkmcnt(0)
	v_mfma_f32_16x16x32_bf16 v[62:65], v[142:145], v[174:177], v[62:65]
	v_mfma_f32_16x16x32_bf16 v[54:57], v[150:153], v[174:177], v[54:57]
	v_mfma_f32_16x16x32_bf16 v[46:49], v[142:145], v[182:185], v[46:49]
	v_mfma_f32_16x16x32_bf16 v[38:41], v[150:153], v[182:185], v[38:41]
	v_mfma_f32_16x16x32_bf16 v[30:33], v[142:145], v[190:193], v[30:33]
	v_mfma_f32_16x16x32_bf16 v[22:25], v[150:153], v[190:193], v[22:25]
	v_mfma_f32_16x16x32_bf16 v[14:17], v[142:145], v[198:201], v[14:17]
	v_mfma_f32_16x16x32_bf16 v[6:9], v[150:153], v[198:201], v[6:9]
	v_mfma_f32_16x16x32_bf16 v[62:65], v[146:149], v[178:181], v[62:65]
	v_mfma_f32_16x16x32_bf16 v[54:57], v[154:157], v[178:181], v[54:57]
	v_mfma_f32_16x16x32_bf16 v[46:49], v[146:149], v[186:189], v[46:49]
	v_mfma_f32_16x16x32_bf16 v[38:41], v[154:157], v[186:189], v[38:41]
	v_mfma_f32_16x16x32_bf16 v[30:33], v[146:149], v[194:197], v[30:33]
	v_mfma_f32_16x16x32_bf16 v[22:25], v[154:157], v[194:197], v[22:25]
	v_mfma_f32_16x16x32_bf16 v[14:17], v[146:149], v[202:205], v[14:17]
	v_mfma_f32_16x16x32_bf16 v[6:9], v[154:157], v[202:205], v[6:9]
	s_setprio 0
	s_setprio 1
	v_mfma_f32_16x16x32_bf16 v[58:61], v[158:161], v[174:177], v[58:61]
	v_mfma_f32_16x16x32_bf16 v[50:53], v[166:169], v[174:177], v[50:53]
	v_mfma_f32_16x16x32_bf16 v[42:45], v[158:161], v[182:185], v[42:45]
	v_mfma_f32_16x16x32_bf16 v[34:37], v[166:169], v[182:185], v[34:37]
	v_mfma_f32_16x16x32_bf16 v[26:29], v[158:161], v[190:193], v[26:29]
	v_mfma_f32_16x16x32_bf16 v[18:21], v[166:169], v[190:193], v[18:21]
	v_mfma_f32_16x16x32_bf16 v[10:13], v[158:161], v[198:201], v[10:13]
	v_mfma_f32_16x16x32_bf16 v[2:5], v[166:169], v[198:201], v[2:5]
	v_mfma_f32_16x16x32_bf16 v[58:61], v[162:165], v[178:181], v[58:61]
	v_mfma_f32_16x16x32_bf16 v[50:53], v[170:173], v[178:181], v[50:53]
	v_mfma_f32_16x16x32_bf16 v[42:45], v[162:165], v[186:189], v[42:45]
	v_mfma_f32_16x16x32_bf16 v[34:37], v[170:173], v[186:189], v[34:37]
	v_mfma_f32_16x16x32_bf16 v[26:29], v[162:165], v[194:197], v[26:29]
	v_mfma_f32_16x16x32_bf16 v[18:21], v[170:173], v[194:197], v[18:21]
	v_mfma_f32_16x16x32_bf16 v[10:13], v[162:165], v[202:205], v[10:13]
	v_mfma_f32_16x16x32_bf16 v[2:5], v[170:173], v[202:205], v[2:5]
	s_setprio 0
	s_barrier
	s_add_i32 s49, s49, 2
	s_add_u32 s45, s45, 0x100
	s_addc_u32 s48, s48, 0
	s_add_u32 s26, s26, 0x100
	s_addc_u32 s27, s27, 0
	s_cmp_gt_u32 s49, 29
	s_cbranch_scc0 .LBB0_1060

.LBB0_1188:
	v_and_b32_e32 v212, 15, v213
	v_and_b32_e32 v18, 48, v213
	v_lshlrev_b32_e32 v19, 2, v213
	s_and_b32 s33, s17, 3
	s_lshl_b32 s34, s4, 6
	s_lshl_b32 s4, s4, 13
	v_lshl_or_b32 v18, v212, 6, v18
	v_and_b32_e32 v19, 32, v19
	s_add_i32 m0, s61, 0x18000
	v_lshl_add_u64 v[8:9], v[8:9], 0, s[54:55]
	s_lshr_b32 s5, s5, 2
	v_bitop3_b32 v20, v18, s4, v19 bitop3:0xde
	s_lshl_b32 s4, s33, 12
	s_waitcnt vmcnt(2)
	s_barrier
	global_load_lds_dwordx4 v[8:9], off
	v_lshl_add_u64 v[6:7], v[6:7], 0, s[54:55]
	s_add_i32 m0, s61, 0x1a000
	s_add_i32 s68, s61, 0x8000
	s_add_i32 s69, s61, 0xa000
	v_bitop3_b32 v140, v18, s4, v19 bitop3:0xde
	global_load_lds_dwordx4 v[6:7], off
	v_lshl_add_u64 v[4:5], v[4:5], 0, s[54:55]
	s_mov_b32 m0, s68
	s_add_u32 s4, s22, 0x160080
	s_sext_i32_i8 s16, s5
	global_load_lds_dwordx4 v[4:5], off
	v_lshl_add_u64 v[2:3], v[2:3], 0, s[54:55]
	s_mov_b32 m0, s69
	s_addc_u32 s5, s23, 0
	global_load_lds_dwordx4 v[2:3], off
	s_add_i32 m0, s61, 0x1c000
	v_lshl_add_u64 v[2:3], s[4:5], 0, v[0:1]
	global_load_lds_dwordx4 v[2:3], off
	v_lshl_add_u64 v[2:3], s[4:5], 0, v[130:131]
	s_add_i32 m0, s61, 0x1e000
	s_movk_i32 s7, 0x1600
	global_load_lds_dwordx4 v[2:3], off
	v_lshrrev_b32_e32 v3, 1, v14
	v_mul_lo_u32 v2, v16, s7
	s_mov_b32 s6, 0x16000
	v_mad_u64_u32 v[2:3], s[4:5], v3, s6, v[2:3]
	v_or_b32_e32 v2, v2, v15
	v_add_lshl_u32 v132, v2, v17, 1
	v_lshrrev_b32_e32 v3, 1, v10
	v_mul_lo_u32 v2, v12, s7
	v_mad_u64_u32 v[2:3], s[4:5], v3, s6, v[2:3]
	s_waitcnt vmcnt(6)
	v_or_b32_e32 v2, v2, v11
	v_add_lshl_u32 v134, v2, v13, 1
	v_or_b32_e32 v211, s34, v212
	v_mov_b32_e32 v133, v1
	v_mov_b32_e32 v135, v1
	s_mov_b32 s70, 0
	v_add_u32_e32 v141, 0, v20
	s_barrier

.Lz0_G4:
	s_add_u32 s28, s18, s22
	s_addc_u32 s29, s19, s23
	s_add_u32 s28, s28, 0x100
	s_addc_u32 s29, s29, 0
	s_add_u32 s78, s74, s22
	s_addc_u32 s79, s75, s23
	s_add_i32 s80, 0, 0x10000
	s_cmpk_eq_i32 s22, 0x2b00
	s_cselect_b32 s31, s21, s29
	s_cselect_b32 s30, s20, s28
	s_cselect_b32 s29, s9, s79
	s_cselect_b32 s28, s8, s78
	s_add_i32 s81, 0, 0x14000
	v_add_u32_e32 v154, s80, v140
	v_add_u32_e32 v170, s81, v140
	ds_read_b128 v[142:145], v154
	ds_read_b128 v[146:149], v154 offset:1024
	ds_read_b128 v[150:153], v154 offset:2048
	ds_read_b128 v[154:157], v154 offset:3072
	ds_read_b128 v[158:161], v170
	ds_read_b128 v[162:165], v170 offset:1024
	ds_read_b128 v[166:169], v170 offset:2048
	ds_read_b128 v[170:173], v170 offset:3072
	v_lshl_add_u64 v[206:207], v[138:139], 0, s[22:23]
	s_add_i32 m0, s61, 0xc000
	ds_read_b128 v[174:177], v141
	ds_read_b128 v[178:181], v141 offset:1024
	ds_read_b128 v[182:185], v141 offset:2048
	ds_read_b128 v[186:189], v141 offset:3072
	ds_read_b128 v[190:193], v141 offset:4096
	ds_read_b128 v[194:197], v141 offset:5120
	ds_read_b128 v[198:201], v141 offset:6144
	ds_read_b128 v[202:205], v141 offset:7168
	global_load_lds_dwordx4 v[206:207], off
	v_lshl_add_u64 v[206:207], v[136:137], 0, s[22:23]
	s_add_i32 m0, s61, 0xe000
	s_nop 0
	global_load_lds_dwordx4 v[206:207], off
	s_waitcnt vmcnt(8)
	s_waitcnt lgkmcnt(0)
	s_barrier
	s_setprio 1
	s_waitcnt lgkmcnt(0)
	v_mfma_f32_16x16x32_bf16 v[126:129], v[142:145], v[174:177], 0
	v_mfma_f32_16x16x32_bf16 v[122:125], v[150:153], v[174:177], 0
	v_mfma_f32_16x16x32_bf16 v[110:113], v[142:145], v[182:185], 0
	v_mfma_f32_16x16x32_bf16 v[106:109], v[150:153], v[182:185], 0
	v_mfma_f32_16x16x32_bf16 v[98:101], v[142:145], v[190:193], 0
	v_mfma_f32_16x16x32_bf16 v[90:93], v[150:153], v[190:193], 0
	v_mfma_f32_16x16x32_bf16 v[82:85], v[142:145], v[198:201], 0
	v_mfma_f32_16x16x32_bf16 v[74:77], v[150:153], v[198:201], 0
	v_mfma_f32_16x16x32_bf16 v[126:129], v[146:149], v[178:181], v[126:129]
	v_mfma_f32_16x16x32_bf16 v[122:125], v[154:157], v[178:181], v[122:125]
	v_mfma_f32_16x16x32_bf16 v[110:113], v[146:149], v[186:189], v[110:113]
	v_mfma_f32_16x16x32_bf16 v[106:109], v[154:157], v[186:189], v[106:109]
	v_mfma_f32_16x16x32_bf16 v[98:101], v[146:149], v[194:197], v[98:101]
	v_mfma_f32_16x16x32_bf16 v[90:93], v[154:157], v[194:197], v[90:93]
	v_mfma_f32_16x16x32_bf16 v[82:85], v[146:149], v[202:205], v[82:85]
	v_mfma_f32_16x16x32_bf16 v[74:77], v[154:157], v[202:205], v[74:77]
	s_setprio 0
	s_setprio 1
	v_mfma_f32_16x16x32_bf16 v[118:121], v[158:161], v[174:177], 0
	v_mfma_f32_16x16x32_bf16 v[114:117], v[166:169], v[174:177], 0
	v_mfma_f32_16x16x32_bf16 v[102:105], v[158:161], v[182:185], 0
	v_mfma_f32_16x16x32_bf16 v[94:97], v[166:169], v[182:185], 0
	v_mfma_f32_16x16x32_bf16 v[86:89], v[158:161], v[190:193], 0
	v_mfma_f32_16x16x32_bf16 v[78:81], v[166:169], v[190:193], 0
	v_mfma_f32_16x16x32_bf16 v[70:73], v[158:161], v[198:201], 0
	v_mfma_f32_16x16x32_bf16 v[66:69], v[166:169], v[198:201], 0
	v_mfma_f32_16x16x32_bf16 v[118:121], v[162:165], v[178:181], v[118:121]
	v_mfma_f32_16x16x32_bf16 v[114:117], v[170:173], v[178:181], v[114:117]
	v_mfma_f32_16x16x32_bf16 v[102:105], v[162:165], v[186:189], v[102:105]
	v_mfma_f32_16x16x32_bf16 v[94:97], v[170:173], v[186:189], v[94:97]
	v_mfma_f32_16x16x32_bf16 v[86:89], v[162:165], v[194:197], v[86:89]
	v_mfma_f32_16x16x32_bf16 v[78:81], v[170:173], v[194:197], v[78:81]
	v_mfma_f32_16x16x32_bf16 v[70:73], v[162:165], v[202:205], v[70:73]
	v_mfma_f32_16x16x32_bf16 v[66:69], v[170:173], v[202:205], v[66:69]
	s_setprio 0
	s_barrier
	s_add_i32 s78, s80, s44
	v_lshl_add_u64 v[206:207], s[28:29], 0, v[0:1]
	s_mov_b32 m0, s78
	ds_read_b128 v[174:177], v141 offset:16384
	ds_read_b128 v[178:181], v141 offset:17408
	ds_read_b128 v[182:185], v141 offset:18432
	ds_read_b128 v[186:189], v141 offset:19456
	ds_read_b128 v[190:193], v141 offset:20480
	ds_read_b128 v[194:197], v141 offset:21504
	ds_read_b128 v[198:201], v141 offset:22528
	ds_read_b128 v[202:205], v141 offset:23552
	global_load_lds_dwordx4 v[206:207], off
	s_add_i32 m0, s78, 0x2000
	s_add_u32 s78, s28, 0x160000
	v_lshl_add_u64 v[208:209], s[28:29], 0, v[130:131]
	s_addc_u32 s79, s29, 0
	s_add_i32 s80, s81, s44
	global_load_lds_dwordx4 v[208:209], off
	v_lshl_add_u64 v[214:215], s[78:79], 0, v[0:1]
	s_mov_b32 m0, s80
	v_lshl_add_u64 v[216:217], s[30:31], 0, v[130:131]
	global_load_lds_dwordx4 v[214:215], off
	v_lshl_add_u64 v[214:215], s[78:79], 0, v[130:131]
	s_add_i32 m0, s80, 0x2000
	s_nop 0
	global_load_lds_dwordx4 v[214:215], off
	v_lshl_add_u64 v[214:215], s[30:31], 0, v[0:1]
	s_mov_b32 m0, s61
	s_nop 0
	global_load_lds_dwordx4 v[214:215], off
	s_mov_b32 m0, s65
	s_nop 0
	global_load_lds_dwordx4 v[216:217], off
	s_waitcnt vmcnt(8)
	s_waitcnt lgkmcnt(0)
	s_barrier
	s_setprio 1
	s_waitcnt lgkmcnt(0)
	v_mfma_f32_16x16x32_bf16 v[62:65], v[142:145], v[174:177], 0
	v_mfma_f32_16x16x32_bf16 v[58:61], v[150:153], v[174:177], 0
	v_mfma_f32_16x16x32_bf16 v[50:53], v[142:145], v[182:185], 0
	v_mfma_f32_16x16x32_bf16 v[42:45], v[150:153], v[182:185], 0
	v_mfma_f32_16x16x32_bf16 v[34:37], v[142:145], v[190:193], 0
	v_mfma_f32_16x16x32_bf16 v[26:29], v[150:153], v[190:193], 0
	v_mfma_f32_16x16x32_bf16 v[18:21], v[142:145], v[198:201], 0
	v_mfma_f32_16x16x32_bf16 v[10:13], v[150:153], v[198:201], 0
	v_mfma_f32_16x16x32_bf16 v[62:65], v[146:149], v[178:181], v[62:65]
	v_mfma_f32_16x16x32_bf16 v[58:61], v[154:157], v[178:181], v[58:61]
	v_mfma_f32_16x16x32_bf16 v[50:53], v[146:149], v[186:189], v[50:53]
	v_mfma_f32_16x16x32_bf16 v[42:45], v[154:157], v[186:189], v[42:45]
	v_mfma_f32_16x16x32_bf16 v[34:37], v[146:149], v[194:197], v[34:37]
	v_mfma_f32_16x16x32_bf16 v[26:29], v[154:157], v[194:197], v[26:29]
	v_mfma_f32_16x16x32_bf16 v[18:21], v[146:149], v[202:205], v[18:21]
	v_mfma_f32_16x16x32_bf16 v[10:13], v[154:157], v[202:205], v[10:13]
	s_setprio 0
	s_setprio 1
	v_mfma_f32_16x16x32_bf16 v[54:57], v[158:161], v[174:177], 0
	v_mfma_f32_16x16x32_bf16 v[46:49], v[166:169], v[174:177], 0
	v_mfma_f32_16x16x32_bf16 v[38:41], v[158:161], v[182:185], 0
	v_mfma_f32_16x16x32_bf16 v[30:33], v[166:169], v[182:185], 0
	v_mfma_f32_16x16x32_bf16 v[22:25], v[158:161], v[190:193], 0
	v_mfma_f32_16x16x32_bf16 v[14:17], v[166:169], v[190:193], 0
	v_mfma_f32_16x16x32_bf16 v[6:9], v[158:161], v[198:201], 0
	v_mfma_f32_16x16x32_bf16 v[2:5], v[166:169], v[198:201], 0
	v_mfma_f32_16x16x32_bf16 v[54:57], v[162:165], v[178:181], v[54:57]
	v_mfma_f32_16x16x32_bf16 v[46:49], v[170:173], v[178:181], v[46:49]
	v_mfma_f32_16x16x32_bf16 v[38:41], v[162:165], v[186:189], v[38:41]
	v_mfma_f32_16x16x32_bf16 v[30:33], v[170:173], v[186:189], v[30:33]
	v_mfma_f32_16x16x32_bf16 v[22:25], v[162:165], v[194:197], v[22:25]
	v_mfma_f32_16x16x32_bf16 v[14:17], v[170:173], v[194:197], v[14:17]
	v_mfma_f32_16x16x32_bf16 v[6:9], v[162:165], v[202:205], v[6:9]
	v_mfma_f32_16x16x32_bf16 v[2:5], v[170:173], v[202:205], v[2:5]
	s_setprio 0
	s_barrier
	s_add_i32 s78, 0, 0x18000
	s_add_i32 s79, 0, 0x1c000
	v_add_u32_e32 v154, s78, v140
	v_add_u32_e32 v170, s79, v140
	ds_read_b128 v[142:145], v154
	ds_read_b128 v[146:149], v154 offset:1024
	ds_read_b128 v[150:153], v154 offset:2048
	ds_read_b128 v[154:157], v154 offset:3072
	ds_read_b128 v[158:161], v170
	ds_read_b128 v[162:165], v170 offset:1024
	ds_read_b128 v[166:169], v170 offset:2048
	ds_read_b128 v[170:173], v170 offset:3072
	s_add_u32 s30, s30, 0x160000
	s_addc_u32 s31, s31, 0
	s_mov_b32 m0, s66
	v_lshl_add_u64 v[218:219], s[30:31], 0, v[0:1]
	ds_read_b128 v[174:177], v141 offset:32768
	ds_read_b128 v[178:181], v141 offset:33792
	ds_read_b128 v[182:185], v141 offset:34816
	ds_read_b128 v[186:189], v141 offset:35840
	ds_read_b128 v[190:193], v141 offset:36864
	ds_read_b128 v[194:197], v141 offset:37888
	ds_read_b128 v[198:201], v141 offset:38912
	ds_read_b128 v[202:205], v141 offset:39936
	global_load_lds_dwordx4 v[218:219], off
	v_lshl_add_u64 v[218:219], s[30:31], 0, v[130:131]
	s_mov_b32 m0, s67
	s_nop 0
	global_load_lds_dwordx4 v[218:219], off
	s_waitcnt vmcnt(8)
	s_waitcnt lgkmcnt(0)
	s_barrier
	s_setprio 1
	s_waitcnt lgkmcnt(0)
	v_mfma_f32_16x16x32_bf16 v[126:129], v[142:145], v[174:177], v[126:129]
	v_mfma_f32_16x16x32_bf16 v[122:125], v[150:153], v[174:177], v[122:125]
	v_mfma_f32_16x16x32_bf16 v[110:113], v[142:145], v[182:185], v[110:113]
	v_mfma_f32_16x16x32_bf16 v[106:109], v[150:153], v[182:185], v[106:109]
	v_mfma_f32_16x16x32_bf16 v[98:101], v[142:145], v[190:193], v[98:101]
	v_mfma_f32_16x16x32_bf16 v[90:93], v[150:153], v[190:193], v[90:93]
	v_mfma_f32_16x16x32_bf16 v[82:85], v[142:145], v[198:201], v[82:85]
	v_mfma_f32_16x16x32_bf16 v[74:77], v[150:153], v[198:201], v[74:77]
	v_mfma_f32_16x16x32_bf16 v[126:129], v[146:149], v[178:181], v[126:129]
	v_mfma_f32_16x16x32_bf16 v[122:125], v[154:157], v[178:181], v[122:125]
	v_mfma_f32_16x16x32_bf16 v[110:113], v[146:149], v[186:189], v[110:113]
	v_mfma_f32_16x16x32_bf16 v[106:109], v[154:157], v[186:189], v[106:109]
	v_mfma_f32_16x16x32_bf16 v[98:101], v[146:149], v[194:197], v[98:101]
	v_mfma_f32_16x16x32_bf16 v[90:93], v[154:157], v[194:197], v[90:93]
	v_mfma_f32_16x16x32_bf16 v[82:85], v[146:149], v[202:205], v[82:85]
	v_mfma_f32_16x16x32_bf16 v[74:77], v[154:157], v[202:205], v[74:77]
	s_setprio 0
	s_setprio 1
	v_mfma_f32_16x16x32_bf16 v[118:121], v[158:161], v[174:177], v[118:121]
	v_mfma_f32_16x16x32_bf16 v[114:117], v[166:169], v[174:177], v[114:117]
	v_mfma_f32_16x16x32_bf16 v[102:105], v[158:161], v[182:185], v[102:105]
	v_mfma_f32_16x16x32_bf16 v[94:97], v[166:169], v[182:185], v[94:97]
	v_mfma_f32_16x16x32_bf16 v[86:89], v[158:161], v[190:193], v[86:89]
	v_mfma_f32_16x16x32_bf16 v[78:81], v[166:169], v[190:193], v[78:81]
	v_mfma_f32_16x16x32_bf16 v[70:73], v[158:161], v[198:201], v[70:73]
	v_mfma_f32_16x16x32_bf16 v[66:69], v[166:169], v[198:201], v[66:69]
	v_mfma_f32_16x16x32_bf16 v[118:121], v[162:165], v[178:181], v[118:121]
	v_mfma_f32_16x16x32_bf16 v[114:117], v[170:173], v[178:181], v[114:117]
	v_mfma_f32_16x16x32_bf16 v[102:105], v[162:165], v[186:189], v[102:105]
	v_mfma_f32_16x16x32_bf16 v[94:97], v[170:173], v[186:189], v[94:97]
	v_mfma_f32_16x16x32_bf16 v[86:89], v[162:165], v[194:197], v[86:89]
	v_mfma_f32_16x16x32_bf16 v[78:81], v[170:173], v[194:197], v[78:81]
	v_mfma_f32_16x16x32_bf16 v[70:73], v[162:165], v[202:205], v[70:73]
	v_mfma_f32_16x16x32_bf16 v[66:69], v[170:173], v[202:205], v[66:69]
	s_setprio 0
	s_barrier
	s_add_i32 s30, s78, s44
	v_lshl_add_u64 v[206:207], v[206:207], 0, s[54:55]
	s_mov_b32 m0, s30
	ds_read_b128 v[174:177], v141 offset:49152
	ds_read_b128 v[178:181], v141 offset:50176
	ds_read_b128 v[182:185], v141 offset:51200
	ds_read_b128 v[186:189], v141 offset:52224
	ds_read_b128 v[190:193], v141 offset:53248
	ds_read_b128 v[194:197], v141 offset:54272
	ds_read_b128 v[198:201], v141 offset:55296
	ds_read_b128 v[202:205], v141 offset:56320
	global_load_lds_dwordx4 v[206:207], off
	s_add_i32 m0, s30, 0x2000
	s_add_u32 s28, s28, 0x160080
	v_lshl_add_u64 v[206:207], v[208:209], 0, s[54:55]
	s_addc_u32 s29, s29, 0
	s_add_i32 s30, s79, s44
	global_load_lds_dwordx4 v[206:207], off
	v_lshl_add_u64 v[206:207], s[28:29], 0, v[0:1]
	s_mov_b32 m0, s30
	s_nop 0
	global_load_lds_dwordx4 v[206:207], off
	v_lshl_add_u64 v[206:207], s[28:29], 0, v[130:131]
	s_add_i32 m0, s30, 0x2000
	s_nop 0
	global_load_lds_dwordx4 v[206:207], off
	v_lshl_add_u64 v[206:207], v[214:215], 0, s[54:55]
	s_mov_b32 m0, s68
	s_nop 0
	global_load_lds_dwordx4 v[206:207], off
	v_lshl_add_u64 v[206:207], v[216:217], 0, s[54:55]
	s_mov_b32 m0, s69
	s_nop 0
	global_load_lds_dwordx4 v[206:207], off
	s_waitcnt vmcnt(8)
	s_waitcnt lgkmcnt(0)
	s_barrier
	s_setprio 1
	s_waitcnt lgkmcnt(0)
	v_mfma_f32_16x16x32_bf16 v[62:65], v[142:145], v[174:177], v[62:65]
	v_mfma_f32_16x16x32_bf16 v[58:61], v[150:153], v[174:177], v[58:61]
	v_mfma_f32_16x16x32_bf16 v[50:53], v[142:145], v[182:185], v[50:53]
	v_mfma_f32_16x16x32_bf16 v[42:45], v[150:153], v[182:185], v[42:45]
	v_mfma_f32_16x16x32_bf16 v[34:37], v[142:145], v[190:193], v[34:37]
	v_mfma_f32_16x16x32_bf16 v[26:29], v[150:153], v[190:193], v[26:29]
	v_mfma_f32_16x16x32_bf16 v[18:21], v[142:145], v[198:201], v[18:21]
	v_mfma_f32_16x16x32_bf16 v[10:13], v[150:153], v[198:201], v[10:13]
	v_mfma_f32_16x16x32_bf16 v[62:65], v[146:149], v[178:181], v[62:65]
	v_mfma_f32_16x16x32_bf16 v[58:61], v[154:157], v[178:181], v[58:61]
	v_mfma_f32_16x16x32_bf16 v[50:53], v[146:149], v[186:189], v[50:53]
	v_mfma_f32_16x16x32_bf16 v[42:45], v[154:157], v[186:189], v[42:45]
	v_mfma_f32_16x16x32_bf16 v[34:37], v[146:149], v[194:197], v[34:37]
	v_mfma_f32_16x16x32_bf16 v[26:29], v[154:157], v[194:197], v[26:29]
	v_mfma_f32_16x16x32_bf16 v[18:21], v[146:149], v[202:205], v[18:21]
	v_mfma_f32_16x16x32_bf16 v[10:13], v[154:157], v[202:205], v[10:13]
	s_setprio 0
	s_setprio 1
	v_mfma_f32_16x16x32_bf16 v[54:57], v[158:161], v[174:177], v[54:57]
	v_mfma_f32_16x16x32_bf16 v[46:49], v[166:169], v[174:177], v[46:49]
	v_mfma_f32_16x16x32_bf16 v[38:41], v[158:161], v[182:185], v[38:41]
	v_mfma_f32_16x16x32_bf16 v[30:33], v[166:169], v[182:185], v[30:33]
	v_mfma_f32_16x16x32_bf16 v[22:25], v[158:161], v[190:193], v[22:25]
	v_mfma_f32_16x16x32_bf16 v[14:17], v[166:169], v[190:193], v[14:17]
	v_mfma_f32_16x16x32_bf16 v[6:9], v[158:161], v[198:201], v[6:9]
	v_mfma_f32_16x16x32_bf16 v[2:5], v[166:169], v[198:201], v[2:5]
	v_mfma_f32_16x16x32_bf16 v[54:57], v[162:165], v[178:181], v[54:57]
	v_mfma_f32_16x16x32_bf16 v[46:49], v[170:173], v[178:181], v[46:49]
	v_mfma_f32_16x16x32_bf16 v[38:41], v[162:165], v[186:189], v[38:41]
	v_mfma_f32_16x16x32_bf16 v[30:33], v[170:173], v[186:189], v[30:33]
	v_mfma_f32_16x16x32_bf16 v[22:25], v[162:165], v[194:197], v[22:25]
	v_mfma_f32_16x16x32_bf16 v[14:17], v[170:173], v[194:197], v[14:17]
	v_mfma_f32_16x16x32_bf16 v[6:9], v[162:165], v[202:205], v[6:9]
	v_mfma_f32_16x16x32_bf16 v[2:5], v[170:173], v[202:205], v[2:5]
	s_setprio 0
	s_barrier
	s_add_i32 s76, s76, 2
	s_add_u32 s22, s22, 0x100
	s_addc_u32 s23, s23, 0
	s_cmpk_gt_u32 s76, 0x55
	s_cbranch_scc1 .Lz0_exit_G4

.Lz0_exit_G4:
	s_add_u32 s22, s74, 0xffffff00
	s_addc_u32 s23, s75, -1
	s_and_b64 vcc, exec, s[6:7]
	s_cbranch_vccnz .LBB0_1203
	v_mov_b32_e32 v2, 0
	s_mov_b32 s16, s71
	s_mov_b32 s39, s72
	s_mov_b64 s[18:19], s[20:21]
	s_mov_b32 s70, s73
	v_mov_b32_e32 v3, v2
	v_mov_b32_e32 v4, v2
	v_mov_b32_e32 v5, v2
	v_mov_b32_e32 v6, v2
	v_mov_b32_e32 v7, v2
	v_mov_b32_e32 v8, v2
	v_mov_b32_e32 v9, v2
	v_mov_b32_e32 v14, v2
	v_mov_b32_e32 v15, v2
	v_mov_b32_e32 v16, v2
	v_mov_b32_e32 v17, v2
	v_mov_b32_e32 v22, v2
	v_mov_b32_e32 v23, v2
	v_mov_b32_e32 v24, v2
	v_mov_b32_e32 v25, v2
	v_mov_b32_e32 v30, v2
	v_mov_b32_e32 v31, v2
	v_mov_b32_e32 v32, v2
	v_mov_b32_e32 v33, v2
	v_mov_b32_e32 v38, v2
	v_mov_b32_e32 v39, v2
	v_mov_b32_e32 v40, v2
	v_mov_b32_e32 v41, v2
	v_mov_b32_e32 v46, v2
	v_mov_b32_e32 v47, v2
	v_mov_b32_e32 v48, v2
	v_mov_b32_e32 v49, v2
	v_mov_b32_e32 v54, v2
	v_mov_b32_e32 v55, v2
	v_mov_b32_e32 v56, v2
	v_mov_b32_e32 v57, v2
	v_mov_b32_e32 v10, v2
	v_mov_b32_e32 v11, v2
	v_mov_b32_e32 v12, v2
	v_mov_b32_e32 v13, v2
	v_mov_b32_e32 v18, v2
	v_mov_b32_e32 v19, v2
	v_mov_b32_e32 v20, v2
	v_mov_b32_e32 v21, v2
	v_mov_b32_e32 v26, v2
	v_mov_b32_e32 v27, v2
	v_mov_b32_e32 v28, v2
	v_mov_b32_e32 v29, v2
	v_mov_b32_e32 v34, v2
	v_mov_b32_e32 v35, v2
	v_mov_b32_e32 v36, v2
	v_mov_b32_e32 v37, v2
	v_mov_b32_e32 v42, v2
	v_mov_b32_e32 v43, v2
	v_mov_b32_e32 v44, v2
	v_mov_b32_e32 v45, v2
	v_mov_b32_e32 v50, v2
	v_mov_b32_e32 v51, v2
	v_mov_b32_e32 v52, v2
	v_mov_b32_e32 v53, v2
	v_mov_b32_e32 v58, v2
	v_mov_b32_e32 v59, v2
	v_mov_b32_e32 v60, v2
	v_mov_b32_e32 v61, v2
	v_mov_b32_e32 v62, v2
	v_mov_b32_e32 v63, v2
	v_mov_b32_e32 v64, v2
	v_mov_b32_e32 v65, v2
	v_mov_b32_e32 v66, v2
	v_mov_b32_e32 v67, v2
	v_mov_b32_e32 v68, v2
	v_mov_b32_e32 v69, v2
	v_mov_b32_e32 v70, v2
	v_mov_b32_e32 v71, v2
	v_mov_b32_e32 v72, v2
	v_mov_b32_e32 v73, v2
	v_mov_b32_e32 v78, v2
	v_mov_b32_e32 v79, v2
	v_mov_b32_e32 v80, v2
	v_mov_b32_e32 v81, v2
	v_mov_b32_e32 v86, v2
	v_mov_b32_e32 v87, v2
	v_mov_b32_e32 v88, v2
	v_mov_b32_e32 v89, v2
	v_mov_b32_e32 v94, v2
	v_mov_b32_e32 v95, v2
	v_mov_b32_e32 v96, v2
	v_mov_b32_e32 v97, v2
	v_mov_b32_e32 v102, v2
	v_mov_b32_e32 v103, v2
	v_mov_b32_e32 v104, v2
	v_mov_b32_e32 v105, v2
	v_mov_b32_e32 v114, v2
	v_mov_b32_e32 v115, v2
	v_mov_b32_e32 v116, v2
	v_mov_b32_e32 v117, v2
	v_mov_b32_e32 v118, v2
	v_mov_b32_e32 v119, v2
	v_mov_b32_e32 v120, v2
	v_mov_b32_e32 v121, v2
	v_mov_b32_e32 v74, v2
	v_mov_b32_e32 v75, v2
	v_mov_b32_e32 v76, v2
	v_mov_b32_e32 v77, v2
	v_mov_b32_e32 v82, v2
	v_mov_b32_e32 v83, v2
	v_mov_b32_e32 v84, v2
	v_mov_b32_e32 v85, v2
	v_mov_b32_e32 v90, v2
	v_mov_b32_e32 v91, v2
	v_mov_b32_e32 v92, v2
	v_mov_b32_e32 v93, v2
	v_mov_b32_e32 v98, v2
	v_mov_b32_e32 v99, v2
	v_mov_b32_e32 v100, v2
	v_mov_b32_e32 v101, v2
	v_mov_b32_e32 v106, v2
	v_mov_b32_e32 v107, v2
	v_mov_b32_e32 v108, v2
	v_mov_b32_e32 v109, v2
	v_mov_b32_e32 v110, v2
	v_mov_b32_e32 v111, v2
	v_mov_b32_e32 v112, v2
	v_mov_b32_e32 v113, v2
	v_mov_b32_e32 v122, v2
	v_mov_b32_e32 v123, v2
	v_mov_b32_e32 v124, v2
	v_mov_b32_e32 v125, v2
	v_mov_b32_e32 v126, v2
	v_mov_b32_e32 v127, v2
	v_mov_b32_e32 v128, v2
	v_mov_b32_e32 v129, v2
	s_andn2_b64 vcc, exec, s[4:5]
	s_cbranch_vccnz .LBB0_1204
	s_branch .LBB0_1205
